# ladder + reorder + removed the per-block s_setprio 1/0 flips in the six K-loops
# speedup vs baseline: 1.0173x; 1.0173x over previous
.LBB0_134:
	s_add_u32 s28, s66, 0xfffc0080
	s_addc_u32 s29, s67, -1
	s_add_i32 s88, 0, 0x10000
	v_add_u32_e32 v152, s88, v191
	ds_read_b128 v[128:131], v152
	ds_read_b128 v[132:135], v152 offset:1024
	ds_read_b128 v[148:151], v152 offset:2048
	ds_read_b128 v[152:155], v152 offset:3072
	s_cmp_eq_u32 vcc_lo, 12
	s_cselect_b32 s71, s5, s29
	s_cselect_b32 s70, s7, s28
	s_cselect_b32 s69, s17, s91
	s_cselect_b32 s68, s19, s85
	v_lshl_add_u64 v[172:173], s[66:67], 0, v[144:145]
	s_add_i32 m0, s73, 0xc000
	ds_read_b128 v[156:159], v192
	ds_read_b128 v[164:167], v192 offset:2048
	ds_read_b128 v[194:197], v192 offset:4096
	ds_read_b128 v[202:205], v192 offset:6144
	ds_read_b128 v[160:163], v192 offset:1024
	ds_read_b128 v[168:171], v192 offset:3072
	ds_read_b128 v[198:201], v192 offset:5120
	ds_read_b128 v[206:209], v192 offset:7168
	global_load_lds_dwordx4 v[172:173], off
	v_lshl_add_u64 v[172:173], s[66:67], 0, v[146:147]
	s_add_i32 m0, s73, 0xe000
	s_nop 0
	global_load_lds_dwordx4 v[172:173], off
	s_waitcnt lgkmcnt(8)
	s_barrier
	s_waitcnt lgkmcnt(7)
	v_mfma_f32_16x16x32_bf16 v[124:127], v[128:131], v[156:159], v[124:127]
	v_mfma_f32_16x16x32_bf16 v[120:123], v[148:151], v[156:159], v[120:123]
	s_waitcnt lgkmcnt(6)
	v_mfma_f32_16x16x32_bf16 v[108:111], v[128:131], v[164:167], v[108:111]
	v_mfma_f32_16x16x32_bf16 v[104:107], v[148:151], v[164:167], v[104:107]
	s_waitcnt lgkmcnt(5)
	v_mfma_f32_16x16x32_bf16 v[92:95], v[128:131], v[194:197], v[92:95]
	v_mfma_f32_16x16x32_bf16 v[88:91], v[148:151], v[194:197], v[88:91]
	s_waitcnt lgkmcnt(4)
	v_mfma_f32_16x16x32_bf16 v[76:79], v[128:131], v[202:205], v[76:79]
	v_mfma_f32_16x16x32_bf16 v[72:75], v[148:151], v[202:205], v[72:75]
	s_waitcnt lgkmcnt(3)
	v_mfma_f32_16x16x32_bf16 v[124:127], v[132:135], v[160:163], v[124:127]
	v_mfma_f32_16x16x32_bf16 v[120:123], v[152:155], v[160:163], v[120:123]
	s_waitcnt lgkmcnt(2)
	v_mfma_f32_16x16x32_bf16 v[108:111], v[132:135], v[168:171], v[108:111]
	v_mfma_f32_16x16x32_bf16 v[104:107], v[152:155], v[168:171], v[104:107]
	s_waitcnt lgkmcnt(1)
	v_mfma_f32_16x16x32_bf16 v[92:95], v[132:135], v[198:201], v[92:95]
	v_mfma_f32_16x16x32_bf16 v[88:91], v[152:155], v[198:201], v[88:91]
	s_waitcnt lgkmcnt(0)
	v_mfma_f32_16x16x32_bf16 v[76:79], v[132:135], v[206:209], v[76:79]
	v_mfma_f32_16x16x32_bf16 v[72:75], v[152:155], v[206:209], v[72:75]
	s_barrier
	s_add_i32 s89, 0, 0x14000
	v_add_u32_e32 v172, s89, v191
	s_add_i32 s28, s88, s72
	ds_read_b128 v[210:213], v172
	ds_read_b128 v[214:217], v172 offset:1024
	ds_read_b128 v[232:235], v172 offset:2048
	ds_read_b128 v[236:239], v172 offset:3072
	v_lshl_add_u64 v[172:173], s[68:69], 0, v[138:139]
	s_mov_b32 m0, s28
	v_lshl_add_u64 v[188:189], s[68:69], 0, v[142:143]
	global_load_lds_dwordx4 v[172:173], off
	s_add_i32 m0, s28, 0x2000
	s_nop 0
	global_load_lds_dwordx4 v[188:189], off
	s_barrier
	s_waitcnt lgkmcnt(3)
	v_mfma_f32_16x16x32_bf16 v[116:119], v[210:213], v[156:159], v[116:119]
	s_waitcnt lgkmcnt(1)
	v_mfma_f32_16x16x32_bf16 v[112:115], v[232:235], v[156:159], v[112:115]
	v_mfma_f32_16x16x32_bf16 v[100:103], v[210:213], v[164:167], v[100:103]
	v_mfma_f32_16x16x32_bf16 v[96:99], v[232:235], v[164:167], v[96:99]
	v_mfma_f32_16x16x32_bf16 v[84:87], v[210:213], v[194:197], v[84:87]
	v_mfma_f32_16x16x32_bf16 v[80:83], v[232:235], v[194:197], v[80:83]
	v_mfma_f32_16x16x32_bf16 v[68:71], v[210:213], v[202:205], v[68:71]
	v_mfma_f32_16x16x32_bf16 v[64:67], v[232:235], v[202:205], v[64:67]
	v_mfma_f32_16x16x32_bf16 v[116:119], v[214:217], v[160:163], v[116:119]
	s_waitcnt lgkmcnt(0)
	v_mfma_f32_16x16x32_bf16 v[112:115], v[236:239], v[160:163], v[112:115]
	v_mfma_f32_16x16x32_bf16 v[100:103], v[214:217], v[168:171], v[100:103]
	v_mfma_f32_16x16x32_bf16 v[96:99], v[236:239], v[168:171], v[96:99]
	v_mfma_f32_16x16x32_bf16 v[84:87], v[214:217], v[198:201], v[84:87]
	v_mfma_f32_16x16x32_bf16 v[80:83], v[236:239], v[198:201], v[80:83]
	v_mfma_f32_16x16x32_bf16 v[68:71], v[214:217], v[206:209], v[68:71]
	v_mfma_f32_16x16x32_bf16 v[64:67], v[236:239], v[206:209], v[64:67]
	s_mov_b32 m0, s73
	v_lshl_add_u64 v[240:241], s[70:71], 0, v[136:137]
	s_barrier
	ds_read_b128 v[156:159], v192 offset:16384
	ds_read_b128 v[164:167], v192 offset:18432
	ds_read_b128 v[194:197], v192 offset:20480
	ds_read_b128 v[202:205], v192 offset:22528
	ds_read_b128 v[160:163], v192 offset:17408
	ds_read_b128 v[168:171], v192 offset:19456
	ds_read_b128 v[198:201], v192 offset:21504
	ds_read_b128 v[206:209], v192 offset:23552
	global_load_lds_dwordx4 v[240:241], off
	v_lshl_add_u64 v[242:243], s[70:71], 0, v[140:141]
	s_mov_b32 m0, s74
	s_nop 0
	global_load_lds_dwordx4 v[242:243], off
	s_barrier
	s_waitcnt lgkmcnt(7)
	v_mfma_f32_16x16x32_bf16 v[60:63], v[128:131], v[156:159], v[60:63]
	v_mfma_f32_16x16x32_bf16 v[56:59], v[148:151], v[156:159], v[56:59]
	s_waitcnt lgkmcnt(6)
	v_mfma_f32_16x16x32_bf16 v[44:47], v[128:131], v[164:167], v[44:47]
	v_mfma_f32_16x16x32_bf16 v[40:43], v[148:151], v[164:167], v[40:43]
	s_waitcnt lgkmcnt(5)
	v_mfma_f32_16x16x32_bf16 v[28:31], v[128:131], v[194:197], v[28:31]
	v_mfma_f32_16x16x32_bf16 v[24:27], v[148:151], v[194:197], v[24:27]
	s_waitcnt lgkmcnt(4)
	v_mfma_f32_16x16x32_bf16 v[12:15], v[128:131], v[202:205], v[12:15]
	v_mfma_f32_16x16x32_bf16 v[8:11], v[148:151], v[202:205], v[8:11]
	s_waitcnt lgkmcnt(3)
	v_mfma_f32_16x16x32_bf16 v[60:63], v[132:135], v[160:163], v[60:63]
	v_mfma_f32_16x16x32_bf16 v[56:59], v[152:155], v[160:163], v[56:59]
	s_waitcnt lgkmcnt(2)
	v_mfma_f32_16x16x32_bf16 v[44:47], v[132:135], v[168:171], v[44:47]
	v_mfma_f32_16x16x32_bf16 v[40:43], v[152:155], v[168:171], v[40:43]
	s_waitcnt lgkmcnt(1)
	v_mfma_f32_16x16x32_bf16 v[28:31], v[132:135], v[198:201], v[28:31]
	v_mfma_f32_16x16x32_bf16 v[24:27], v[152:155], v[198:201], v[24:27]
	s_waitcnt lgkmcnt(0)
	v_mfma_f32_16x16x32_bf16 v[12:15], v[132:135], v[206:209], v[12:15]
	v_mfma_f32_16x16x32_bf16 v[8:11], v[152:155], v[206:209], v[8:11]
	s_barrier
	s_add_u32 s28, s68, 0x40000
	s_addc_u32 s29, s69, 0
	s_add_i32 s88, s89, s72
	v_lshl_add_u64 v[128:129], s[28:29], 0, v[138:139]
	s_mov_b32 m0, s88
	s_nop 0
	global_load_lds_dwordx4 v[128:129], off
	v_lshl_add_u64 v[128:129], s[28:29], 0, v[142:143]
	s_add_i32 m0, s88, 0x2000
	s_nop 0
	global_load_lds_dwordx4 v[128:129], off
	s_waitcnt vmcnt(6)
	s_barrier
	v_mfma_f32_16x16x32_bf16 v[52:55], v[210:213], v[156:159], v[52:55]
	v_mfma_f32_16x16x32_bf16 v[48:51], v[232:235], v[156:159], v[48:51]
	v_mfma_f32_16x16x32_bf16 v[36:39], v[210:213], v[164:167], v[36:39]
	v_mfma_f32_16x16x32_bf16 v[32:35], v[232:235], v[164:167], v[32:35]
	v_mfma_f32_16x16x32_bf16 v[20:23], v[210:213], v[194:197], v[20:23]
	v_mfma_f32_16x16x32_bf16 v[16:19], v[232:235], v[194:197], v[16:19]
	v_mfma_f32_16x16x32_bf16 v[4:7], v[210:213], v[202:205], v[4:7]
	v_mfma_f32_16x16x32_bf16 v[0:3], v[232:235], v[202:205], v[0:3]
	v_mfma_f32_16x16x32_bf16 v[52:55], v[214:217], v[160:163], v[52:55]
	v_mfma_f32_16x16x32_bf16 v[48:51], v[236:239], v[160:163], v[48:51]
	v_mfma_f32_16x16x32_bf16 v[36:39], v[214:217], v[168:171], v[36:39]
	v_mfma_f32_16x16x32_bf16 v[32:35], v[236:239], v[168:171], v[32:35]
	v_mfma_f32_16x16x32_bf16 v[20:23], v[214:217], v[198:201], v[20:23]
	v_mfma_f32_16x16x32_bf16 v[16:19], v[236:239], v[198:201], v[16:19]
	v_mfma_f32_16x16x32_bf16 v[4:7], v[214:217], v[206:209], v[4:7]
	v_mfma_f32_16x16x32_bf16 v[0:3], v[236:239], v[206:209], v[0:3]
	s_add_i32 s88, 0, 0x18000
	v_add_u32_e32 v152, s88, v191
	s_barrier
	ds_read_b128 v[128:131], v152
	ds_read_b128 v[132:135], v152 offset:1024
	ds_read_b128 v[148:151], v152 offset:2048
	ds_read_b128 v[152:155], v152 offset:3072
	s_add_u32 s28, s70, 0x40000
	s_addc_u32 s29, s71, 0
	s_mov_b32 m0, s75
	v_lshl_add_u64 v[210:211], s[28:29], 0, v[136:137]
	ds_read_b128 v[156:159], v192 offset:32768
	ds_read_b128 v[164:167], v192 offset:34816
	ds_read_b128 v[194:197], v192 offset:36864
	ds_read_b128 v[202:205], v192 offset:38912
	ds_read_b128 v[160:163], v192 offset:33792
	ds_read_b128 v[168:171], v192 offset:35840
	ds_read_b128 v[198:201], v192 offset:37888
	ds_read_b128 v[206:209], v192 offset:39936
	global_load_lds_dwordx4 v[210:211], off
	v_lshl_add_u64 v[210:211], s[28:29], 0, v[140:141]
	s_mov_b32 m0, s76
	s_nop 0
	global_load_lds_dwordx4 v[210:211], off
	s_waitcnt lgkmcnt(8)
	s_barrier
	s_waitcnt lgkmcnt(7)
	v_mfma_f32_16x16x32_bf16 v[124:127], v[128:131], v[156:159], v[124:127]
	v_mfma_f32_16x16x32_bf16 v[120:123], v[148:151], v[156:159], v[120:123]
	s_waitcnt lgkmcnt(6)
	v_mfma_f32_16x16x32_bf16 v[108:111], v[128:131], v[164:167], v[108:111]
	v_mfma_f32_16x16x32_bf16 v[104:107], v[148:151], v[164:167], v[104:107]
	s_waitcnt lgkmcnt(5)
	v_mfma_f32_16x16x32_bf16 v[92:95], v[128:131], v[194:197], v[92:95]
	v_mfma_f32_16x16x32_bf16 v[88:91], v[148:151], v[194:197], v[88:91]
	s_waitcnt lgkmcnt(4)
	v_mfma_f32_16x16x32_bf16 v[76:79], v[128:131], v[202:205], v[76:79]
	v_mfma_f32_16x16x32_bf16 v[72:75], v[148:151], v[202:205], v[72:75]
	s_waitcnt lgkmcnt(3)
	v_mfma_f32_16x16x32_bf16 v[124:127], v[132:135], v[160:163], v[124:127]
	v_mfma_f32_16x16x32_bf16 v[120:123], v[152:155], v[160:163], v[120:123]
	s_waitcnt lgkmcnt(2)
	v_mfma_f32_16x16x32_bf16 v[108:111], v[132:135], v[168:171], v[108:111]
	v_mfma_f32_16x16x32_bf16 v[104:107], v[152:155], v[168:171], v[104:107]
	s_waitcnt lgkmcnt(1)
	v_mfma_f32_16x16x32_bf16 v[92:95], v[132:135], v[198:201], v[92:95]
	v_mfma_f32_16x16x32_bf16 v[88:91], v[152:155], v[198:201], v[88:91]
	s_waitcnt lgkmcnt(0)
	v_mfma_f32_16x16x32_bf16 v[76:79], v[132:135], v[206:209], v[76:79]
	v_mfma_f32_16x16x32_bf16 v[72:75], v[152:155], v[206:209], v[72:75]
	s_barrier
	s_add_i32 s70, 0, 0x1c000
	s_add_i32 s28, s88, s72
	v_add_u32_e32 v174, s70, v191
	v_lshl_add_u64 v[172:173], v[172:173], 0, s[40:41]
	s_mov_b32 m0, s28
	ds_read_b128 v[210:213], v174
	ds_read_b128 v[214:217], v174 offset:1024
	ds_read_b128 v[232:235], v174 offset:2048
	ds_read_b128 v[236:239], v174 offset:3072
	global_load_lds_dwordx4 v[172:173], off
	v_lshl_add_u64 v[172:173], v[188:189], 0, s[40:41]
	s_add_i32 m0, s28, 0x2000
	s_nop 0
	global_load_lds_dwordx4 v[172:173], off
	s_barrier
	s_waitcnt lgkmcnt(3)
	v_mfma_f32_16x16x32_bf16 v[116:119], v[210:213], v[156:159], v[116:119]
	s_waitcnt lgkmcnt(1)
	v_mfma_f32_16x16x32_bf16 v[112:115], v[232:235], v[156:159], v[112:115]
	v_mfma_f32_16x16x32_bf16 v[100:103], v[210:213], v[164:167], v[100:103]
	v_mfma_f32_16x16x32_bf16 v[96:99], v[232:235], v[164:167], v[96:99]
	v_mfma_f32_16x16x32_bf16 v[84:87], v[210:213], v[194:197], v[84:87]
	v_mfma_f32_16x16x32_bf16 v[80:83], v[232:235], v[194:197], v[80:83]
	v_mfma_f32_16x16x32_bf16 v[68:71], v[210:213], v[202:205], v[68:71]
	v_mfma_f32_16x16x32_bf16 v[64:67], v[232:235], v[202:205], v[64:67]
	v_mfma_f32_16x16x32_bf16 v[116:119], v[214:217], v[160:163], v[116:119]
	s_waitcnt lgkmcnt(0)
	v_mfma_f32_16x16x32_bf16 v[112:115], v[236:239], v[160:163], v[112:115]
	v_mfma_f32_16x16x32_bf16 v[100:103], v[214:217], v[168:171], v[100:103]
	v_mfma_f32_16x16x32_bf16 v[96:99], v[236:239], v[168:171], v[96:99]
	v_mfma_f32_16x16x32_bf16 v[84:87], v[214:217], v[198:201], v[84:87]
	v_mfma_f32_16x16x32_bf16 v[80:83], v[236:239], v[198:201], v[80:83]
	v_mfma_f32_16x16x32_bf16 v[68:71], v[214:217], v[206:209], v[68:71]
	v_mfma_f32_16x16x32_bf16 v[64:67], v[236:239], v[206:209], v[64:67]
	s_mov_b32 m0, s79
	v_lshl_add_u64 v[172:173], v[240:241], 0, s[40:41]
	s_barrier
	ds_read_b128 v[156:159], v192 offset:49152
	ds_read_b128 v[164:167], v192 offset:51200
	ds_read_b128 v[194:197], v192 offset:53248
	ds_read_b128 v[202:205], v192 offset:55296
	ds_read_b128 v[160:163], v192 offset:50176
	ds_read_b128 v[168:171], v192 offset:52224
	ds_read_b128 v[198:201], v192 offset:54272
	ds_read_b128 v[206:209], v192 offset:56320
	global_load_lds_dwordx4 v[172:173], off
	v_lshl_add_u64 v[172:173], v[242:243], 0, s[40:41]
	s_mov_b32 m0, s80
	s_nop 0
	global_load_lds_dwordx4 v[172:173], off
	s_barrier
	s_waitcnt lgkmcnt(7)
	v_mfma_f32_16x16x32_bf16 v[60:63], v[128:131], v[156:159], v[60:63]
	v_mfma_f32_16x16x32_bf16 v[56:59], v[148:151], v[156:159], v[56:59]
	s_waitcnt lgkmcnt(6)
	v_mfma_f32_16x16x32_bf16 v[44:47], v[128:131], v[164:167], v[44:47]
	v_mfma_f32_16x16x32_bf16 v[40:43], v[148:151], v[164:167], v[40:43]
	s_waitcnt lgkmcnt(5)
	v_mfma_f32_16x16x32_bf16 v[28:31], v[128:131], v[194:197], v[28:31]
	v_mfma_f32_16x16x32_bf16 v[24:27], v[148:151], v[194:197], v[24:27]
	s_waitcnt lgkmcnt(4)
	v_mfma_f32_16x16x32_bf16 v[12:15], v[128:131], v[202:205], v[12:15]
	v_mfma_f32_16x16x32_bf16 v[8:11], v[148:151], v[202:205], v[8:11]
	s_waitcnt lgkmcnt(3)
	v_mfma_f32_16x16x32_bf16 v[60:63], v[132:135], v[160:163], v[60:63]
	v_mfma_f32_16x16x32_bf16 v[56:59], v[152:155], v[160:163], v[56:59]
	s_waitcnt lgkmcnt(2)
	v_mfma_f32_16x16x32_bf16 v[44:47], v[132:135], v[168:171], v[44:47]
	v_mfma_f32_16x16x32_bf16 v[40:43], v[152:155], v[168:171], v[40:43]
	s_waitcnt lgkmcnt(1)
	v_mfma_f32_16x16x32_bf16 v[28:31], v[132:135], v[198:201], v[28:31]
	v_mfma_f32_16x16x32_bf16 v[24:27], v[152:155], v[198:201], v[24:27]
	s_waitcnt lgkmcnt(0)
	v_mfma_f32_16x16x32_bf16 v[12:15], v[132:135], v[206:209], v[12:15]
	v_mfma_f32_16x16x32_bf16 v[8:11], v[152:155], v[206:209], v[8:11]
	s_barrier
	s_add_u32 s28, s68, 0x40080
	s_addc_u32 s29, s69, 0
	s_add_i32 s68, s70, s72
	v_lshl_add_u64 v[128:129], s[28:29], 0, v[138:139]
	s_mov_b32 m0, s68
	s_nop 0
	global_load_lds_dwordx4 v[128:129], off
	v_lshl_add_u64 v[128:129], s[28:29], 0, v[142:143]
	s_add_i32 m0, s68, 0x2000
	s_nop 0
	global_load_lds_dwordx4 v[128:129], off
	s_waitcnt vmcnt(6)
	s_barrier
	v_mfma_f32_16x16x32_bf16 v[52:55], v[210:213], v[156:159], v[52:55]
	v_mfma_f32_16x16x32_bf16 v[48:51], v[232:235], v[156:159], v[48:51]
	v_mfma_f32_16x16x32_bf16 v[36:39], v[210:213], v[164:167], v[36:39]
	v_mfma_f32_16x16x32_bf16 v[32:35], v[232:235], v[164:167], v[32:35]
	v_mfma_f32_16x16x32_bf16 v[20:23], v[210:213], v[194:197], v[20:23]
	v_mfma_f32_16x16x32_bf16 v[16:19], v[232:235], v[194:197], v[16:19]
	v_mfma_f32_16x16x32_bf16 v[4:7], v[210:213], v[202:205], v[4:7]
	v_mfma_f32_16x16x32_bf16 v[0:3], v[232:235], v[202:205], v[0:3]
	v_mfma_f32_16x16x32_bf16 v[52:55], v[214:217], v[160:163], v[52:55]
	v_mfma_f32_16x16x32_bf16 v[48:51], v[236:239], v[160:163], v[48:51]
	v_mfma_f32_16x16x32_bf16 v[36:39], v[214:217], v[168:171], v[36:39]
	v_mfma_f32_16x16x32_bf16 v[32:35], v[236:239], v[168:171], v[32:35]
	v_mfma_f32_16x16x32_bf16 v[20:23], v[214:217], v[198:201], v[20:23]
	v_mfma_f32_16x16x32_bf16 v[16:19], v[236:239], v[198:201], v[16:19]
	v_mfma_f32_16x16x32_bf16 v[4:7], v[214:217], v[206:209], v[4:7]
	v_mfma_f32_16x16x32_bf16 v[0:3], v[236:239], v[206:209], v[0:3]
	s_add_i32 vcc_lo, vcc_lo, 2
	s_add_u32 s66, s66, 0x100
	s_addc_u32 s67, s67, 0
	s_add_u32 s85, s85, 0x100
	s_addc_u32 s91, s91, 0
	s_cmp_lt_u32 vcc_lo, 14
	s_barrier
	s_cbranch_scc1 .LBB0_134
	s_lshl_b32 s4, s4, 8
	v_mov_b32_e32 v176, v175
	v_mov_b32_e32 v188, v190
	s_add_i32 s4, s4, s77
	s_cmp_gt_i32 s6, 7
	v_add_u32_e32 v148, s4, v176
	v_lshlrev_b32_e32 v128, 2, v188
	v_ashrrev_i32_e32 v129, 31, v128
	v_ashrrev_i32_e32 v149, 31, v148
	v_lshl_add_u64 v[128:129], v[128:129], 2, s[8:9]
	v_lshlrev_b64 v[130:131], 6, v[148:149]
	v_add_u32_e32 v166, 16, v148
	v_lshl_add_u64 v[130:131], v[128:129], 0, v[130:131]
	v_ashrrev_i32_e32 v167, 31, v166
	global_load_dwordx4 v[160:163], v[130:131], off
	v_lshlrev_b64 v[130:131], 6, v[166:167]
	v_lshl_add_u64 v[130:131], v[128:129], 0, v[130:131]
	global_load_dwordx4 v[168:171], v[130:131], off
	v_add_u32_e32 v164, 32, v148
	v_ashrrev_i32_e32 v165, 31, v164
	v_lshlrev_b64 v[130:131], 6, v[164:165]
	v_add_u32_e32 v158, 48, v148
	v_lshl_add_u64 v[130:131], v[128:129], 0, v[130:131]
	v_ashrrev_i32_e32 v159, 31, v158
	global_load_dwordx4 v[194:197], v[130:131], off
	v_lshlrev_b64 v[130:131], 6, v[158:159]
	v_lshl_add_u64 v[130:131], v[128:129], 0, v[130:131]
	global_load_dwordx4 v[198:201], v[130:131], off
	v_add_u32_e32 v156, 0x80, v148
	v_ashrrev_i32_e32 v157, 31, v156
	v_lshlrev_b64 v[130:131], 6, v[156:157]
	v_add_u32_e32 v154, 0x90, v148
	v_lshl_add_u64 v[130:131], v[128:129], 0, v[130:131]
	v_ashrrev_i32_e32 v155, 31, v154
	global_load_dwordx4 v[202:205], v[130:131], off
	v_lshlrev_b64 v[130:131], 6, v[154:155]
	v_add_u32_e32 v152, 0xa0, v148
	v_lshl_add_u64 v[130:131], v[128:129], 0, v[130:131]
	v_ashrrev_i32_e32 v153, 31, v152
	global_load_dwordx4 v[206:209], v[130:131], off
	v_lshlrev_b64 v[130:131], 6, v[152:153]
	v_add_u32_e32 v150, 0xb0, v148
	v_lshl_add_u64 v[130:131], v[128:129], 0, v[130:131]
	v_ashrrev_i32_e32 v151, 31, v150
	global_load_dwordx4 v[132:135], v[130:131], off
	v_lshlrev_b64 v[130:131], 6, v[150:151]
	v_lshl_add_u64 v[128:129], v[128:129], 0, v[130:131]
	global_load_dwordx4 v[128:131], v[128:129], off
	s_cselect_b64 s[66:67], -1, 0
	s_lshl_b32 s7, s6, 8
	s_add_i32 s7, s81, s7
	s_cmp_lt_i32 s6, 8
	s_mov_b64 s[68:69], -1
	s_waitcnt vmcnt(0)
	v_mov_b32_e32 v172, v161
	v_mov_b32_e32 v173, v162
	v_mov_b32_e32 v161, v163
	v_mov_b32_e32 v162, v169
	v_mov_b32_e32 v163, v170
	v_mov_b32_e32 v169, v171
	v_pk_add_f32 v[160:161], v[172:173], v[160:161]
	v_pk_add_f32 v[162:163], v[162:163], v[168:169]
	v_mov_b32_e32 v169, v160
	v_mov_b32_e32 v168, v162
	v_mov_b32_e32 v160, v163
	v_pk_add_f32 v[160:161], v[168:169], v[160:161]
	ds_bpermute_b32 v163, v219, v161
	ds_bpermute_b32 v162, v219, v160
	s_waitcnt lgkmcnt(0)
	v_pk_add_f32 v[160:161], v[160:161], v[162:163]
	ds_bpermute_b32 v163, v218, v161
	ds_bpermute_b32 v162, v218, v160
	s_waitcnt lgkmcnt(0)
	v_pk_add_f32 v[160:161], v[160:161], v[162:163]
	s_nop 0
	v_pk_fma_f32 v[172:173], v[160:161], s[30:31], v[178:179] op_sel_hi:[1,0,0]
	v_mov_b32_e32 v162, v199
	v_mul_f32_e32 v160, 0x4b800000, v173
	v_cmp_gt_f32_e32 vcc, s86, v173
	v_mov_b32_e32 v163, v200
	v_mov_b32_e32 v199, v201
	v_cndmask_b32_e32 v160, v173, v160, vcc
	v_rsq_f32_e32 v160, v160
	v_pk_add_f32 v[162:163], v[162:163], v[198:199]
	v_cmp_gt_f32_e64 s[4:5], s86, v172
	v_mov_b32_e32 v168, v162
	v_mul_f32_e32 v161, 0x45800000, v160
	v_cndmask_b32_e32 v174, v160, v161, vcc
	v_mov_b32_e32 v160, v195
	v_mov_b32_e32 v161, v196
	v_mov_b32_e32 v195, v197
	v_pk_add_f32 v[160:161], v[160:161], v[194:195]
	s_nop 0
	v_mov_b32_e32 v169, v160
	v_mov_b32_e32 v160, v163
	v_pk_add_f32 v[160:161], v[168:169], v[160:161]
	ds_bpermute_b32 v163, v219, v161
	ds_bpermute_b32 v162, v219, v160
	s_waitcnt lgkmcnt(0)
	v_pk_add_f32 v[168:169], v[160:161], v[162:163]
	v_mov_b32_e32 v160, v203
	v_mov_b32_e32 v161, v204
	v_mov_b32_e32 v203, v205
	v_mov_b32_e32 v162, v207
	v_mov_b32_e32 v163, v208
	v_mov_b32_e32 v207, v209
	v_pk_add_f32 v[160:161], v[160:161], v[202:203]
	v_pk_add_f32 v[162:163], v[162:163], v[206:207]
	v_mov_b32_e32 v195, v160
	v_mov_b32_e32 v194, v162
	v_mov_b32_e32 v160, v163
	v_pk_add_f32 v[160:161], v[194:195], v[160:161]
	v_mov_b32_e32 v194, v133
	v_mov_b32_e32 v195, v134
	v_mov_b32_e32 v133, v135
	v_mov_b32_e32 v134, v129
	v_mov_b32_e32 v135, v130
	v_mov_b32_e32 v129, v131
	v_pk_add_f32 v[132:133], v[194:195], v[132:133]
	v_pk_add_f32 v[128:129], v[134:135], v[128:129]
	v_mov_b32_e32 v131, v132
	v_mov_b32_e32 v130, v128
	v_mov_b32_e32 v132, v129
	v_pk_add_f32 v[128:129], v[130:131], v[132:133]
	ds_bpermute_b32 v163, v219, v161
	ds_bpermute_b32 v162, v219, v160
	ds_bpermute_b32 v131, v219, v129
	ds_bpermute_b32 v130, v219, v128
	ds_bpermute_b32 v171, v218, v169
	ds_bpermute_b32 v170, v218, v168
	s_waitcnt lgkmcnt(4)
	v_pk_add_f32 v[160:161], v[160:161], v[162:163]
	ds_bpermute_b32 v163, v218, v161
	s_waitcnt lgkmcnt(3)
	v_pk_add_f32 v[132:133], v[128:129], v[130:131]
	ds_bpermute_b32 v162, v218, v160
	ds_bpermute_b32 v135, v218, v133
	ds_bpermute_b32 v134, v218, v132
	v_lshlrev_b32_e32 v128, 3, v188
	v_add_u32_e32 v130, s7, v128
	v_lshlrev_b64 v[188:189], 11, v[148:149]
	v_ashrrev_i32_e32 v131, 31, v130
	s_cbranch_scc1 .LBB0_137
	v_mul_f32_e32 v196, v120, v174
	v_mul_f32_e32 v197, v121, v174
	v_mul_f32_e32 v198, v122, v174
	v_mul_f32_e32 v199, v123, v174
	v_mul_f32_e32 v129, v124, v174
	v_mul_f32_e32 v149, v125, v174
	v_mul_f32_e32 v173, v126, v174
	v_mul_f32_e32 v193, v127, v174
	v_cvt_pk_bf16_f32 v194, v129, v149
	v_cvt_pk_bf16_f32 v195, v173, v193
	v_cvt_pk_bf16_f32 v196, v196, v197
	v_cvt_pk_bf16_f32 v197, v198, v199
	v_lshl_add_u64 v[198:199], s[12:13], 0, v[188:189]
	v_lshl_add_u64 v[198:199], v[130:131], 1, v[198:199]
	global_store_dwordx4 v[198:199], v[194:197], off
	s_mov_b64 s[68:69], 0
	v_mul_f32_e32 v129, v116, v174
	v_mul_f32_e32 v196, v112, v174
	v_mul_f32_e32 v197, v113, v174
	v_mul_f32_e32 v149, v117, v174
	v_mul_f32_e32 v173, v118, v174
	v_mul_f32_e32 v193, v119, v174
	v_mul_f32_e32 v200, v114, v174
	v_mul_f32_e32 v201, v115, v174
	v_cvt_pk_bf16_f32 v194, v129, v149
	v_cvt_pk_bf16_f32 v195, v173, v193
	v_cvt_pk_bf16_f32 v196, v196, v197
	v_cvt_pk_bf16_f32 v197, v200, v201
	global_store_dwordx4 v[198:199], v[194:197], off offset:256

.LBB0_413:
	s_add_i32 vcc_lo, s62, 2
	s_add_u32 s4, s18, 0x100
	s_addc_u32 s5, s19, 0
	s_add_i32 s28, 0, 0x10000
	v_add_u32_e32 v140, s28, v164
	ds_read_b128 v[128:131], v140
	ds_read_b128 v[132:135], v140 offset:1024
	ds_read_b128 v[136:139], v140 offset:2048
	ds_read_b128 v[140:143], v140 offset:3072
	s_cmp_eq_u32 s13, s62
	s_cselect_b32 s62, s6, s85
	s_cselect_b32 s65, s17, s5
	s_cselect_b32 s64, s16, s4
	s_cselect_b32 s63, s7, s91
	v_lshl_add_u64 v[174:175], s[18:19], 0, v[150:151]
	s_add_i32 m0, s69, 0xc000
	ds_read_b128 v[154:157], v165
	ds_read_b128 v[166:169], v165 offset:2048
	ds_read_b128 v[188:191], v165 offset:4096
	ds_read_b128 v[196:199], v165 offset:6144
	ds_read_b128 v[158:161], v165 offset:1024
	ds_read_b128 v[170:173], v165 offset:3072
	ds_read_b128 v[192:195], v165 offset:5120
	ds_read_b128 v[200:203], v165 offset:7168
	global_load_lds_dwordx4 v[174:175], off
	v_lshl_add_u64 v[174:175], s[18:19], 0, v[152:153]
	s_add_i32 m0, s69, 0xe000
	s_nop 0
	global_load_lds_dwordx4 v[174:175], off
	s_waitcnt lgkmcnt(8)
	s_barrier
	s_waitcnt lgkmcnt(7)
	v_mfma_f32_16x16x32_bf16 v[124:127], v[128:131], v[154:157], v[124:127]
	v_mfma_f32_16x16x32_bf16 v[120:123], v[136:139], v[154:157], v[120:123]
	s_waitcnt lgkmcnt(6)
	v_mfma_f32_16x16x32_bf16 v[108:111], v[128:131], v[166:169], v[108:111]
	v_mfma_f32_16x16x32_bf16 v[104:107], v[136:139], v[166:169], v[104:107]
	s_waitcnt lgkmcnt(5)
	v_mfma_f32_16x16x32_bf16 v[92:95], v[128:131], v[188:191], v[92:95]
	v_mfma_f32_16x16x32_bf16 v[88:91], v[136:139], v[188:191], v[88:91]
	s_waitcnt lgkmcnt(4)
	v_mfma_f32_16x16x32_bf16 v[76:79], v[128:131], v[196:199], v[76:79]
	v_mfma_f32_16x16x32_bf16 v[72:75], v[136:139], v[196:199], v[72:75]
	s_waitcnt lgkmcnt(3)
	v_mfma_f32_16x16x32_bf16 v[124:127], v[132:135], v[158:161], v[124:127]
	v_mfma_f32_16x16x32_bf16 v[120:123], v[140:143], v[158:161], v[120:123]
	s_waitcnt lgkmcnt(2)
	v_mfma_f32_16x16x32_bf16 v[108:111], v[132:135], v[170:173], v[108:111]
	v_mfma_f32_16x16x32_bf16 v[104:107], v[140:143], v[170:173], v[104:107]
	s_waitcnt lgkmcnt(1)
	v_mfma_f32_16x16x32_bf16 v[92:95], v[132:135], v[192:195], v[92:95]
	v_mfma_f32_16x16x32_bf16 v[88:91], v[140:143], v[192:195], v[88:91]
	s_waitcnt lgkmcnt(0)
	v_mfma_f32_16x16x32_bf16 v[76:79], v[132:135], v[200:203], v[76:79]
	v_mfma_f32_16x16x32_bf16 v[72:75], v[140:143], v[200:203], v[72:75]
	s_barrier
	s_add_i32 s29, 0, 0x14000
	v_add_u32_e32 v174, s29, v164
	s_add_i32 s18, s28, s68
	ds_read_b128 v[204:207], v174
	ds_read_b128 v[208:211], v174 offset:1024
	ds_read_b128 v[212:215], v174 offset:2048
	ds_read_b128 v[232:235], v174 offset:3072
	v_lshl_add_u64 v[174:175], s[62:63], 0, v[176:177]
	s_mov_b32 m0, s18
	v_lshl_add_u64 v[216:217], s[62:63], 0, v[148:149]
	global_load_lds_dwordx4 v[174:175], off
	s_add_i32 m0, s18, 0x2000
	s_nop 0
	global_load_lds_dwordx4 v[216:217], off
	s_barrier
	s_waitcnt lgkmcnt(3)
	v_mfma_f32_16x16x32_bf16 v[116:119], v[204:207], v[154:157], v[116:119]
	s_waitcnt lgkmcnt(1)
	v_mfma_f32_16x16x32_bf16 v[112:115], v[212:215], v[154:157], v[112:115]
	v_mfma_f32_16x16x32_bf16 v[100:103], v[204:207], v[166:169], v[100:103]
	v_mfma_f32_16x16x32_bf16 v[96:99], v[212:215], v[166:169], v[96:99]
	v_mfma_f32_16x16x32_bf16 v[84:87], v[204:207], v[188:191], v[84:87]
	v_mfma_f32_16x16x32_bf16 v[80:83], v[212:215], v[188:191], v[80:83]
	v_mfma_f32_16x16x32_bf16 v[68:71], v[204:207], v[196:199], v[68:71]
	v_mfma_f32_16x16x32_bf16 v[64:67], v[212:215], v[196:199], v[64:67]
	v_mfma_f32_16x16x32_bf16 v[116:119], v[208:211], v[158:161], v[116:119]
	s_waitcnt lgkmcnt(0)
	v_mfma_f32_16x16x32_bf16 v[112:115], v[232:235], v[158:161], v[112:115]
	v_mfma_f32_16x16x32_bf16 v[100:103], v[208:211], v[170:173], v[100:103]
	v_mfma_f32_16x16x32_bf16 v[96:99], v[232:235], v[170:173], v[96:99]
	v_mfma_f32_16x16x32_bf16 v[84:87], v[208:211], v[192:195], v[84:87]
	v_mfma_f32_16x16x32_bf16 v[80:83], v[232:235], v[192:195], v[80:83]
	v_mfma_f32_16x16x32_bf16 v[68:71], v[208:211], v[200:203], v[68:71]
	v_mfma_f32_16x16x32_bf16 v[64:67], v[232:235], v[200:203], v[64:67]
	s_mov_b32 m0, s69
	v_lshl_add_u64 v[236:237], s[64:65], 0, v[144:145]
	s_barrier
	ds_read_b128 v[154:157], v165 offset:16384
	ds_read_b128 v[166:169], v165 offset:18432
	ds_read_b128 v[188:191], v165 offset:20480
	ds_read_b128 v[196:199], v165 offset:22528
	ds_read_b128 v[158:161], v165 offset:17408
	ds_read_b128 v[170:173], v165 offset:19456
	ds_read_b128 v[192:195], v165 offset:21504
	ds_read_b128 v[200:203], v165 offset:23552
	global_load_lds_dwordx4 v[236:237], off
	v_lshl_add_u64 v[238:239], s[64:65], 0, v[146:147]
	s_mov_b32 m0, s70
	s_nop 0
	global_load_lds_dwordx4 v[238:239], off
	s_barrier
	s_waitcnt lgkmcnt(7)
	v_mfma_f32_16x16x32_bf16 v[60:63], v[128:131], v[154:157], v[60:63]
	v_mfma_f32_16x16x32_bf16 v[56:59], v[136:139], v[154:157], v[56:59]
	s_waitcnt lgkmcnt(6)
	v_mfma_f32_16x16x32_bf16 v[44:47], v[128:131], v[166:169], v[44:47]
	v_mfma_f32_16x16x32_bf16 v[40:43], v[136:139], v[166:169], v[40:43]
	s_waitcnt lgkmcnt(5)
	v_mfma_f32_16x16x32_bf16 v[28:31], v[128:131], v[188:191], v[28:31]
	v_mfma_f32_16x16x32_bf16 v[24:27], v[136:139], v[188:191], v[24:27]
	s_waitcnt lgkmcnt(4)
	v_mfma_f32_16x16x32_bf16 v[12:15], v[128:131], v[196:199], v[12:15]
	v_mfma_f32_16x16x32_bf16 v[8:11], v[136:139], v[196:199], v[8:11]
	s_waitcnt lgkmcnt(3)
	v_mfma_f32_16x16x32_bf16 v[60:63], v[132:135], v[158:161], v[60:63]
	v_mfma_f32_16x16x32_bf16 v[56:59], v[140:143], v[158:161], v[56:59]
	s_waitcnt lgkmcnt(2)
	v_mfma_f32_16x16x32_bf16 v[44:47], v[132:135], v[170:173], v[44:47]
	v_mfma_f32_16x16x32_bf16 v[40:43], v[140:143], v[170:173], v[40:43]
	s_waitcnt lgkmcnt(1)
	v_mfma_f32_16x16x32_bf16 v[28:31], v[132:135], v[192:195], v[28:31]
	v_mfma_f32_16x16x32_bf16 v[24:27], v[140:143], v[192:195], v[24:27]
	s_waitcnt lgkmcnt(0)
	v_mfma_f32_16x16x32_bf16 v[12:15], v[132:135], v[200:203], v[12:15]
	v_mfma_f32_16x16x32_bf16 v[8:11], v[140:143], v[200:203], v[8:11]
	s_barrier
	s_add_u32 s18, s62, 0x18000
	s_addc_u32 s19, s63, 0
	s_add_i32 s28, s29, s68
	v_lshl_add_u64 v[128:129], s[18:19], 0, v[176:177]
	s_mov_b32 m0, s28
	s_nop 0
	global_load_lds_dwordx4 v[128:129], off
	v_lshl_add_u64 v[128:129], s[18:19], 0, v[148:149]
	s_add_i32 m0, s28, 0x2000
	s_nop 0
	global_load_lds_dwordx4 v[128:129], off
	s_waitcnt vmcnt(6)
	s_barrier
	v_mfma_f32_16x16x32_bf16 v[52:55], v[204:207], v[154:157], v[52:55]
	v_mfma_f32_16x16x32_bf16 v[48:51], v[212:215], v[154:157], v[48:51]
	v_mfma_f32_16x16x32_bf16 v[36:39], v[204:207], v[166:169], v[36:39]
	v_mfma_f32_16x16x32_bf16 v[32:35], v[212:215], v[166:169], v[32:35]
	v_mfma_f32_16x16x32_bf16 v[20:23], v[204:207], v[188:191], v[20:23]
	v_mfma_f32_16x16x32_bf16 v[16:19], v[212:215], v[188:191], v[16:19]
	v_mfma_f32_16x16x32_bf16 v[4:7], v[204:207], v[196:199], v[4:7]
	v_mfma_f32_16x16x32_bf16 v[0:3], v[212:215], v[196:199], v[0:3]
	v_mfma_f32_16x16x32_bf16 v[52:55], v[208:211], v[158:161], v[52:55]
	v_mfma_f32_16x16x32_bf16 v[48:51], v[232:235], v[158:161], v[48:51]
	v_mfma_f32_16x16x32_bf16 v[36:39], v[208:211], v[170:173], v[36:39]
	v_mfma_f32_16x16x32_bf16 v[32:35], v[232:235], v[170:173], v[32:35]
	v_mfma_f32_16x16x32_bf16 v[20:23], v[208:211], v[192:195], v[20:23]
	v_mfma_f32_16x16x32_bf16 v[16:19], v[232:235], v[192:195], v[16:19]
	v_mfma_f32_16x16x32_bf16 v[4:7], v[208:211], v[200:203], v[4:7]
	v_mfma_f32_16x16x32_bf16 v[0:3], v[232:235], v[200:203], v[0:3]
	s_add_i32 s28, 0, 0x18000
	v_add_u32_e32 v140, s28, v164
	s_barrier
	ds_read_b128 v[128:131], v140
	ds_read_b128 v[132:135], v140 offset:1024
	ds_read_b128 v[136:139], v140 offset:2048
	ds_read_b128 v[140:143], v140 offset:3072
	s_add_u32 s18, s64, 0x18000
	s_addc_u32 s19, s65, 0
	s_mov_b32 m0, s71
	v_lshl_add_u64 v[204:205], s[18:19], 0, v[144:145]
	ds_read_b128 v[154:157], v165 offset:32768
	ds_read_b128 v[166:169], v165 offset:34816
	ds_read_b128 v[188:191], v165 offset:36864
	ds_read_b128 v[196:199], v165 offset:38912
	ds_read_b128 v[158:161], v165 offset:33792
	ds_read_b128 v[170:173], v165 offset:35840
	ds_read_b128 v[192:195], v165 offset:37888
	ds_read_b128 v[200:203], v165 offset:39936
	global_load_lds_dwordx4 v[204:205], off
	v_lshl_add_u64 v[204:205], s[18:19], 0, v[146:147]
	s_mov_b32 m0, s72
	s_nop 0
	global_load_lds_dwordx4 v[204:205], off
	s_waitcnt lgkmcnt(8)
	s_barrier
	s_waitcnt lgkmcnt(7)
	v_mfma_f32_16x16x32_bf16 v[124:127], v[128:131], v[154:157], v[124:127]
	v_mfma_f32_16x16x32_bf16 v[120:123], v[136:139], v[154:157], v[120:123]
	s_waitcnt lgkmcnt(6)
	v_mfma_f32_16x16x32_bf16 v[108:111], v[128:131], v[166:169], v[108:111]
	v_mfma_f32_16x16x32_bf16 v[104:107], v[136:139], v[166:169], v[104:107]
	s_waitcnt lgkmcnt(5)
	v_mfma_f32_16x16x32_bf16 v[92:95], v[128:131], v[188:191], v[92:95]
	v_mfma_f32_16x16x32_bf16 v[88:91], v[136:139], v[188:191], v[88:91]
	s_waitcnt lgkmcnt(4)
	v_mfma_f32_16x16x32_bf16 v[76:79], v[128:131], v[196:199], v[76:79]
	v_mfma_f32_16x16x32_bf16 v[72:75], v[136:139], v[196:199], v[72:75]
	s_waitcnt lgkmcnt(3)
	v_mfma_f32_16x16x32_bf16 v[124:127], v[132:135], v[158:161], v[124:127]
	v_mfma_f32_16x16x32_bf16 v[120:123], v[140:143], v[158:161], v[120:123]
	s_waitcnt lgkmcnt(2)
	v_mfma_f32_16x16x32_bf16 v[108:111], v[132:135], v[170:173], v[108:111]
	v_mfma_f32_16x16x32_bf16 v[104:107], v[140:143], v[170:173], v[104:107]
	s_waitcnt lgkmcnt(1)
	v_mfma_f32_16x16x32_bf16 v[92:95], v[132:135], v[192:195], v[92:95]
	v_mfma_f32_16x16x32_bf16 v[88:91], v[140:143], v[192:195], v[88:91]
	s_waitcnt lgkmcnt(0)
	v_mfma_f32_16x16x32_bf16 v[76:79], v[132:135], v[200:203], v[76:79]
	v_mfma_f32_16x16x32_bf16 v[72:75], v[140:143], v[200:203], v[72:75]
	s_barrier
	s_add_i32 s29, 0, 0x1c000
	s_add_i32 s18, s28, s68
	v_add_u32_e32 v232, s29, v164
	v_lshl_add_u64 v[174:175], v[174:175], 0, s[40:41]
	s_mov_b32 m0, s18
	ds_read_b128 v[204:207], v232
	ds_read_b128 v[208:211], v232 offset:1024
	ds_read_b128 v[212:215], v232 offset:2048
	ds_read_b128 v[232:235], v232 offset:3072
	global_load_lds_dwordx4 v[174:175], off
	v_lshl_add_u64 v[174:175], v[216:217], 0, s[40:41]
	s_add_i32 m0, s18, 0x2000
	s_nop 0
	global_load_lds_dwordx4 v[174:175], off
	s_barrier
	s_waitcnt lgkmcnt(3)
	v_mfma_f32_16x16x32_bf16 v[116:119], v[204:207], v[154:157], v[116:119]
	s_waitcnt lgkmcnt(1)
	v_mfma_f32_16x16x32_bf16 v[112:115], v[212:215], v[154:157], v[112:115]
	v_mfma_f32_16x16x32_bf16 v[100:103], v[204:207], v[166:169], v[100:103]
	v_mfma_f32_16x16x32_bf16 v[96:99], v[212:215], v[166:169], v[96:99]
	v_mfma_f32_16x16x32_bf16 v[84:87], v[204:207], v[188:191], v[84:87]
	v_mfma_f32_16x16x32_bf16 v[80:83], v[212:215], v[188:191], v[80:83]
	v_mfma_f32_16x16x32_bf16 v[68:71], v[204:207], v[196:199], v[68:71]
	v_mfma_f32_16x16x32_bf16 v[64:67], v[212:215], v[196:199], v[64:67]
	v_mfma_f32_16x16x32_bf16 v[116:119], v[208:211], v[158:161], v[116:119]
	s_waitcnt lgkmcnt(0)
	v_mfma_f32_16x16x32_bf16 v[112:115], v[232:235], v[158:161], v[112:115]
	v_mfma_f32_16x16x32_bf16 v[100:103], v[208:211], v[170:173], v[100:103]
	v_mfma_f32_16x16x32_bf16 v[96:99], v[232:235], v[170:173], v[96:99]
	v_mfma_f32_16x16x32_bf16 v[84:87], v[208:211], v[192:195], v[84:87]
	v_mfma_f32_16x16x32_bf16 v[80:83], v[232:235], v[192:195], v[80:83]
	v_mfma_f32_16x16x32_bf16 v[68:71], v[208:211], v[200:203], v[68:71]
	v_mfma_f32_16x16x32_bf16 v[64:67], v[232:235], v[200:203], v[64:67]
	s_mov_b32 m0, s75
	v_lshl_add_u64 v[174:175], v[236:237], 0, s[40:41]
	s_barrier
	ds_read_b128 v[154:157], v165 offset:49152
	ds_read_b128 v[166:169], v165 offset:51200
	ds_read_b128 v[188:191], v165 offset:53248
	ds_read_b128 v[196:199], v165 offset:55296
	ds_read_b128 v[158:161], v165 offset:50176
	ds_read_b128 v[170:173], v165 offset:52224
	ds_read_b128 v[192:195], v165 offset:54272
	ds_read_b128 v[200:203], v165 offset:56320
	global_load_lds_dwordx4 v[174:175], off
	v_lshl_add_u64 v[174:175], v[238:239], 0, s[40:41]
	s_mov_b32 m0, s76
	s_nop 0
	global_load_lds_dwordx4 v[174:175], off
	s_barrier
	s_waitcnt lgkmcnt(7)
	v_mfma_f32_16x16x32_bf16 v[60:63], v[128:131], v[154:157], v[60:63]
	v_mfma_f32_16x16x32_bf16 v[56:59], v[136:139], v[154:157], v[56:59]
	s_waitcnt lgkmcnt(6)
	v_mfma_f32_16x16x32_bf16 v[44:47], v[128:131], v[166:169], v[44:47]
	v_mfma_f32_16x16x32_bf16 v[40:43], v[136:139], v[166:169], v[40:43]
	s_waitcnt lgkmcnt(5)
	v_mfma_f32_16x16x32_bf16 v[28:31], v[128:131], v[188:191], v[28:31]
	v_mfma_f32_16x16x32_bf16 v[24:27], v[136:139], v[188:191], v[24:27]
	s_waitcnt lgkmcnt(4)
	v_mfma_f32_16x16x32_bf16 v[12:15], v[128:131], v[196:199], v[12:15]
	v_mfma_f32_16x16x32_bf16 v[8:11], v[136:139], v[196:199], v[8:11]
	s_waitcnt lgkmcnt(3)
	v_mfma_f32_16x16x32_bf16 v[60:63], v[132:135], v[158:161], v[60:63]
	v_mfma_f32_16x16x32_bf16 v[56:59], v[140:143], v[158:161], v[56:59]
	s_waitcnt lgkmcnt(2)
	v_mfma_f32_16x16x32_bf16 v[44:47], v[132:135], v[170:173], v[44:47]
	v_mfma_f32_16x16x32_bf16 v[40:43], v[140:143], v[170:173], v[40:43]
	s_waitcnt lgkmcnt(1)
	v_mfma_f32_16x16x32_bf16 v[28:31], v[132:135], v[192:195], v[28:31]
	v_mfma_f32_16x16x32_bf16 v[24:27], v[140:143], v[192:195], v[24:27]
	s_waitcnt lgkmcnt(0)
	v_mfma_f32_16x16x32_bf16 v[12:15], v[132:135], v[200:203], v[12:15]
	v_mfma_f32_16x16x32_bf16 v[8:11], v[140:143], v[200:203], v[8:11]
	s_barrier
	s_add_u32 s18, s62, 0x18080
	s_addc_u32 s19, s63, 0
	s_add_i32 s28, s29, s68
	v_lshl_add_u64 v[128:129], s[18:19], 0, v[176:177]
	s_mov_b32 m0, s28
	s_nop 0
	global_load_lds_dwordx4 v[128:129], off
	v_lshl_add_u64 v[128:129], s[18:19], 0, v[148:149]
	s_add_i32 m0, s28, 0x2000
	s_nop 0
	global_load_lds_dwordx4 v[128:129], off
	s_waitcnt vmcnt(6)
	s_barrier
	v_mfma_f32_16x16x32_bf16 v[52:55], v[204:207], v[154:157], v[52:55]
	v_mfma_f32_16x16x32_bf16 v[48:51], v[212:215], v[154:157], v[48:51]
	v_mfma_f32_16x16x32_bf16 v[36:39], v[204:207], v[166:169], v[36:39]
	v_mfma_f32_16x16x32_bf16 v[32:35], v[212:215], v[166:169], v[32:35]
	v_mfma_f32_16x16x32_bf16 v[20:23], v[204:207], v[188:191], v[20:23]
	v_mfma_f32_16x16x32_bf16 v[16:19], v[212:215], v[188:191], v[16:19]
	v_mfma_f32_16x16x32_bf16 v[4:7], v[204:207], v[196:199], v[4:7]
	v_mfma_f32_16x16x32_bf16 v[0:3], v[212:215], v[196:199], v[0:3]
	v_mfma_f32_16x16x32_bf16 v[52:55], v[208:211], v[158:161], v[52:55]
	v_mfma_f32_16x16x32_bf16 v[48:51], v[232:235], v[158:161], v[48:51]
	v_mfma_f32_16x16x32_bf16 v[36:39], v[208:211], v[170:173], v[36:39]
	v_mfma_f32_16x16x32_bf16 v[32:35], v[232:235], v[170:173], v[32:35]
	v_mfma_f32_16x16x32_bf16 v[20:23], v[208:211], v[192:195], v[20:23]
	v_mfma_f32_16x16x32_bf16 v[16:19], v[232:235], v[192:195], v[16:19]
	v_mfma_f32_16x16x32_bf16 v[4:7], v[208:211], v[200:203], v[4:7]
	v_mfma_f32_16x16x32_bf16 v[0:3], v[232:235], v[200:203], v[0:3]
	s_add_u32 s85, s85, 0x100
	s_addc_u32 s91, s91, 0
	s_cmp_lt_i32 vcc_lo, s67
	s_mov_b64 s[18:19], s[4:5]
	s_mov_b32 s62, vcc_lo
	s_barrier
	s_cbranch_scc1 .LBB0_413
	s_ashr_i32 s4, s66, 2
	v_mov_b32_e32 v128, v163
	v_mov_b32_e32 v166, v162
	s_cmp_eq_u32 s4, 2
	s_cbranch_scc1 .LBB0_416
	s_mul_i32 s13, s4, 0x2280000
	s_mul_hi_i32 s5, s4, 0x2280000
	s_add_u32 s18, s13, 0x5858000
	s_addc_u32 s19, s5, 0
	s_mov_b32 s62, 1.0
	s_branch .LBB0_417

.LBB0_505:
	s_add_u32 s6, s4, 0xfff80080
	s_addc_u32 s7, s5, -1
	s_add_i32 s28, 0, 0x10000
	v_add_u32_e32 v154, s28, v144
	ds_read_b128 v[138:141], v154
	ds_read_b128 v[146:149], v154 offset:1024
	ds_read_b128 v[150:153], v154 offset:2048
	ds_read_b128 v[154:157], v154 offset:3072
	s_cmp_eq_u32 s72, 28
	s_cselect_b32 s9, s10, s7
	s_cselect_b32 s8, s11, s6
	s_cselect_b32 s7, s63, s71
	s_cselect_b32 s6, s65, s70
	v_lshl_add_u64 v[174:175], s[4:5], 0, v[134:135]
	s_add_i32 m0, s17, 0xc000
	ds_read_b128 v[158:161], v145
	ds_read_b128 v[166:169], v145 offset:2048
	ds_read_b128 v[188:191], v145 offset:4096
	ds_read_b128 v[196:199], v145 offset:6144
	ds_read_b128 v[162:165], v145 offset:1024
	ds_read_b128 v[170:173], v145 offset:3072
	ds_read_b128 v[192:195], v145 offset:5120
	ds_read_b128 v[200:203], v145 offset:7168
	global_load_lds_dwordx4 v[174:175], off
	v_lshl_add_u64 v[174:175], s[4:5], 0, v[136:137]
	s_add_i32 m0, s17, 0xe000
	s_nop 0
	global_load_lds_dwordx4 v[174:175], off
	s_waitcnt lgkmcnt(8)
	s_barrier
	s_waitcnt lgkmcnt(7)
	v_mfma_f32_16x16x32_bf16 v[124:127], v[138:141], v[158:161], v[124:127]
	v_mfma_f32_16x16x32_bf16 v[120:123], v[150:153], v[158:161], v[120:123]
	s_waitcnt lgkmcnt(6)
	v_mfma_f32_16x16x32_bf16 v[116:119], v[138:141], v[166:169], v[116:119]
	v_mfma_f32_16x16x32_bf16 v[108:111], v[150:153], v[166:169], v[108:111]
	s_waitcnt lgkmcnt(5)
	v_mfma_f32_16x16x32_bf16 v[100:103], v[138:141], v[188:191], v[100:103]
	v_mfma_f32_16x16x32_bf16 v[92:95], v[150:153], v[188:191], v[92:95]
	s_waitcnt lgkmcnt(4)
	v_mfma_f32_16x16x32_bf16 v[84:87], v[138:141], v[196:199], v[84:87]
	v_mfma_f32_16x16x32_bf16 v[76:79], v[150:153], v[196:199], v[76:79]
	s_waitcnt lgkmcnt(3)
	v_mfma_f32_16x16x32_bf16 v[124:127], v[146:149], v[162:165], v[124:127]
	v_mfma_f32_16x16x32_bf16 v[120:123], v[154:157], v[162:165], v[120:123]
	s_waitcnt lgkmcnt(2)
	v_mfma_f32_16x16x32_bf16 v[116:119], v[146:149], v[170:173], v[116:119]
	v_mfma_f32_16x16x32_bf16 v[108:111], v[154:157], v[170:173], v[108:111]
	s_waitcnt lgkmcnt(1)
	v_mfma_f32_16x16x32_bf16 v[100:103], v[146:149], v[192:195], v[100:103]
	v_mfma_f32_16x16x32_bf16 v[92:95], v[154:157], v[192:195], v[92:95]
	s_waitcnt lgkmcnt(0)
	v_mfma_f32_16x16x32_bf16 v[84:87], v[146:149], v[200:203], v[84:87]
	v_mfma_f32_16x16x32_bf16 v[76:79], v[154:157], v[200:203], v[76:79]
	s_barrier
	s_add_i32 s29, 0, 0x14000
	v_add_u32_e32 v174, s29, v144
	s_add_i32 s28, s28, s77
	ds_read_b128 v[204:207], v174
	ds_read_b128 v[208:211], v174 offset:1024
	ds_read_b128 v[212:215], v174 offset:2048
	ds_read_b128 v[232:235], v174 offset:3072
	v_lshl_add_u64 v[174:175], s[6:7], 0, v[176:177]
	s_mov_b32 m0, s28
	v_lshl_add_u64 v[216:217], s[6:7], 0, v[132:133]
	global_load_lds_dwordx4 v[174:175], off
	s_add_i32 m0, s28, 0x2000
	s_nop 0
	global_load_lds_dwordx4 v[216:217], off
	s_barrier
	s_waitcnt lgkmcnt(3)
	v_mfma_f32_16x16x32_bf16 v[112:115], v[204:207], v[158:161], v[112:115]
	s_waitcnt lgkmcnt(1)
	v_mfma_f32_16x16x32_bf16 v[104:107], v[212:215], v[158:161], v[104:107]
	v_mfma_f32_16x16x32_bf16 v[96:99], v[204:207], v[166:169], v[96:99]
	v_mfma_f32_16x16x32_bf16 v[88:91], v[212:215], v[166:169], v[88:91]
	v_mfma_f32_16x16x32_bf16 v[80:83], v[204:207], v[188:191], v[80:83]
	v_mfma_f32_16x16x32_bf16 v[72:75], v[212:215], v[188:191], v[72:75]
	v_mfma_f32_16x16x32_bf16 v[68:71], v[204:207], v[196:199], v[68:71]
	v_mfma_f32_16x16x32_bf16 v[64:67], v[212:215], v[196:199], v[64:67]
	v_mfma_f32_16x16x32_bf16 v[112:115], v[208:211], v[162:165], v[112:115]
	s_waitcnt lgkmcnt(0)
	v_mfma_f32_16x16x32_bf16 v[104:107], v[232:235], v[162:165], v[104:107]
	v_mfma_f32_16x16x32_bf16 v[96:99], v[208:211], v[170:173], v[96:99]
	v_mfma_f32_16x16x32_bf16 v[88:91], v[232:235], v[170:173], v[88:91]
	v_mfma_f32_16x16x32_bf16 v[80:83], v[208:211], v[192:195], v[80:83]
	v_mfma_f32_16x16x32_bf16 v[72:75], v[232:235], v[192:195], v[72:75]
	v_mfma_f32_16x16x32_bf16 v[68:71], v[208:211], v[200:203], v[68:71]
	v_mfma_f32_16x16x32_bf16 v[64:67], v[232:235], v[200:203], v[64:67]
	s_mov_b32 m0, s17
	v_lshl_add_u64 v[236:237], s[8:9], 0, v[128:129]
	s_barrier
	ds_read_b128 v[158:161], v145 offset:16384
	ds_read_b128 v[166:169], v145 offset:18432
	ds_read_b128 v[188:191], v145 offset:20480
	ds_read_b128 v[196:199], v145 offset:22528
	ds_read_b128 v[162:165], v145 offset:17408
	ds_read_b128 v[170:173], v145 offset:19456
	ds_read_b128 v[192:195], v145 offset:21504
	ds_read_b128 v[200:203], v145 offset:23552
	global_load_lds_dwordx4 v[236:237], off
	v_lshl_add_u64 v[238:239], s[8:9], 0, v[130:131]
	s_mov_b32 m0, s19
	s_nop 0
	global_load_lds_dwordx4 v[238:239], off
	s_barrier
	s_waitcnt lgkmcnt(7)
	v_mfma_f32_16x16x32_bf16 v[60:63], v[138:141], v[158:161], v[60:63]
	v_mfma_f32_16x16x32_bf16 v[56:59], v[150:153], v[158:161], v[56:59]
	s_waitcnt lgkmcnt(6)
	v_mfma_f32_16x16x32_bf16 v[52:55], v[138:141], v[166:169], v[52:55]
	v_mfma_f32_16x16x32_bf16 v[44:47], v[150:153], v[166:169], v[44:47]
	s_waitcnt lgkmcnt(5)
	v_mfma_f32_16x16x32_bf16 v[36:39], v[138:141], v[188:191], v[36:39]
	v_mfma_f32_16x16x32_bf16 v[28:31], v[150:153], v[188:191], v[28:31]
	s_waitcnt lgkmcnt(4)
	v_mfma_f32_16x16x32_bf16 v[20:23], v[138:141], v[196:199], v[20:23]
	v_mfma_f32_16x16x32_bf16 v[12:15], v[150:153], v[196:199], v[12:15]
	s_waitcnt lgkmcnt(3)
	v_mfma_f32_16x16x32_bf16 v[60:63], v[146:149], v[162:165], v[60:63]
	v_mfma_f32_16x16x32_bf16 v[56:59], v[154:157], v[162:165], v[56:59]
	s_waitcnt lgkmcnt(2)
	v_mfma_f32_16x16x32_bf16 v[52:55], v[146:149], v[170:173], v[52:55]
	v_mfma_f32_16x16x32_bf16 v[44:47], v[154:157], v[170:173], v[44:47]
	s_waitcnt lgkmcnt(1)
	v_mfma_f32_16x16x32_bf16 v[36:39], v[146:149], v[192:195], v[36:39]
	v_mfma_f32_16x16x32_bf16 v[28:31], v[154:157], v[192:195], v[28:31]
	s_waitcnt lgkmcnt(0)
	v_mfma_f32_16x16x32_bf16 v[20:23], v[146:149], v[200:203], v[20:23]
	v_mfma_f32_16x16x32_bf16 v[12:15], v[154:157], v[200:203], v[12:15]
	s_barrier
	s_add_u32 vcc_lo, s6, 0x80000
	s_addc_u32 vcc_hi, s7, 0
	s_add_i32 s28, s29, s77
	v_lshl_add_u64 v[138:139], vcc, 0, v[176:177]
	s_mov_b32 m0, s28
	s_nop 0
	global_load_lds_dwordx4 v[138:139], off
	v_lshl_add_u64 v[138:139], vcc, 0, v[132:133]
	s_add_i32 m0, s28, 0x2000
	s_nop 0
	global_load_lds_dwordx4 v[138:139], off
	s_waitcnt vmcnt(6)
	s_barrier
	v_mfma_f32_16x16x32_bf16 v[48:51], v[204:207], v[158:161], v[48:51]
	v_mfma_f32_16x16x32_bf16 v[40:43], v[212:215], v[158:161], v[40:43]
	v_mfma_f32_16x16x32_bf16 v[32:35], v[204:207], v[166:169], v[32:35]
	v_mfma_f32_16x16x32_bf16 v[24:27], v[212:215], v[166:169], v[24:27]
	v_mfma_f32_16x16x32_bf16 v[16:19], v[204:207], v[188:191], v[16:19]
	v_mfma_f32_16x16x32_bf16 v[8:11], v[212:215], v[188:191], v[8:11]
	v_mfma_f32_16x16x32_bf16 v[4:7], v[204:207], v[196:199], v[4:7]
	v_mfma_f32_16x16x32_bf16 v[0:3], v[212:215], v[196:199], v[0:3]
	v_mfma_f32_16x16x32_bf16 v[48:51], v[208:211], v[162:165], v[48:51]
	v_mfma_f32_16x16x32_bf16 v[40:43], v[232:235], v[162:165], v[40:43]
	v_mfma_f32_16x16x32_bf16 v[32:35], v[208:211], v[170:173], v[32:35]
	v_mfma_f32_16x16x32_bf16 v[24:27], v[232:235], v[170:173], v[24:27]
	v_mfma_f32_16x16x32_bf16 v[16:19], v[208:211], v[192:195], v[16:19]
	v_mfma_f32_16x16x32_bf16 v[8:11], v[232:235], v[192:195], v[8:11]
	v_mfma_f32_16x16x32_bf16 v[4:7], v[208:211], v[200:203], v[4:7]
	v_mfma_f32_16x16x32_bf16 v[0:3], v[232:235], v[200:203], v[0:3]
	s_add_i32 s28, 0, 0x18000
	v_add_u32_e32 v154, s28, v144
	s_barrier
	ds_read_b128 v[138:141], v154
	ds_read_b128 v[146:149], v154 offset:1024
	ds_read_b128 v[150:153], v154 offset:2048
	ds_read_b128 v[154:157], v154 offset:3072
	s_add_u32 s8, s8, 0x80000
	s_addc_u32 s9, s9, 0
	s_mov_b32 m0, s78
	v_lshl_add_u64 v[204:205], s[8:9], 0, v[128:129]
	ds_read_b128 v[158:161], v145 offset:32768
	ds_read_b128 v[166:169], v145 offset:34816
	ds_read_b128 v[188:191], v145 offset:36864
	ds_read_b128 v[196:199], v145 offset:38912
	ds_read_b128 v[162:165], v145 offset:33792
	ds_read_b128 v[170:173], v145 offset:35840
	ds_read_b128 v[192:195], v145 offset:37888
	ds_read_b128 v[200:203], v145 offset:39936
	global_load_lds_dwordx4 v[204:205], off
	v_lshl_add_u64 v[204:205], s[8:9], 0, v[130:131]
	s_mov_b32 m0, s79
	s_nop 0
	global_load_lds_dwordx4 v[204:205], off
	s_waitcnt lgkmcnt(8)
	s_barrier
	s_waitcnt lgkmcnt(7)
	v_mfma_f32_16x16x32_bf16 v[124:127], v[138:141], v[158:161], v[124:127]
	v_mfma_f32_16x16x32_bf16 v[120:123], v[150:153], v[158:161], v[120:123]
	s_waitcnt lgkmcnt(6)
	v_mfma_f32_16x16x32_bf16 v[116:119], v[138:141], v[166:169], v[116:119]
	v_mfma_f32_16x16x32_bf16 v[108:111], v[150:153], v[166:169], v[108:111]
	s_waitcnt lgkmcnt(5)
	v_mfma_f32_16x16x32_bf16 v[100:103], v[138:141], v[188:191], v[100:103]
	v_mfma_f32_16x16x32_bf16 v[92:95], v[150:153], v[188:191], v[92:95]
	s_waitcnt lgkmcnt(4)
	v_mfma_f32_16x16x32_bf16 v[84:87], v[138:141], v[196:199], v[84:87]
	v_mfma_f32_16x16x32_bf16 v[76:79], v[150:153], v[196:199], v[76:79]
	s_waitcnt lgkmcnt(3)
	v_mfma_f32_16x16x32_bf16 v[124:127], v[146:149], v[162:165], v[124:127]
	v_mfma_f32_16x16x32_bf16 v[120:123], v[154:157], v[162:165], v[120:123]
	s_waitcnt lgkmcnt(2)
	v_mfma_f32_16x16x32_bf16 v[116:119], v[146:149], v[170:173], v[116:119]
	v_mfma_f32_16x16x32_bf16 v[108:111], v[154:157], v[170:173], v[108:111]
	s_waitcnt lgkmcnt(1)
	v_mfma_f32_16x16x32_bf16 v[100:103], v[146:149], v[192:195], v[100:103]
	v_mfma_f32_16x16x32_bf16 v[92:95], v[154:157], v[192:195], v[92:95]
	s_waitcnt lgkmcnt(0)
	v_mfma_f32_16x16x32_bf16 v[84:87], v[146:149], v[200:203], v[84:87]
	v_mfma_f32_16x16x32_bf16 v[76:79], v[154:157], v[200:203], v[76:79]
	s_barrier
	s_add_i32 s8, 0, 0x1c000
	s_add_i32 s9, s28, s77
	v_add_u32_e32 v232, s8, v144
	v_lshl_add_u64 v[174:175], v[174:175], 0, s[40:41]
	s_mov_b32 m0, s9
	ds_read_b128 v[204:207], v232
	ds_read_b128 v[208:211], v232 offset:1024
	ds_read_b128 v[212:215], v232 offset:2048
	ds_read_b128 v[232:235], v232 offset:3072
	global_load_lds_dwordx4 v[174:175], off
	v_lshl_add_u64 v[174:175], v[216:217], 0, s[40:41]
	s_add_i32 m0, s9, 0x2000
	s_nop 0
	global_load_lds_dwordx4 v[174:175], off
	s_barrier
	s_waitcnt lgkmcnt(3)
	v_mfma_f32_16x16x32_bf16 v[112:115], v[204:207], v[158:161], v[112:115]
	s_waitcnt lgkmcnt(1)
	v_mfma_f32_16x16x32_bf16 v[104:107], v[212:215], v[158:161], v[104:107]
	v_mfma_f32_16x16x32_bf16 v[96:99], v[204:207], v[166:169], v[96:99]
	v_mfma_f32_16x16x32_bf16 v[88:91], v[212:215], v[166:169], v[88:91]
	v_mfma_f32_16x16x32_bf16 v[80:83], v[204:207], v[188:191], v[80:83]
	v_mfma_f32_16x16x32_bf16 v[72:75], v[212:215], v[188:191], v[72:75]
	v_mfma_f32_16x16x32_bf16 v[68:71], v[204:207], v[196:199], v[68:71]
	v_mfma_f32_16x16x32_bf16 v[64:67], v[212:215], v[196:199], v[64:67]
	v_mfma_f32_16x16x32_bf16 v[112:115], v[208:211], v[162:165], v[112:115]
	s_waitcnt lgkmcnt(0)
	v_mfma_f32_16x16x32_bf16 v[104:107], v[232:235], v[162:165], v[104:107]
	v_mfma_f32_16x16x32_bf16 v[96:99], v[208:211], v[170:173], v[96:99]
	v_mfma_f32_16x16x32_bf16 v[88:91], v[232:235], v[170:173], v[88:91]
	v_mfma_f32_16x16x32_bf16 v[80:83], v[208:211], v[192:195], v[80:83]
	v_mfma_f32_16x16x32_bf16 v[72:75], v[232:235], v[192:195], v[72:75]
	v_mfma_f32_16x16x32_bf16 v[68:71], v[208:211], v[200:203], v[68:71]
	v_mfma_f32_16x16x32_bf16 v[64:67], v[232:235], v[200:203], v[64:67]
	s_mov_b32 m0, s82
	v_lshl_add_u64 v[174:175], v[236:237], 0, s[40:41]
	s_barrier
	ds_read_b128 v[158:161], v145 offset:49152
	ds_read_b128 v[166:169], v145 offset:51200
	ds_read_b128 v[188:191], v145 offset:53248
	ds_read_b128 v[196:199], v145 offset:55296
	ds_read_b128 v[162:165], v145 offset:50176
	ds_read_b128 v[170:173], v145 offset:52224
	ds_read_b128 v[192:195], v145 offset:54272
	ds_read_b128 v[200:203], v145 offset:56320
	global_load_lds_dwordx4 v[174:175], off
	v_lshl_add_u64 v[174:175], v[238:239], 0, s[40:41]
	s_mov_b32 m0, s83
	s_nop 0
	global_load_lds_dwordx4 v[174:175], off
	s_barrier
	s_waitcnt lgkmcnt(7)
	v_mfma_f32_16x16x32_bf16 v[60:63], v[138:141], v[158:161], v[60:63]
	v_mfma_f32_16x16x32_bf16 v[56:59], v[150:153], v[158:161], v[56:59]
	s_waitcnt lgkmcnt(6)
	v_mfma_f32_16x16x32_bf16 v[52:55], v[138:141], v[166:169], v[52:55]
	v_mfma_f32_16x16x32_bf16 v[44:47], v[150:153], v[166:169], v[44:47]
	s_waitcnt lgkmcnt(5)
	v_mfma_f32_16x16x32_bf16 v[36:39], v[138:141], v[188:191], v[36:39]
	v_mfma_f32_16x16x32_bf16 v[28:31], v[150:153], v[188:191], v[28:31]
	s_waitcnt lgkmcnt(4)
	v_mfma_f32_16x16x32_bf16 v[20:23], v[138:141], v[196:199], v[20:23]
	v_mfma_f32_16x16x32_bf16 v[12:15], v[150:153], v[196:199], v[12:15]
	s_waitcnt lgkmcnt(3)
	v_mfma_f32_16x16x32_bf16 v[60:63], v[146:149], v[162:165], v[60:63]
	v_mfma_f32_16x16x32_bf16 v[56:59], v[154:157], v[162:165], v[56:59]
	s_waitcnt lgkmcnt(2)
	v_mfma_f32_16x16x32_bf16 v[52:55], v[146:149], v[170:173], v[52:55]
	v_mfma_f32_16x16x32_bf16 v[44:47], v[154:157], v[170:173], v[44:47]
	s_waitcnt lgkmcnt(1)
	v_mfma_f32_16x16x32_bf16 v[36:39], v[146:149], v[192:195], v[36:39]
	v_mfma_f32_16x16x32_bf16 v[28:31], v[154:157], v[192:195], v[28:31]
	s_waitcnt lgkmcnt(0)
	v_mfma_f32_16x16x32_bf16 v[20:23], v[146:149], v[200:203], v[20:23]
	v_mfma_f32_16x16x32_bf16 v[12:15], v[154:157], v[200:203], v[12:15]
	s_barrier
	s_add_u32 s6, s6, 0x80080
	s_addc_u32 s7, s7, 0
	s_add_i32 s8, s8, s77
	v_lshl_add_u64 v[138:139], s[6:7], 0, v[176:177]
	s_mov_b32 m0, s8
	s_nop 0
	global_load_lds_dwordx4 v[138:139], off
	v_lshl_add_u64 v[138:139], s[6:7], 0, v[132:133]
	s_add_i32 m0, s8, 0x2000
	s_nop 0
	global_load_lds_dwordx4 v[138:139], off
	s_waitcnt vmcnt(6)
	s_barrier
	v_mfma_f32_16x16x32_bf16 v[48:51], v[204:207], v[158:161], v[48:51]
	v_mfma_f32_16x16x32_bf16 v[40:43], v[212:215], v[158:161], v[40:43]
	v_mfma_f32_16x16x32_bf16 v[32:35], v[204:207], v[166:169], v[32:35]
	v_mfma_f32_16x16x32_bf16 v[24:27], v[212:215], v[166:169], v[24:27]
	v_mfma_f32_16x16x32_bf16 v[16:19], v[204:207], v[188:191], v[16:19]
	v_mfma_f32_16x16x32_bf16 v[8:11], v[212:215], v[188:191], v[8:11]
	v_mfma_f32_16x16x32_bf16 v[4:7], v[204:207], v[196:199], v[4:7]
	v_mfma_f32_16x16x32_bf16 v[0:3], v[212:215], v[196:199], v[0:3]
	v_mfma_f32_16x16x32_bf16 v[48:51], v[208:211], v[162:165], v[48:51]
	v_mfma_f32_16x16x32_bf16 v[40:43], v[232:235], v[162:165], v[40:43]
	v_mfma_f32_16x16x32_bf16 v[32:35], v[208:211], v[170:173], v[32:35]
	v_mfma_f32_16x16x32_bf16 v[24:27], v[232:235], v[170:173], v[24:27]
	v_mfma_f32_16x16x32_bf16 v[16:19], v[208:211], v[192:195], v[16:19]
	v_mfma_f32_16x16x32_bf16 v[8:11], v[232:235], v[192:195], v[8:11]
	v_mfma_f32_16x16x32_bf16 v[4:7], v[208:211], v[200:203], v[4:7]
	v_mfma_f32_16x16x32_bf16 v[0:3], v[232:235], v[200:203], v[0:3]
	s_add_i32 s72, s72, 2
	s_add_u32 s4, s4, 0x100
	s_addc_u32 s5, s5, 0
	s_add_u32 s70, s70, 0x100
	s_addc_u32 s71, s71, 0
	s_cmp_lt_u32 s72, 30
	s_barrier
	s_cbranch_scc1 .LBB0_505
	v_mov_b32_e32 v147, v142
	v_mov_b32_e32 v146, v143
	s_cmp_lt_i32 s16, 12
	s_mov_b64 s[4:5], -1
	s_cbranch_scc1 .LBB0_1052
	s_lshl_b32 s4, s18, 8
	s_add_i32 s4, s4, s80
	v_add_u32_e32 v149, s4, v147
	s_lshl_b32 s4, s16, 8
	s_add_i32 s4, s84, s4
	v_lshl_add_u32 v138, v146, 3, s4
	v_mad_i64_i32 v[140:141], s[4:5], v149, s97, 0
	v_cmp_gt_i32_e32 vcc, s34, v138
	s_and_saveexec_b64 s[10:11], vcc
	s_cbranch_execz .LBB0_541
	v_cmp_lt_i32_e64 s[8:9], 63, v138
	v_cmp_gt_u32_e64 s[4:5], s93, v138
	v_cmp_gt_u32_e64 s[6:7], s96, v138
	s_and_saveexec_b64 s[70:71], s[8:9]
	s_xor_b64 s[70:71], exec, s[70:71]
	s_cbranch_execz .LBB0_510
	v_mul_f32_e32 v139, 0xbfb8aa3b, v124
	v_exp_f32_e32 v139, v139
	s_nop 0
	v_add_f32_e32 v139, 1.0, v139
	v_rcp_f32_e32 v139, v139
	s_nop 0
	v_cndmask_b32_e64 v139, 0, v139, s[6:7]
	v_cndmask_b32_e64 v139, v139, v124, s[4:5]
	s_andn2_saveexec_b64 s[70:71], s[70:71]
	s_cbranch_execz .LBB0_512
	s_branch .LBB0_511

.LBB0_1114:
	s_add_i32 vcc_hi, s66, 2
	s_add_u32 s28, s64, 0x80
	s_addc_u32 s29, s65, 0
	s_add_i32 s88, 0, 0x10000
	v_add_u32_e32 v140, s88, v194
	ds_read_b128 v[128:131], v140
	ds_read_b128 v[132:135], v140 offset:1024
	ds_read_b128 v[136:139], v140 offset:2048
	ds_read_b128 v[140:143], v140 offset:3072
	s_cmp_eq_u32 s85, s66
	s_cselect_b32 s66, s4, s28
	s_cselect_b32 s67, s5, s29
	s_cselect_b32 s69, s7, vcc_lo
	s_cselect_b32 s68, s6, s91
	v_lshl_add_u64 v[174:175], s[64:65], 0, v[158:159]
	s_add_i32 m0, s70, 0xc000
	ds_read_b128 v[144:147], v195
	ds_read_b128 v[162:165], v195 offset:2048
	ds_read_b128 v[170:173], v195 offset:4096
	ds_read_b128 v[196:199], v195 offset:6144
	ds_read_b128 v[148:151], v195 offset:1024
	ds_read_b128 v[166:169], v195 offset:3072
	ds_read_b128 v[188:191], v195 offset:5120
	ds_read_b128 v[200:203], v195 offset:7168
	global_load_lds_dwordx4 v[174:175], off
	v_lshl_add_u64 v[174:175], s[64:65], 0, v[160:161]
	s_add_i32 m0, s70, 0xe000
	s_nop 0
	global_load_lds_dwordx4 v[174:175], off
	s_waitcnt lgkmcnt(8)
	s_barrier
	s_waitcnt lgkmcnt(7)
	v_mfma_f32_16x16x32_bf16 v[124:127], v[128:131], v[144:147], v[124:127]
	v_mfma_f32_16x16x32_bf16 v[120:123], v[136:139], v[144:147], v[120:123]
	s_waitcnt lgkmcnt(6)
	v_mfma_f32_16x16x32_bf16 v[108:111], v[128:131], v[162:165], v[108:111]
	v_mfma_f32_16x16x32_bf16 v[104:107], v[136:139], v[162:165], v[104:107]
	s_waitcnt lgkmcnt(5)
	v_mfma_f32_16x16x32_bf16 v[92:95], v[128:131], v[170:173], v[92:95]
	v_mfma_f32_16x16x32_bf16 v[88:91], v[136:139], v[170:173], v[88:91]
	s_waitcnt lgkmcnt(4)
	v_mfma_f32_16x16x32_bf16 v[76:79], v[128:131], v[196:199], v[76:79]
	v_mfma_f32_16x16x32_bf16 v[72:75], v[136:139], v[196:199], v[72:75]
	s_waitcnt lgkmcnt(3)
	v_mfma_f32_16x16x32_bf16 v[124:127], v[132:135], v[148:151], v[124:127]
	v_mfma_f32_16x16x32_bf16 v[120:123], v[140:143], v[148:151], v[120:123]
	s_waitcnt lgkmcnt(2)
	v_mfma_f32_16x16x32_bf16 v[108:111], v[132:135], v[166:169], v[108:111]
	v_mfma_f32_16x16x32_bf16 v[104:107], v[140:143], v[166:169], v[104:107]
	s_waitcnt lgkmcnt(1)
	v_mfma_f32_16x16x32_bf16 v[92:95], v[132:135], v[188:191], v[92:95]
	v_mfma_f32_16x16x32_bf16 v[88:91], v[140:143], v[188:191], v[88:91]
	s_waitcnt lgkmcnt(0)
	v_mfma_f32_16x16x32_bf16 v[76:79], v[132:135], v[200:203], v[76:79]
	v_mfma_f32_16x16x32_bf16 v[72:75], v[140:143], v[200:203], v[72:75]
	s_barrier
	s_add_i32 s28, 0, 0x14000
	v_add_u32_e32 v174, s28, v194
	s_add_i32 s29, s88, s47
	ds_read_b128 v[204:207], v174
	ds_read_b128 v[208:211], v174 offset:1024
	ds_read_b128 v[212:215], v174 offset:2048
	ds_read_b128 v[232:235], v174 offset:3072
	v_lshl_add_u64 v[174:175], s[68:69], 0, v[176:177]
	s_mov_b32 m0, s29
	v_lshl_add_u64 v[216:217], s[68:69], 0, v[156:157]
	global_load_lds_dwordx4 v[174:175], off
	s_add_i32 m0, s29, 0x2000
	s_nop 0
	global_load_lds_dwordx4 v[216:217], off
	s_barrier
	s_waitcnt lgkmcnt(3)
	v_mfma_f32_16x16x32_bf16 v[116:119], v[204:207], v[144:147], v[116:119]
	s_waitcnt lgkmcnt(1)
	v_mfma_f32_16x16x32_bf16 v[112:115], v[212:215], v[144:147], v[112:115]
	v_mfma_f32_16x16x32_bf16 v[100:103], v[204:207], v[162:165], v[100:103]
	v_mfma_f32_16x16x32_bf16 v[96:99], v[212:215], v[162:165], v[96:99]
	v_mfma_f32_16x16x32_bf16 v[84:87], v[204:207], v[170:173], v[84:87]
	v_mfma_f32_16x16x32_bf16 v[80:83], v[212:215], v[170:173], v[80:83]
	v_mfma_f32_16x16x32_bf16 v[68:71], v[204:207], v[196:199], v[68:71]
	v_mfma_f32_16x16x32_bf16 v[64:67], v[212:215], v[196:199], v[64:67]
	v_mfma_f32_16x16x32_bf16 v[116:119], v[208:211], v[148:151], v[116:119]
	s_waitcnt lgkmcnt(0)
	v_mfma_f32_16x16x32_bf16 v[112:115], v[232:235], v[148:151], v[112:115]
	v_mfma_f32_16x16x32_bf16 v[100:103], v[208:211], v[166:169], v[100:103]
	v_mfma_f32_16x16x32_bf16 v[96:99], v[232:235], v[166:169], v[96:99]
	v_mfma_f32_16x16x32_bf16 v[84:87], v[208:211], v[188:191], v[84:87]
	v_mfma_f32_16x16x32_bf16 v[80:83], v[232:235], v[188:191], v[80:83]
	v_mfma_f32_16x16x32_bf16 v[68:71], v[208:211], v[200:203], v[68:71]
	v_mfma_f32_16x16x32_bf16 v[64:67], v[232:235], v[200:203], v[64:67]
	s_mov_b32 m0, s70
	v_lshl_add_u64 v[236:237], s[66:67], 0, v[152:153]
	s_barrier
	ds_read_b128 v[144:147], v195 offset:16384
	ds_read_b128 v[162:165], v195 offset:18432
	ds_read_b128 v[170:173], v195 offset:20480
	ds_read_b128 v[196:199], v195 offset:22528
	ds_read_b128 v[148:151], v195 offset:17408
	ds_read_b128 v[166:169], v195 offset:19456
	ds_read_b128 v[188:191], v195 offset:21504
	ds_read_b128 v[200:203], v195 offset:23552
	global_load_lds_dwordx4 v[236:237], off
	v_lshl_add_u64 v[238:239], s[66:67], 0, v[154:155]
	s_mov_b32 m0, s71
	s_nop 0
	global_load_lds_dwordx4 v[238:239], off
	s_barrier
	s_waitcnt lgkmcnt(7)
	v_mfma_f32_16x16x32_bf16 v[60:63], v[128:131], v[144:147], v[60:63]
	v_mfma_f32_16x16x32_bf16 v[56:59], v[136:139], v[144:147], v[56:59]
	s_waitcnt lgkmcnt(6)
	v_mfma_f32_16x16x32_bf16 v[44:47], v[128:131], v[162:165], v[44:47]
	v_mfma_f32_16x16x32_bf16 v[40:43], v[136:139], v[162:165], v[40:43]
	s_waitcnt lgkmcnt(5)
	v_mfma_f32_16x16x32_bf16 v[28:31], v[128:131], v[170:173], v[28:31]
	v_mfma_f32_16x16x32_bf16 v[24:27], v[136:139], v[170:173], v[24:27]
	s_waitcnt lgkmcnt(4)
	v_mfma_f32_16x16x32_bf16 v[12:15], v[128:131], v[196:199], v[12:15]
	v_mfma_f32_16x16x32_bf16 v[8:11], v[136:139], v[196:199], v[8:11]
	s_waitcnt lgkmcnt(3)
	v_mfma_f32_16x16x32_bf16 v[60:63], v[132:135], v[148:151], v[60:63]
	v_mfma_f32_16x16x32_bf16 v[56:59], v[140:143], v[148:151], v[56:59]
	s_waitcnt lgkmcnt(2)
	v_mfma_f32_16x16x32_bf16 v[44:47], v[132:135], v[166:169], v[44:47]
	v_mfma_f32_16x16x32_bf16 v[40:43], v[140:143], v[166:169], v[40:43]
	s_waitcnt lgkmcnt(1)
	v_mfma_f32_16x16x32_bf16 v[28:31], v[132:135], v[188:191], v[28:31]
	v_mfma_f32_16x16x32_bf16 v[24:27], v[140:143], v[188:191], v[24:27]
	s_waitcnt lgkmcnt(0)
	v_mfma_f32_16x16x32_bf16 v[12:15], v[132:135], v[200:203], v[12:15]
	v_mfma_f32_16x16x32_bf16 v[8:11], v[140:143], v[200:203], v[8:11]
	s_barrier
	s_add_u32 s68, s68, s58
	s_addc_u32 s69, s69, 0
	s_add_i32 s28, s28, s47
	v_lshl_add_u64 v[240:241], s[68:69], 0, v[176:177]
	s_mov_b32 m0, s28
	v_lshl_add_u64 v[242:243], s[68:69], 0, v[156:157]
	global_load_lds_dwordx4 v[240:241], off
	s_add_i32 m0, s28, 0x2000
	s_nop 0
	global_load_lds_dwordx4 v[242:243], off
	s_waitcnt vmcnt(6)
	s_barrier
	v_mfma_f32_16x16x32_bf16 v[52:55], v[204:207], v[144:147], v[52:55]
	v_mfma_f32_16x16x32_bf16 v[48:51], v[212:215], v[144:147], v[48:51]
	v_mfma_f32_16x16x32_bf16 v[36:39], v[204:207], v[162:165], v[36:39]
	v_mfma_f32_16x16x32_bf16 v[32:35], v[212:215], v[162:165], v[32:35]
	v_mfma_f32_16x16x32_bf16 v[20:23], v[204:207], v[170:173], v[20:23]
	v_mfma_f32_16x16x32_bf16 v[16:19], v[212:215], v[170:173], v[16:19]
	v_mfma_f32_16x16x32_bf16 v[4:7], v[204:207], v[196:199], v[4:7]
	v_mfma_f32_16x16x32_bf16 v[0:3], v[212:215], v[196:199], v[0:3]
	v_mfma_f32_16x16x32_bf16 v[52:55], v[208:211], v[148:151], v[52:55]
	v_mfma_f32_16x16x32_bf16 v[48:51], v[232:235], v[148:151], v[48:51]
	v_mfma_f32_16x16x32_bf16 v[36:39], v[208:211], v[166:169], v[36:39]
	v_mfma_f32_16x16x32_bf16 v[32:35], v[232:235], v[166:169], v[32:35]
	v_mfma_f32_16x16x32_bf16 v[20:23], v[208:211], v[188:191], v[20:23]
	v_mfma_f32_16x16x32_bf16 v[16:19], v[232:235], v[188:191], v[16:19]
	v_mfma_f32_16x16x32_bf16 v[4:7], v[208:211], v[200:203], v[4:7]
	v_mfma_f32_16x16x32_bf16 v[0:3], v[232:235], v[200:203], v[0:3]
	s_add_i32 s28, 0, 0x18000
	v_add_u32_e32 v140, s28, v194
	s_barrier
	ds_read_b128 v[128:131], v140
	ds_read_b128 v[132:135], v140 offset:1024
	ds_read_b128 v[136:139], v140 offset:2048
	ds_read_b128 v[140:143], v140 offset:3072
	s_add_u32 s66, s66, s58
	s_addc_u32 s67, s67, 0
	s_mov_b32 m0, s72
	v_lshl_add_u64 v[204:205], s[66:67], 0, v[152:153]
	ds_read_b128 v[144:147], v195 offset:32768
	ds_read_b128 v[162:165], v195 offset:34816
	ds_read_b128 v[170:173], v195 offset:36864
	ds_read_b128 v[196:199], v195 offset:38912
	ds_read_b128 v[148:151], v195 offset:33792
	ds_read_b128 v[166:169], v195 offset:35840
	ds_read_b128 v[188:191], v195 offset:37888
	ds_read_b128 v[200:203], v195 offset:39936
	global_load_lds_dwordx4 v[204:205], off
	v_lshl_add_u64 v[204:205], s[66:67], 0, v[154:155]
	s_mov_b32 m0, s73
	s_nop 0
	global_load_lds_dwordx4 v[204:205], off
	s_waitcnt lgkmcnt(8)
	s_barrier
	s_waitcnt lgkmcnt(7)
	v_mfma_f32_16x16x32_bf16 v[124:127], v[128:131], v[144:147], v[124:127]
	v_mfma_f32_16x16x32_bf16 v[120:123], v[136:139], v[144:147], v[120:123]
	s_waitcnt lgkmcnt(6)
	v_mfma_f32_16x16x32_bf16 v[108:111], v[128:131], v[162:165], v[108:111]
	v_mfma_f32_16x16x32_bf16 v[104:107], v[136:139], v[162:165], v[104:107]
	s_waitcnt lgkmcnt(5)
	v_mfma_f32_16x16x32_bf16 v[92:95], v[128:131], v[170:173], v[92:95]
	v_mfma_f32_16x16x32_bf16 v[88:91], v[136:139], v[170:173], v[88:91]
	s_waitcnt lgkmcnt(4)
	v_mfma_f32_16x16x32_bf16 v[76:79], v[128:131], v[196:199], v[76:79]
	v_mfma_f32_16x16x32_bf16 v[72:75], v[136:139], v[196:199], v[72:75]
	s_waitcnt lgkmcnt(3)
	v_mfma_f32_16x16x32_bf16 v[124:127], v[132:135], v[148:151], v[124:127]
	v_mfma_f32_16x16x32_bf16 v[120:123], v[140:143], v[148:151], v[120:123]
	s_waitcnt lgkmcnt(2)
	v_mfma_f32_16x16x32_bf16 v[108:111], v[132:135], v[166:169], v[108:111]
	v_mfma_f32_16x16x32_bf16 v[104:107], v[140:143], v[166:169], v[104:107]
	s_waitcnt lgkmcnt(1)
	v_mfma_f32_16x16x32_bf16 v[92:95], v[132:135], v[188:191], v[92:95]
	v_mfma_f32_16x16x32_bf16 v[88:91], v[140:143], v[188:191], v[88:91]
	s_waitcnt lgkmcnt(0)
	v_mfma_f32_16x16x32_bf16 v[76:79], v[132:135], v[200:203], v[76:79]
	v_mfma_f32_16x16x32_bf16 v[72:75], v[140:143], v[200:203], v[72:75]
	s_barrier
	s_add_i32 s29, 0, 0x1c000
	s_add_i32 s28, s28, s47
	v_add_u32_e32 v232, s29, v194
	v_lshl_add_u64 v[174:175], v[174:175], 0, s[40:41]
	s_mov_b32 m0, s28
	ds_read_b128 v[204:207], v232
	ds_read_b128 v[208:211], v232 offset:1024
	ds_read_b128 v[212:215], v232 offset:2048
	ds_read_b128 v[232:235], v232 offset:3072
	global_load_lds_dwordx4 v[174:175], off
	v_lshl_add_u64 v[174:175], v[216:217], 0, s[40:41]
	s_add_i32 m0, s28, 0x2000
	s_nop 0
	global_load_lds_dwordx4 v[174:175], off
	s_barrier
	s_waitcnt lgkmcnt(3)
	v_mfma_f32_16x16x32_bf16 v[116:119], v[204:207], v[144:147], v[116:119]
	s_waitcnt lgkmcnt(1)
	v_mfma_f32_16x16x32_bf16 v[112:115], v[212:215], v[144:147], v[112:115]
	v_mfma_f32_16x16x32_bf16 v[100:103], v[204:207], v[162:165], v[100:103]
	v_mfma_f32_16x16x32_bf16 v[96:99], v[212:215], v[162:165], v[96:99]
	v_mfma_f32_16x16x32_bf16 v[84:87], v[204:207], v[170:173], v[84:87]
	v_mfma_f32_16x16x32_bf16 v[80:83], v[212:215], v[170:173], v[80:83]
	v_mfma_f32_16x16x32_bf16 v[68:71], v[204:207], v[196:199], v[68:71]
	v_mfma_f32_16x16x32_bf16 v[64:67], v[212:215], v[196:199], v[64:67]
	v_mfma_f32_16x16x32_bf16 v[116:119], v[208:211], v[148:151], v[116:119]
	s_waitcnt lgkmcnt(0)
	v_mfma_f32_16x16x32_bf16 v[112:115], v[232:235], v[148:151], v[112:115]
	v_mfma_f32_16x16x32_bf16 v[100:103], v[208:211], v[166:169], v[100:103]
	v_mfma_f32_16x16x32_bf16 v[96:99], v[232:235], v[166:169], v[96:99]
	v_mfma_f32_16x16x32_bf16 v[84:87], v[208:211], v[188:191], v[84:87]
	v_mfma_f32_16x16x32_bf16 v[80:83], v[232:235], v[188:191], v[80:83]
	v_mfma_f32_16x16x32_bf16 v[68:71], v[208:211], v[200:203], v[68:71]
	v_mfma_f32_16x16x32_bf16 v[64:67], v[232:235], v[200:203], v[64:67]
	s_mov_b32 m0, s74
	v_lshl_add_u64 v[174:175], v[236:237], 0, s[40:41]
	s_barrier
	ds_read_b128 v[144:147], v195 offset:49152
	ds_read_b128 v[162:165], v195 offset:51200
	ds_read_b128 v[170:173], v195 offset:53248
	ds_read_b128 v[196:199], v195 offset:55296
	ds_read_b128 v[148:151], v195 offset:50176
	ds_read_b128 v[166:169], v195 offset:52224
	ds_read_b128 v[188:191], v195 offset:54272
	ds_read_b128 v[200:203], v195 offset:56320
	global_load_lds_dwordx4 v[174:175], off
	v_lshl_add_u64 v[174:175], v[238:239], 0, s[40:41]
	s_mov_b32 m0, s75
	s_nop 0
	global_load_lds_dwordx4 v[174:175], off
	s_barrier
	s_waitcnt lgkmcnt(7)
	v_mfma_f32_16x16x32_bf16 v[60:63], v[128:131], v[144:147], v[60:63]
	v_mfma_f32_16x16x32_bf16 v[56:59], v[136:139], v[144:147], v[56:59]
	s_waitcnt lgkmcnt(6)
	v_mfma_f32_16x16x32_bf16 v[44:47], v[128:131], v[162:165], v[44:47]
	v_mfma_f32_16x16x32_bf16 v[40:43], v[136:139], v[162:165], v[40:43]
	s_waitcnt lgkmcnt(5)
	v_mfma_f32_16x16x32_bf16 v[28:31], v[128:131], v[170:173], v[28:31]
	v_mfma_f32_16x16x32_bf16 v[24:27], v[136:139], v[170:173], v[24:27]
	s_waitcnt lgkmcnt(4)
	v_mfma_f32_16x16x32_bf16 v[12:15], v[128:131], v[196:199], v[12:15]
	v_mfma_f32_16x16x32_bf16 v[8:11], v[136:139], v[196:199], v[8:11]
	s_waitcnt lgkmcnt(3)
	v_mfma_f32_16x16x32_bf16 v[60:63], v[132:135], v[148:151], v[60:63]
	v_mfma_f32_16x16x32_bf16 v[56:59], v[140:143], v[148:151], v[56:59]
	s_waitcnt lgkmcnt(2)
	v_mfma_f32_16x16x32_bf16 v[44:47], v[132:135], v[166:169], v[44:47]
	v_mfma_f32_16x16x32_bf16 v[40:43], v[140:143], v[166:169], v[40:43]
	s_waitcnt lgkmcnt(1)
	v_mfma_f32_16x16x32_bf16 v[28:31], v[132:135], v[188:191], v[28:31]
	v_mfma_f32_16x16x32_bf16 v[24:27], v[140:143], v[188:191], v[24:27]
	s_waitcnt lgkmcnt(0)
	v_mfma_f32_16x16x32_bf16 v[12:15], v[132:135], v[200:203], v[12:15]
	v_mfma_f32_16x16x32_bf16 v[8:11], v[140:143], v[200:203], v[8:11]
	s_barrier
	s_add_i32 s28, s29, s47
	v_lshl_add_u64 v[128:129], v[240:241], 0, s[40:41]
	s_mov_b32 m0, s28
	s_nop 0
	global_load_lds_dwordx4 v[128:129], off
	v_lshl_add_u64 v[128:129], v[242:243], 0, s[40:41]
	s_add_i32 m0, s28, 0x2000
	s_nop 0
	global_load_lds_dwordx4 v[128:129], off
	s_waitcnt vmcnt(6)
	s_barrier
	v_mfma_f32_16x16x32_bf16 v[52:55], v[204:207], v[144:147], v[52:55]
	v_mfma_f32_16x16x32_bf16 v[48:51], v[212:215], v[144:147], v[48:51]
	v_mfma_f32_16x16x32_bf16 v[36:39], v[204:207], v[162:165], v[36:39]
	v_mfma_f32_16x16x32_bf16 v[32:35], v[212:215], v[162:165], v[32:35]
	v_mfma_f32_16x16x32_bf16 v[20:23], v[204:207], v[170:173], v[20:23]
	v_mfma_f32_16x16x32_bf16 v[16:19], v[212:215], v[170:173], v[16:19]
	v_mfma_f32_16x16x32_bf16 v[4:7], v[204:207], v[196:199], v[4:7]
	v_mfma_f32_16x16x32_bf16 v[0:3], v[212:215], v[196:199], v[0:3]
	v_mfma_f32_16x16x32_bf16 v[52:55], v[208:211], v[148:151], v[52:55]
	v_mfma_f32_16x16x32_bf16 v[48:51], v[232:235], v[148:151], v[48:51]
	v_mfma_f32_16x16x32_bf16 v[36:39], v[208:211], v[166:169], v[36:39]
	v_mfma_f32_16x16x32_bf16 v[32:35], v[232:235], v[166:169], v[32:35]
	v_mfma_f32_16x16x32_bf16 v[20:23], v[208:211], v[188:191], v[20:23]
	v_mfma_f32_16x16x32_bf16 v[16:19], v[232:235], v[188:191], v[16:19]
	v_mfma_f32_16x16x32_bf16 v[4:7], v[208:211], v[200:203], v[4:7]
	v_mfma_f32_16x16x32_bf16 v[0:3], v[232:235], v[200:203], v[0:3]
	s_add_u32 s64, s64, 0x100
	s_addc_u32 s65, s65, 0
	s_add_u32 s91, s91, 0x100
	s_addc_u32 vcc_lo, vcc_lo, 0
	s_cmp_lt_i32 vcc_hi, s76
	s_mov_b32 s66, vcc_hi
	s_barrier
	s_cbranch_scc1 .LBB0_1114
	s_lshl_b32 s28, s84, 8
	v_mov_b32_e32 v128, v193
	v_mov_b32_e32 v129, v192
	s_add_i32 s28, s28, s78
	s_lshl_b32 s64, s24, 2
	v_add_u32_e32 v166, s28, v129
	s_lshl_b32 s28, s24, 8
	s_or_b32 s28, s28, s79
	v_lshl_add_u32 v162, v128, 3, s28
	v_ashrrev_i32_e32 v163, 31, v162
	v_lshlrev_b64 v[204:205], 1, v[162:163]
	v_ashrrev_i32_e32 v167, 31, v166
	v_lshl_add_u64 v[164:165], s[12:13], 0, v[204:205]
	v_lshlrev_b64 v[206:207], 11, v[166:167]
	v_cmp_eq_u32_e32 vcc, 0, v128
	v_lshl_add_u64 v[128:129], v[164:165], 0, v[206:207]
	global_load_dwordx4 v[196:199], v[128:129], off
	global_load_dwordx4 v[200:203], v[128:129], off offset:256
	v_add_u32_e32 v188, 16, v166
	v_ashrrev_i32_e32 v189, 31, v188
	v_add_u32_e32 v172, 32, v166
	v_lshlrev_b64 v[190:191], 11, v[188:189]
	v_ashrrev_i32_e32 v173, 31, v172
	v_add_u32_e32 v168, 48, v166
	v_lshl_add_u64 v[128:129], v[164:165], 0, v[190:191]
	v_lshlrev_b64 v[174:175], 11, v[172:173]
	v_ashrrev_i32_e32 v169, 31, v168
	global_load_dwordx4 v[148:151], v[128:129], off
	global_load_dwordx4 v[144:147], v[128:129], off offset:256
	v_lshl_add_u64 v[128:129], v[164:165], 0, v[174:175]
	v_lshlrev_b64 v[170:171], 11, v[168:169]
	global_load_dwordx4 v[140:143], v[128:129], off
	global_load_dwordx4 v[136:139], v[128:129], off offset:256
	v_lshl_add_u64 v[128:129], v[164:165], 0, v[170:171]
	global_load_dwordx4 v[132:135], v[128:129], off
	s_nop 0
	global_load_dwordx4 v[128:131], v[128:129], off offset:256
	v_lshl_add_u64 v[206:207], s[12:13], 0, v[206:207]
	v_lshl_add_u64 v[204:205], v[206:207], 0, v[204:205]
	s_ashr_i32 s65, s64, 31
	s_waitcnt vmcnt(0)
	v_lshlrev_b32_e32 v208, 16, v196
	v_and_b32_e32 v209, 0xffff0000, v196
	v_lshlrev_b32_e32 v196, 16, v197
	v_and_b32_e32 v197, 0xffff0000, v197
	v_lshlrev_b32_e32 v210, 16, v198
	v_and_b32_e32 v211, 0xffff0000, v198
	v_lshlrev_b32_e32 v198, 16, v199
	v_and_b32_e32 v199, 0xffff0000, v199
	v_pk_fma_f32 v[126:127], s[62:63], v[126:127], v[196:197]
	v_pk_fma_f32 v[124:125], s[10:11], v[124:125], v[208:209]
	v_pk_fma_f32 v[196:197], s[62:63], v[122:123], v[198:199]
	v_pk_fma_f32 v[198:199], s[10:11], v[120:121], v[210:211]
	v_cvt_pk_bf16_f32 v120, v124, v125
	v_cvt_pk_bf16_f32 v121, v126, v127
	s_nop 0
	v_cvt_pk_bf16_f32 v122, v198, v199
	v_cvt_pk_bf16_f32 v123, v196, v197
	global_store_dwordx4 v[204:205], v[120:123], off
	s_nop 1
	v_pk_mul_f32 v[120:121], v[198:199], v[198:199]
	v_pk_mul_f32 v[122:123], v[196:197], v[196:197]
	v_pk_fma_f32 v[120:121], v[124:125], v[124:125], v[120:121]
	v_pk_fma_f32 v[122:123], v[126:127], v[126:127], v[122:123]
	v_add_f32_e32 v120, v120, v121
	v_add_f32_e32 v121, v122, v123
	v_add_f32_e32 v196, v120, v121
	v_lshlrev_b32_e32 v120, 16, v200
	v_and_b32_e32 v121, 0xffff0000, v200
	v_lshlrev_b32_e32 v122, 16, v201
	v_and_b32_e32 v123, 0xffff0000, v201
	v_lshlrev_b32_e32 v124, 16, v202
	v_and_b32_e32 v125, 0xffff0000, v202
	v_lshlrev_b32_e32 v126, 16, v203
	v_and_b32_e32 v127, 0xffff0000, v203
	v_pk_fma_f32 v[118:119], s[62:63], v[118:119], v[122:123]
	v_pk_fma_f32 v[116:117], s[10:11], v[116:117], v[120:121]
	v_pk_fma_f32 v[120:121], s[62:63], v[114:115], v[126:127]
	v_pk_fma_f32 v[122:123], s[10:11], v[112:113], v[124:125]
	v_cvt_pk_bf16_f32 v112, v116, v117
	v_cvt_pk_bf16_f32 v113, v118, v119
	s_nop 0
	v_cvt_pk_bf16_f32 v114, v122, v123
	v_cvt_pk_bf16_f32 v115, v120, v121
	global_store_dwordx4 v[204:205], v[112:115], off offset:256
	s_nop 1
	v_pk_mul_f32 v[112:113], v[122:123], v[122:123]
	v_pk_mul_f32 v[114:115], v[120:121], v[120:121]
	v_pk_fma_f32 v[112:113], v[116:117], v[116:117], v[112:113]
	v_pk_fma_f32 v[114:115], v[118:119], v[118:119], v[114:115]
	v_add_f32_e32 v112, v112, v113
	v_add_f32_e32 v113, v114, v115
	v_add_f32_e32 v112, v112, v113
	v_add_f32_e32 v112, v196, v112
	ds_bpermute_b32 v113, v219, v112
	s_waitcnt lgkmcnt(0)
	v_add_f32_e32 v112, v112, v113
	ds_bpermute_b32 v113, v218, v112
	s_and_saveexec_b64 s[66:67], vcc
	s_cbranch_execz .LBB0_1117
	v_lshlrev_b64 v[114:115], 6, v[166:167]
	v_lshl_add_u64 v[114:115], s[8:9], 0, v[114:115]
	v_lshl_add_u64 v[114:115], s[64:65], 2, v[114:115]
	s_lshl_b32 s24, s77, 2
	v_lshl_add_u64 v[114:115], v[114:115], 0, s[24:25]
	s_waitcnt lgkmcnt(0)
	v_add_f32_e32 v112, v112, v113
	global_store_dword v[114:115], v112, off

.LBB0_1282:
	s_add_i32 s81, s60, 2
	s_add_u32 s28, s58, 0x80
	s_addc_u32 s29, s59, 0
	s_add_i32 s82, 0, 0x10000
	v_add_u32_e32 v140, s82, v195
	ds_read_b128 v[128:131], v140
	ds_read_b128 v[132:135], v140 offset:1024
	ds_read_b128 v[136:139], v140 offset:2048
	ds_read_b128 v[140:143], v140 offset:3072
	s_cmp_eq_u32 s5, s60
	s_cselect_b32 s60, s56, s28
	s_cselect_b32 s61, s57, s29
	s_cselect_b32 s63, s3, s80
	s_cselect_b32 s62, s2, s21
	v_lshl_add_u64 v[174:175], s[58:59], 0, v[158:159]
	s_add_i32 m0, s66, 0xc000
	ds_read_b128 v[144:147], v196
	ds_read_b128 v[162:165], v196 offset:2048
	ds_read_b128 v[170:173], v196 offset:4096
	ds_read_b128 v[198:201], v196 offset:6144
	ds_read_b128 v[148:151], v196 offset:1024
	ds_read_b128 v[166:169], v196 offset:3072
	ds_read_b128 v[188:191], v196 offset:5120
	ds_read_b128 v[202:205], v196 offset:7168
	global_load_lds_dwordx4 v[174:175], off
	v_lshl_add_u64 v[174:175], s[58:59], 0, v[160:161]
	s_add_i32 m0, s66, 0xe000
	s_nop 0
	global_load_lds_dwordx4 v[174:175], off
	s_waitcnt lgkmcnt(8)
	s_barrier
	s_waitcnt lgkmcnt(7)
	v_mfma_f32_16x16x32_bf16 v[124:127], v[128:131], v[144:147], v[124:127]
	v_mfma_f32_16x16x32_bf16 v[120:123], v[136:139], v[144:147], v[120:123]
	s_waitcnt lgkmcnt(6)
	v_mfma_f32_16x16x32_bf16 v[108:111], v[128:131], v[162:165], v[108:111]
	v_mfma_f32_16x16x32_bf16 v[104:107], v[136:139], v[162:165], v[104:107]
	s_waitcnt lgkmcnt(5)
	v_mfma_f32_16x16x32_bf16 v[92:95], v[128:131], v[170:173], v[92:95]
	v_mfma_f32_16x16x32_bf16 v[88:91], v[136:139], v[170:173], v[88:91]
	s_waitcnt lgkmcnt(4)
	v_mfma_f32_16x16x32_bf16 v[76:79], v[128:131], v[198:201], v[76:79]
	v_mfma_f32_16x16x32_bf16 v[72:75], v[136:139], v[198:201], v[72:75]
	s_waitcnt lgkmcnt(3)
	v_mfma_f32_16x16x32_bf16 v[124:127], v[132:135], v[148:151], v[124:127]
	v_mfma_f32_16x16x32_bf16 v[120:123], v[140:143], v[148:151], v[120:123]
	s_waitcnt lgkmcnt(2)
	v_mfma_f32_16x16x32_bf16 v[108:111], v[132:135], v[166:169], v[108:111]
	v_mfma_f32_16x16x32_bf16 v[104:107], v[140:143], v[166:169], v[104:107]
	s_waitcnt lgkmcnt(1)
	v_mfma_f32_16x16x32_bf16 v[92:95], v[132:135], v[188:191], v[92:95]
	v_mfma_f32_16x16x32_bf16 v[88:91], v[140:143], v[188:191], v[88:91]
	s_waitcnt lgkmcnt(0)
	v_mfma_f32_16x16x32_bf16 v[76:79], v[132:135], v[202:205], v[76:79]
	v_mfma_f32_16x16x32_bf16 v[72:75], v[140:143], v[202:205], v[72:75]
	s_barrier
	s_add_i32 s28, 0, 0x14000
	v_add_u32_e32 v174, s28, v195
	s_add_i32 s29, s82, s65
	ds_read_b128 v[206:209], v174
	ds_read_b128 v[210:213], v174 offset:1024
	ds_read_b128 v[214:217], v174 offset:2048
	ds_read_b128 v[232:235], v174 offset:3072
	v_lshl_add_u64 v[174:175], s[62:63], 0, v[176:177]
	s_mov_b32 m0, s29
	v_lshl_add_u64 v[236:237], s[62:63], 0, v[156:157]
	global_load_lds_dwordx4 v[174:175], off
	s_add_i32 m0, s29, 0x2000
	s_nop 0
	global_load_lds_dwordx4 v[236:237], off
	s_barrier
	s_waitcnt lgkmcnt(3)
	v_mfma_f32_16x16x32_bf16 v[116:119], v[206:209], v[144:147], v[116:119]
	s_waitcnt lgkmcnt(1)
	v_mfma_f32_16x16x32_bf16 v[112:115], v[214:217], v[144:147], v[112:115]
	v_mfma_f32_16x16x32_bf16 v[100:103], v[206:209], v[162:165], v[100:103]
	v_mfma_f32_16x16x32_bf16 v[96:99], v[214:217], v[162:165], v[96:99]
	v_mfma_f32_16x16x32_bf16 v[84:87], v[206:209], v[170:173], v[84:87]
	v_mfma_f32_16x16x32_bf16 v[80:83], v[214:217], v[170:173], v[80:83]
	v_mfma_f32_16x16x32_bf16 v[68:71], v[206:209], v[198:201], v[68:71]
	v_mfma_f32_16x16x32_bf16 v[64:67], v[214:217], v[198:201], v[64:67]
	v_mfma_f32_16x16x32_bf16 v[116:119], v[210:213], v[148:151], v[116:119]
	s_waitcnt lgkmcnt(0)
	v_mfma_f32_16x16x32_bf16 v[112:115], v[232:235], v[148:151], v[112:115]
	v_mfma_f32_16x16x32_bf16 v[100:103], v[210:213], v[166:169], v[100:103]
	v_mfma_f32_16x16x32_bf16 v[96:99], v[232:235], v[166:169], v[96:99]
	v_mfma_f32_16x16x32_bf16 v[84:87], v[210:213], v[188:191], v[84:87]
	v_mfma_f32_16x16x32_bf16 v[80:83], v[232:235], v[188:191], v[80:83]
	v_mfma_f32_16x16x32_bf16 v[68:71], v[210:213], v[202:205], v[68:71]
	v_mfma_f32_16x16x32_bf16 v[64:67], v[232:235], v[202:205], v[64:67]
	s_mov_b32 m0, s66
	v_lshl_add_u64 v[238:239], s[60:61], 0, v[152:153]
	s_barrier
	ds_read_b128 v[144:147], v196 offset:16384
	ds_read_b128 v[162:165], v196 offset:18432
	ds_read_b128 v[170:173], v196 offset:20480
	ds_read_b128 v[198:201], v196 offset:22528
	ds_read_b128 v[148:151], v196 offset:17408
	ds_read_b128 v[166:169], v196 offset:19456
	ds_read_b128 v[188:191], v196 offset:21504
	ds_read_b128 v[202:205], v196 offset:23552
	global_load_lds_dwordx4 v[238:239], off
	v_lshl_add_u64 v[240:241], s[60:61], 0, v[154:155]
	s_mov_b32 m0, s67
	s_nop 0
	global_load_lds_dwordx4 v[240:241], off
	s_barrier
	s_waitcnt lgkmcnt(7)
	v_mfma_f32_16x16x32_bf16 v[60:63], v[128:131], v[144:147], v[60:63]
	v_mfma_f32_16x16x32_bf16 v[56:59], v[136:139], v[144:147], v[56:59]
	s_waitcnt lgkmcnt(6)
	v_mfma_f32_16x16x32_bf16 v[44:47], v[128:131], v[162:165], v[44:47]
	v_mfma_f32_16x16x32_bf16 v[40:43], v[136:139], v[162:165], v[40:43]
	s_waitcnt lgkmcnt(5)
	v_mfma_f32_16x16x32_bf16 v[28:31], v[128:131], v[170:173], v[28:31]
	v_mfma_f32_16x16x32_bf16 v[24:27], v[136:139], v[170:173], v[24:27]
	s_waitcnt lgkmcnt(4)
	v_mfma_f32_16x16x32_bf16 v[12:15], v[128:131], v[198:201], v[12:15]
	v_mfma_f32_16x16x32_bf16 v[8:11], v[136:139], v[198:201], v[8:11]
	s_waitcnt lgkmcnt(3)
	v_mfma_f32_16x16x32_bf16 v[60:63], v[132:135], v[148:151], v[60:63]
	v_mfma_f32_16x16x32_bf16 v[56:59], v[140:143], v[148:151], v[56:59]
	s_waitcnt lgkmcnt(2)
	v_mfma_f32_16x16x32_bf16 v[44:47], v[132:135], v[166:169], v[44:47]
	v_mfma_f32_16x16x32_bf16 v[40:43], v[140:143], v[166:169], v[40:43]
	s_waitcnt lgkmcnt(1)
	v_mfma_f32_16x16x32_bf16 v[28:31], v[132:135], v[188:191], v[28:31]
	v_mfma_f32_16x16x32_bf16 v[24:27], v[140:143], v[188:191], v[24:27]
	s_waitcnt lgkmcnt(0)
	v_mfma_f32_16x16x32_bf16 v[12:15], v[132:135], v[202:205], v[12:15]
	v_mfma_f32_16x16x32_bf16 v[8:11], v[140:143], v[202:205], v[8:11]
	s_barrier
	s_add_u32 s62, s62, s4
	s_addc_u32 s63, s63, 0
	s_add_i32 s28, s28, s65
	v_lshl_add_u64 v[242:243], s[62:63], 0, v[176:177]
	s_mov_b32 m0, s28
	v_lshl_add_u64 v[244:245], s[62:63], 0, v[156:157]
	global_load_lds_dwordx4 v[242:243], off
	s_add_i32 m0, s28, 0x2000
	s_nop 0
	global_load_lds_dwordx4 v[244:245], off
	s_waitcnt vmcnt(6)
	s_barrier
	v_mfma_f32_16x16x32_bf16 v[52:55], v[206:209], v[144:147], v[52:55]
	v_mfma_f32_16x16x32_bf16 v[48:51], v[214:217], v[144:147], v[48:51]
	v_mfma_f32_16x16x32_bf16 v[36:39], v[206:209], v[162:165], v[36:39]
	v_mfma_f32_16x16x32_bf16 v[32:35], v[214:217], v[162:165], v[32:35]
	v_mfma_f32_16x16x32_bf16 v[20:23], v[206:209], v[170:173], v[20:23]
	v_mfma_f32_16x16x32_bf16 v[16:19], v[214:217], v[170:173], v[16:19]
	v_mfma_f32_16x16x32_bf16 v[4:7], v[206:209], v[198:201], v[4:7]
	v_mfma_f32_16x16x32_bf16 v[0:3], v[214:217], v[198:201], v[0:3]
	v_mfma_f32_16x16x32_bf16 v[52:55], v[210:213], v[148:151], v[52:55]
	v_mfma_f32_16x16x32_bf16 v[48:51], v[232:235], v[148:151], v[48:51]
	v_mfma_f32_16x16x32_bf16 v[36:39], v[210:213], v[166:169], v[36:39]
	v_mfma_f32_16x16x32_bf16 v[32:35], v[232:235], v[166:169], v[32:35]
	v_mfma_f32_16x16x32_bf16 v[20:23], v[210:213], v[188:191], v[20:23]
	v_mfma_f32_16x16x32_bf16 v[16:19], v[232:235], v[188:191], v[16:19]
	v_mfma_f32_16x16x32_bf16 v[4:7], v[210:213], v[202:205], v[4:7]
	v_mfma_f32_16x16x32_bf16 v[0:3], v[232:235], v[202:205], v[0:3]
	s_add_i32 s28, 0, 0x18000
	v_add_u32_e32 v140, s28, v195
	s_barrier
	ds_read_b128 v[128:131], v140
	ds_read_b128 v[132:135], v140 offset:1024
	ds_read_b128 v[136:139], v140 offset:2048
	ds_read_b128 v[140:143], v140 offset:3072
	s_add_u32 s60, s60, s4
	s_addc_u32 s61, s61, 0
	s_mov_b32 m0, s68
	v_lshl_add_u64 v[206:207], s[60:61], 0, v[152:153]
	ds_read_b128 v[144:147], v196 offset:32768
	ds_read_b128 v[162:165], v196 offset:34816
	ds_read_b128 v[170:173], v196 offset:36864
	ds_read_b128 v[198:201], v196 offset:38912
	ds_read_b128 v[148:151], v196 offset:33792
	ds_read_b128 v[166:169], v196 offset:35840
	ds_read_b128 v[188:191], v196 offset:37888
	ds_read_b128 v[202:205], v196 offset:39936
	global_load_lds_dwordx4 v[206:207], off
	v_lshl_add_u64 v[206:207], s[60:61], 0, v[154:155]
	s_mov_b32 m0, s69
	s_nop 0
	global_load_lds_dwordx4 v[206:207], off
	s_waitcnt lgkmcnt(8)
	s_barrier
	s_waitcnt lgkmcnt(7)
	v_mfma_f32_16x16x32_bf16 v[124:127], v[128:131], v[144:147], v[124:127]
	v_mfma_f32_16x16x32_bf16 v[120:123], v[136:139], v[144:147], v[120:123]
	s_waitcnt lgkmcnt(6)
	v_mfma_f32_16x16x32_bf16 v[108:111], v[128:131], v[162:165], v[108:111]
	v_mfma_f32_16x16x32_bf16 v[104:107], v[136:139], v[162:165], v[104:107]
	s_waitcnt lgkmcnt(5)
	v_mfma_f32_16x16x32_bf16 v[92:95], v[128:131], v[170:173], v[92:95]
	v_mfma_f32_16x16x32_bf16 v[88:91], v[136:139], v[170:173], v[88:91]
	s_waitcnt lgkmcnt(4)
	v_mfma_f32_16x16x32_bf16 v[76:79], v[128:131], v[198:201], v[76:79]
	v_mfma_f32_16x16x32_bf16 v[72:75], v[136:139], v[198:201], v[72:75]
	s_waitcnt lgkmcnt(3)
	v_mfma_f32_16x16x32_bf16 v[124:127], v[132:135], v[148:151], v[124:127]
	v_mfma_f32_16x16x32_bf16 v[120:123], v[140:143], v[148:151], v[120:123]
	s_waitcnt lgkmcnt(2)
	v_mfma_f32_16x16x32_bf16 v[108:111], v[132:135], v[166:169], v[108:111]
	v_mfma_f32_16x16x32_bf16 v[104:107], v[140:143], v[166:169], v[104:107]
	s_waitcnt lgkmcnt(1)
	v_mfma_f32_16x16x32_bf16 v[92:95], v[132:135], v[188:191], v[92:95]
	v_mfma_f32_16x16x32_bf16 v[88:91], v[140:143], v[188:191], v[88:91]
	s_waitcnt lgkmcnt(0)
	v_mfma_f32_16x16x32_bf16 v[76:79], v[132:135], v[202:205], v[76:79]
	v_mfma_f32_16x16x32_bf16 v[72:75], v[140:143], v[202:205], v[72:75]
	s_barrier
	s_add_i32 s29, 0, 0x1c000
	s_add_i32 s28, s28, s65
	v_add_u32_e32 v197, s29, v195
	v_lshl_add_u64 v[174:175], v[174:175], 0, s[40:41]
	s_mov_b32 m0, s28
	ds_read_b128 v[206:209], v197
	ds_read_b128 v[210:213], v197 offset:1024
	ds_read_b128 v[214:217], v197 offset:2048
	ds_read_b128 v[232:235], v197 offset:3072
	global_load_lds_dwordx4 v[174:175], off
	v_lshl_add_u64 v[174:175], v[236:237], 0, s[40:41]
	s_add_i32 m0, s28, 0x2000
	s_nop 0
	global_load_lds_dwordx4 v[174:175], off
	s_barrier
	s_waitcnt lgkmcnt(3)
	v_mfma_f32_16x16x32_bf16 v[116:119], v[206:209], v[144:147], v[116:119]
	s_waitcnt lgkmcnt(1)
	v_mfma_f32_16x16x32_bf16 v[112:115], v[214:217], v[144:147], v[112:115]
	v_mfma_f32_16x16x32_bf16 v[100:103], v[206:209], v[162:165], v[100:103]
	v_mfma_f32_16x16x32_bf16 v[96:99], v[214:217], v[162:165], v[96:99]
	v_mfma_f32_16x16x32_bf16 v[84:87], v[206:209], v[170:173], v[84:87]
	v_mfma_f32_16x16x32_bf16 v[80:83], v[214:217], v[170:173], v[80:83]
	v_mfma_f32_16x16x32_bf16 v[68:71], v[206:209], v[198:201], v[68:71]
	v_mfma_f32_16x16x32_bf16 v[64:67], v[214:217], v[198:201], v[64:67]
	v_mfma_f32_16x16x32_bf16 v[116:119], v[210:213], v[148:151], v[116:119]
	s_waitcnt lgkmcnt(0)
	v_mfma_f32_16x16x32_bf16 v[112:115], v[232:235], v[148:151], v[112:115]
	v_mfma_f32_16x16x32_bf16 v[100:103], v[210:213], v[166:169], v[100:103]
	v_mfma_f32_16x16x32_bf16 v[96:99], v[232:235], v[166:169], v[96:99]
	v_mfma_f32_16x16x32_bf16 v[84:87], v[210:213], v[188:191], v[84:87]
	v_mfma_f32_16x16x32_bf16 v[80:83], v[232:235], v[188:191], v[80:83]
	v_mfma_f32_16x16x32_bf16 v[68:71], v[210:213], v[202:205], v[68:71]
	v_mfma_f32_16x16x32_bf16 v[64:67], v[232:235], v[202:205], v[64:67]
	s_mov_b32 m0, s71
	v_lshl_add_u64 v[174:175], v[238:239], 0, s[40:41]
	s_barrier
	ds_read_b128 v[144:147], v196 offset:49152
	ds_read_b128 v[162:165], v196 offset:51200
	ds_read_b128 v[170:173], v196 offset:53248
	ds_read_b128 v[198:201], v196 offset:55296
	ds_read_b128 v[148:151], v196 offset:50176
	ds_read_b128 v[166:169], v196 offset:52224
	ds_read_b128 v[188:191], v196 offset:54272
	ds_read_b128 v[202:205], v196 offset:56320
	global_load_lds_dwordx4 v[174:175], off
	v_lshl_add_u64 v[174:175], v[240:241], 0, s[40:41]
	s_mov_b32 m0, s72
	s_nop 0
	global_load_lds_dwordx4 v[174:175], off
	s_barrier
	s_waitcnt lgkmcnt(7)
	v_mfma_f32_16x16x32_bf16 v[60:63], v[128:131], v[144:147], v[60:63]
	v_mfma_f32_16x16x32_bf16 v[56:59], v[136:139], v[144:147], v[56:59]
	s_waitcnt lgkmcnt(6)
	v_mfma_f32_16x16x32_bf16 v[44:47], v[128:131], v[162:165], v[44:47]
	v_mfma_f32_16x16x32_bf16 v[40:43], v[136:139], v[162:165], v[40:43]
	s_waitcnt lgkmcnt(5)
	v_mfma_f32_16x16x32_bf16 v[28:31], v[128:131], v[170:173], v[28:31]
	v_mfma_f32_16x16x32_bf16 v[24:27], v[136:139], v[170:173], v[24:27]
	s_waitcnt lgkmcnt(4)
	v_mfma_f32_16x16x32_bf16 v[12:15], v[128:131], v[198:201], v[12:15]
	v_mfma_f32_16x16x32_bf16 v[8:11], v[136:139], v[198:201], v[8:11]
	s_waitcnt lgkmcnt(3)
	v_mfma_f32_16x16x32_bf16 v[60:63], v[132:135], v[148:151], v[60:63]
	v_mfma_f32_16x16x32_bf16 v[56:59], v[140:143], v[148:151], v[56:59]
	s_waitcnt lgkmcnt(2)
	v_mfma_f32_16x16x32_bf16 v[44:47], v[132:135], v[166:169], v[44:47]
	v_mfma_f32_16x16x32_bf16 v[40:43], v[140:143], v[166:169], v[40:43]
	s_waitcnt lgkmcnt(1)
	v_mfma_f32_16x16x32_bf16 v[28:31], v[132:135], v[188:191], v[28:31]
	v_mfma_f32_16x16x32_bf16 v[24:27], v[140:143], v[188:191], v[24:27]
	s_waitcnt lgkmcnt(0)
	v_mfma_f32_16x16x32_bf16 v[12:15], v[132:135], v[202:205], v[12:15]
	v_mfma_f32_16x16x32_bf16 v[8:11], v[140:143], v[202:205], v[8:11]
	s_barrier
	s_add_i32 s28, s29, s65
	v_lshl_add_u64 v[128:129], v[242:243], 0, s[40:41]
	s_mov_b32 m0, s28
	s_nop 0
	global_load_lds_dwordx4 v[128:129], off
	v_lshl_add_u64 v[128:129], v[244:245], 0, s[40:41]
	s_add_i32 m0, s28, 0x2000
	s_nop 0
	global_load_lds_dwordx4 v[128:129], off
	s_waitcnt vmcnt(6)
	s_barrier
	v_mfma_f32_16x16x32_bf16 v[52:55], v[206:209], v[144:147], v[52:55]
	v_mfma_f32_16x16x32_bf16 v[48:51], v[214:217], v[144:147], v[48:51]
	v_mfma_f32_16x16x32_bf16 v[36:39], v[206:209], v[162:165], v[36:39]
	v_mfma_f32_16x16x32_bf16 v[32:35], v[214:217], v[162:165], v[32:35]
	v_mfma_f32_16x16x32_bf16 v[20:23], v[206:209], v[170:173], v[20:23]
	v_mfma_f32_16x16x32_bf16 v[16:19], v[214:217], v[170:173], v[16:19]
	v_mfma_f32_16x16x32_bf16 v[4:7], v[206:209], v[198:201], v[4:7]
	v_mfma_f32_16x16x32_bf16 v[0:3], v[214:217], v[198:201], v[0:3]
	v_mfma_f32_16x16x32_bf16 v[52:55], v[210:213], v[148:151], v[52:55]
	v_mfma_f32_16x16x32_bf16 v[48:51], v[232:235], v[148:151], v[48:51]
	v_mfma_f32_16x16x32_bf16 v[36:39], v[210:213], v[166:169], v[36:39]
	v_mfma_f32_16x16x32_bf16 v[32:35], v[232:235], v[166:169], v[32:35]
	v_mfma_f32_16x16x32_bf16 v[20:23], v[210:213], v[188:191], v[20:23]
	v_mfma_f32_16x16x32_bf16 v[16:19], v[232:235], v[188:191], v[16:19]
	v_mfma_f32_16x16x32_bf16 v[4:7], v[210:213], v[202:205], v[4:7]
	v_mfma_f32_16x16x32_bf16 v[0:3], v[232:235], v[202:205], v[0:3]
	s_add_u32 s58, s58, 0x100
	s_addc_u32 s59, s59, 0
	s_add_u32 s21, s21, 0x100
	s_addc_u32 s80, s80, 0
	s_cmp_ge_i32 s81, s79
	s_mov_b32 s60, s81
	s_barrier
	s_cbranch_scc0 .LBB0_1282
	s_cmp_gt_i32 s24, -1
	s_mov_b64 s[58:59], -1
	s_cbranch_scc0 .LBB0_1285
	s_lshl_b64 s[58:59], s[24:25], 17
	v_mov_b32_e32 v128, v231
	s_add_u32 s58, s37, s58
	s_addc_u32 s59, s46, s59
	v_ashrrev_i32_e32 v129, 31, v128
	v_lshl_add_u64 v[128:129], v[128:129], 4, s[58:59]
	v_add_co_u32_e32 v134, vcc, s36, v128
	v_cvt_pk_bf16_f32 v130, v124, v125
	v_cvt_pk_bf16_f32 v131, v126, v127
	v_cvt_pk_bf16_f32 v132, v120, v121
	v_cvt_pk_bf16_f32 v133, v122, v123
	s_nop 1
	v_addc_co_u32_e32 v135, vcc, 0, v129, vcc
	s_movk_i32 s5, 0x4000
	global_store_dwordx4 v[128:129], v[130:133], off
	s_mov_b64 s[58:59], 0
	s_nop 0
	v_cvt_pk_bf16_f32 v130, v108, v109
	v_cvt_pk_bf16_f32 v131, v110, v111
	v_cvt_pk_bf16_f32 v132, v104, v105
	v_cvt_pk_bf16_f32 v133, v106, v107
	global_store_dwordx4 v[134:135], v[130:133], off
	v_add_co_u32_e32 v134, vcc, s5, v128
	s_movk_i32 s5, 0x6000
	s_nop 0
	v_addc_co_u32_e32 v135, vcc, 0, v129, vcc
	v_cvt_pk_bf16_f32 v130, v92, v93
	v_cvt_pk_bf16_f32 v131, v94, v95
	v_cvt_pk_bf16_f32 v132, v88, v89
	v_cvt_pk_bf16_f32 v133, v90, v91
	global_store_dwordx4 v[134:135], v[130:133], off
	v_add_co_u32_e32 v134, vcc, s5, v128
	s_nop 0
	v_cvt_pk_bf16_f32 v130, v76, v77
	v_cvt_pk_bf16_f32 v131, v78, v79
	v_cvt_pk_bf16_f32 v132, v72, v73
	v_cvt_pk_bf16_f32 v133, v74, v75
	s_nop 0
	v_addc_co_u32_e32 v135, vcc, 0, v129, vcc
	global_store_dwordx4 v[134:135], v[130:133], off
	v_add_co_u32_e32 v134, vcc, s92, v128
	s_mov_b32 s5, 0xa000
	s_nop 0
	v_addc_co_u32_e32 v135, vcc, 0, v129, vcc
	v_cvt_pk_bf16_f32 v130, v116, v117
	v_cvt_pk_bf16_f32 v131, v118, v119
	v_cvt_pk_bf16_f32 v132, v112, v113
	v_cvt_pk_bf16_f32 v133, v114, v115
	global_store_dwordx4 v[134:135], v[130:133], off
	v_add_co_u32_e32 v134, vcc, s5, v128
	s_mov_b32 s5, 0xc000
	s_nop 0
	v_addc_co_u32_e32 v135, vcc, 0, v129, vcc
	v_cvt_pk_bf16_f32 v130, v100, v101
	v_cvt_pk_bf16_f32 v131, v102, v103
	v_cvt_pk_bf16_f32 v132, v96, v97
	v_cvt_pk_bf16_f32 v133, v98, v99
	global_store_dwordx4 v[134:135], v[130:133], off
	v_add_co_u32_e32 v134, vcc, s5, v128
	s_mov_b32 s5, 0xe000
	s_nop 0
	v_addc_co_u32_e32 v135, vcc, 0, v129, vcc
	v_cvt_pk_bf16_f32 v130, v84, v85
	v_cvt_pk_bf16_f32 v131, v86, v87
	v_cvt_pk_bf16_f32 v132, v80, v81
	v_cvt_pk_bf16_f32 v133, v82, v83
	global_store_dwordx4 v[134:135], v[130:133], off
	v_add_co_u32_e32 v134, vcc, s5, v128
	s_mov_b32 s5, 0x10000
	s_nop 0
	v_addc_co_u32_e32 v135, vcc, 0, v129, vcc
	v_cvt_pk_bf16_f32 v130, v68, v69
	v_cvt_pk_bf16_f32 v131, v70, v71
	v_cvt_pk_bf16_f32 v132, v64, v65
	v_cvt_pk_bf16_f32 v133, v66, v67
	global_store_dwordx4 v[134:135], v[130:133], off
	v_add_co_u32_e32 v134, vcc, s5, v128
	s_mov_b32 s5, 0x12000
	s_nop 0
	v_addc_co_u32_e32 v135, vcc, 0, v129, vcc
	v_cvt_pk_bf16_f32 v130, v60, v61
	v_cvt_pk_bf16_f32 v131, v62, v63
	v_cvt_pk_bf16_f32 v132, v56, v57
	v_cvt_pk_bf16_f32 v133, v58, v59
	global_store_dwordx4 v[134:135], v[130:133], off
	v_add_co_u32_e32 v134, vcc, s5, v128
	s_mov_b32 s5, 0x14000
	s_nop 0
	v_addc_co_u32_e32 v135, vcc, 0, v129, vcc
	v_cvt_pk_bf16_f32 v130, v44, v45
	v_cvt_pk_bf16_f32 v131, v46, v47
	v_cvt_pk_bf16_f32 v132, v40, v41
	v_cvt_pk_bf16_f32 v133, v42, v43
	global_store_dwordx4 v[134:135], v[130:133], off
	v_add_co_u32_e32 v134, vcc, s5, v128
	s_mov_b32 s5, 0x16000
	s_nop 0
	v_addc_co_u32_e32 v135, vcc, 0, v129, vcc
	v_cvt_pk_bf16_f32 v130, v28, v29
	v_cvt_pk_bf16_f32 v131, v30, v31
	v_cvt_pk_bf16_f32 v132, v24, v25
	v_cvt_pk_bf16_f32 v133, v26, v27
	global_store_dwordx4 v[134:135], v[130:133], off
	v_add_co_u32_e32 v134, vcc, s5, v128
	s_mov_b32 s5, 0x18000
	s_nop 0
	v_addc_co_u32_e32 v135, vcc, 0, v129, vcc
	v_cvt_pk_bf16_f32 v130, v12, v13
	v_cvt_pk_bf16_f32 v131, v14, v15
	v_cvt_pk_bf16_f32 v132, v8, v9
	v_cvt_pk_bf16_f32 v133, v10, v11
	global_store_dwordx4 v[134:135], v[130:133], off
	v_add_co_u32_e32 v134, vcc, s5, v128
	s_mov_b32 s5, 0x1a000
	s_nop 0
	v_addc_co_u32_e32 v135, vcc, 0, v129, vcc
	v_cvt_pk_bf16_f32 v130, v52, v53
	v_cvt_pk_bf16_f32 v131, v54, v55
	v_cvt_pk_bf16_f32 v132, v48, v49
	v_cvt_pk_bf16_f32 v133, v50, v51
	global_store_dwordx4 v[134:135], v[130:133], off
	v_add_co_u32_e32 v134, vcc, s5, v128
	s_mov_b32 s5, 0x1c000
	s_nop 0
	v_addc_co_u32_e32 v135, vcc, 0, v129, vcc
	v_cvt_pk_bf16_f32 v130, v36, v37
	v_cvt_pk_bf16_f32 v131, v38, v39
	v_cvt_pk_bf16_f32 v132, v32, v33
	v_cvt_pk_bf16_f32 v133, v34, v35
	global_store_dwordx4 v[134:135], v[130:133], off
	v_add_co_u32_e32 v134, vcc, s5, v128
	s_nop 0
	v_cvt_pk_bf16_f32 v130, v20, v21
	v_cvt_pk_bf16_f32 v131, v22, v23
	v_cvt_pk_bf16_f32 v132, v16, v17
	v_cvt_pk_bf16_f32 v133, v18, v19
	s_nop 0
	v_addc_co_u32_e32 v135, vcc, 0, v129, vcc
	v_add_co_u32_e32 v128, vcc, 0x1e000, v128
	global_store_dwordx4 v[134:135], v[130:133], off
	s_nop 0
	v_addc_co_u32_e32 v129, vcc, 0, v129, vcc
	v_cvt_pk_bf16_f32 v130, v4, v5
	v_cvt_pk_bf16_f32 v131, v6, v7
	v_cvt_pk_bf16_f32 v132, v0, v1
	v_cvt_pk_bf16_f32 v133, v2, v3
	global_store_dwordx4 v[128:129], v[130:133], off

.LBB0_1436:
	s_add_u32 s28, s6, 0xfffc0080
	s_addc_u32 s29, s7, -1
	s_add_i32 s71, 0, 0x10000
	v_add_u32_e32 v140, s71, v200
	ds_read_b128 v[128:131], v140
	ds_read_b128 v[132:135], v140 offset:1024
	ds_read_b128 v[136:139], v140 offset:2048
	ds_read_b128 v[140:143], v140 offset:3072
	s_cmp_eq_u32 s70, 12
	s_cselect_b32 s53, s17, s29
	s_cselect_b32 s52, s66, s28
	s_cselect_b32 s51, s13, s69
	s_cselect_b32 s50, s67, s68
	v_lshl_add_u64 v[174:175], s[6:7], 0, v[162:163]
	s_add_i32 m0, s56, 0xc000
	ds_read_b128 v[144:147], v201
	ds_read_b128 v[152:155], v201 offset:2048
	ds_read_b128 v[170:173], v201 offset:4096
	ds_read_b128 v[192:195], v201 offset:6144
	ds_read_b128 v[148:151], v201 offset:1024
	ds_read_b128 v[166:169], v201 offset:3072
	ds_read_b128 v[188:191], v201 offset:5120
	ds_read_b128 v[202:205], v201 offset:7168
	global_load_lds_dwordx4 v[174:175], off
	v_lshl_add_u64 v[174:175], s[6:7], 0, v[164:165]
	s_add_i32 m0, s56, 0xe000
	s_nop 0
	global_load_lds_dwordx4 v[174:175], off
	s_waitcnt lgkmcnt(8)
	s_barrier
	s_waitcnt lgkmcnt(7)
	v_mfma_f32_16x16x32_bf16 v[124:127], v[128:131], v[144:147], v[124:127]
	v_mfma_f32_16x16x32_bf16 v[116:119], v[136:139], v[144:147], v[116:119]
	s_waitcnt lgkmcnt(6)
	v_mfma_f32_16x16x32_bf16 v[108:111], v[128:131], v[152:155], v[108:111]
	v_mfma_f32_16x16x32_bf16 v[100:103], v[136:139], v[152:155], v[100:103]
	s_waitcnt lgkmcnt(5)
	v_mfma_f32_16x16x32_bf16 v[92:95], v[128:131], v[170:173], v[92:95]
	v_mfma_f32_16x16x32_bf16 v[84:87], v[136:139], v[170:173], v[84:87]
	s_waitcnt lgkmcnt(4)
	v_mfma_f32_16x16x32_bf16 v[76:79], v[128:131], v[192:195], v[76:79]
	v_mfma_f32_16x16x32_bf16 v[68:71], v[136:139], v[192:195], v[68:71]
	s_waitcnt lgkmcnt(3)
	v_mfma_f32_16x16x32_bf16 v[124:127], v[132:135], v[148:151], v[124:127]
	v_mfma_f32_16x16x32_bf16 v[116:119], v[140:143], v[148:151], v[116:119]
	s_waitcnt lgkmcnt(2)
	v_mfma_f32_16x16x32_bf16 v[108:111], v[132:135], v[166:169], v[108:111]
	v_mfma_f32_16x16x32_bf16 v[100:103], v[140:143], v[166:169], v[100:103]
	s_waitcnt lgkmcnt(1)
	v_mfma_f32_16x16x32_bf16 v[92:95], v[132:135], v[188:191], v[92:95]
	v_mfma_f32_16x16x32_bf16 v[84:87], v[140:143], v[188:191], v[84:87]
	s_waitcnt lgkmcnt(0)
	v_mfma_f32_16x16x32_bf16 v[76:79], v[132:135], v[202:205], v[76:79]
	v_mfma_f32_16x16x32_bf16 v[68:71], v[140:143], v[202:205], v[68:71]
	s_barrier
	s_add_i32 s28, 0, 0x14000
	v_add_u32_e32 v174, s28, v200
	s_add_i32 s29, s71, s55
	ds_read_b128 v[206:209], v174
	ds_read_b128 v[210:213], v174 offset:1024
	ds_read_b128 v[214:217], v174 offset:2048
	ds_read_b128 v[232:235], v174 offset:3072
	v_lshl_add_u64 v[174:175], s[50:51], 0, v[176:177]
	s_mov_b32 m0, s29
	v_lshl_add_u64 v[196:197], s[50:51], 0, v[160:161]
	global_load_lds_dwordx4 v[174:175], off
	s_add_i32 m0, s29, 0x2000
	s_nop 0
	global_load_lds_dwordx4 v[196:197], off
	s_barrier
	s_waitcnt lgkmcnt(3)
	v_mfma_f32_16x16x32_bf16 v[120:123], v[206:209], v[144:147], v[120:123]
	s_waitcnt lgkmcnt(1)
	v_mfma_f32_16x16x32_bf16 v[112:115], v[214:217], v[144:147], v[112:115]
	v_mfma_f32_16x16x32_bf16 v[104:107], v[206:209], v[152:155], v[104:107]
	v_mfma_f32_16x16x32_bf16 v[96:99], v[214:217], v[152:155], v[96:99]
	v_mfma_f32_16x16x32_bf16 v[88:91], v[206:209], v[170:173], v[88:91]
	v_mfma_f32_16x16x32_bf16 v[80:83], v[214:217], v[170:173], v[80:83]
	v_mfma_f32_16x16x32_bf16 v[72:75], v[206:209], v[192:195], v[72:75]
	v_mfma_f32_16x16x32_bf16 v[64:67], v[214:217], v[192:195], v[64:67]
	v_mfma_f32_16x16x32_bf16 v[120:123], v[210:213], v[148:151], v[120:123]
	s_waitcnt lgkmcnt(0)
	v_mfma_f32_16x16x32_bf16 v[112:115], v[232:235], v[148:151], v[112:115]
	v_mfma_f32_16x16x32_bf16 v[104:107], v[210:213], v[166:169], v[104:107]
	v_mfma_f32_16x16x32_bf16 v[96:99], v[232:235], v[166:169], v[96:99]
	v_mfma_f32_16x16x32_bf16 v[88:91], v[210:213], v[188:191], v[88:91]
	v_mfma_f32_16x16x32_bf16 v[80:83], v[232:235], v[188:191], v[80:83]
	v_mfma_f32_16x16x32_bf16 v[72:75], v[210:213], v[202:205], v[72:75]
	v_mfma_f32_16x16x32_bf16 v[64:67], v[232:235], v[202:205], v[64:67]
	s_mov_b32 m0, s56
	v_lshl_add_u64 v[236:237], s[52:53], 0, v[156:157]
	s_barrier
	ds_read_b128 v[144:147], v201 offset:16384
	ds_read_b128 v[152:155], v201 offset:18432
	ds_read_b128 v[170:173], v201 offset:20480
	ds_read_b128 v[192:195], v201 offset:22528
	ds_read_b128 v[148:151], v201 offset:17408
	ds_read_b128 v[166:169], v201 offset:19456
	ds_read_b128 v[188:191], v201 offset:21504
	ds_read_b128 v[202:205], v201 offset:23552
	global_load_lds_dwordx4 v[236:237], off
	v_lshl_add_u64 v[238:239], s[52:53], 0, v[158:159]
	s_mov_b32 m0, s57
	s_nop 0
	global_load_lds_dwordx4 v[238:239], off
	s_barrier
	s_waitcnt lgkmcnt(7)
	v_mfma_f32_16x16x32_bf16 v[60:63], v[128:131], v[144:147], v[60:63]
	v_mfma_f32_16x16x32_bf16 v[52:55], v[136:139], v[144:147], v[52:55]
	s_waitcnt lgkmcnt(6)
	v_mfma_f32_16x16x32_bf16 v[44:47], v[128:131], v[152:155], v[44:47]
	v_mfma_f32_16x16x32_bf16 v[36:39], v[136:139], v[152:155], v[36:39]
	s_waitcnt lgkmcnt(5)
	v_mfma_f32_16x16x32_bf16 v[28:31], v[128:131], v[170:173], v[28:31]
	v_mfma_f32_16x16x32_bf16 v[20:23], v[136:139], v[170:173], v[20:23]
	s_waitcnt lgkmcnt(4)
	v_mfma_f32_16x16x32_bf16 v[12:15], v[128:131], v[192:195], v[12:15]
	v_mfma_f32_16x16x32_bf16 v[4:7], v[136:139], v[192:195], v[4:7]
	s_waitcnt lgkmcnt(3)
	v_mfma_f32_16x16x32_bf16 v[60:63], v[132:135], v[148:151], v[60:63]
	v_mfma_f32_16x16x32_bf16 v[52:55], v[140:143], v[148:151], v[52:55]
	s_waitcnt lgkmcnt(2)
	v_mfma_f32_16x16x32_bf16 v[44:47], v[132:135], v[166:169], v[44:47]
	v_mfma_f32_16x16x32_bf16 v[36:39], v[140:143], v[166:169], v[36:39]
	s_waitcnt lgkmcnt(1)
	v_mfma_f32_16x16x32_bf16 v[28:31], v[132:135], v[188:191], v[28:31]
	v_mfma_f32_16x16x32_bf16 v[20:23], v[140:143], v[188:191], v[20:23]
	s_waitcnt lgkmcnt(0)
	v_mfma_f32_16x16x32_bf16 v[12:15], v[132:135], v[202:205], v[12:15]
	v_mfma_f32_16x16x32_bf16 v[4:7], v[140:143], v[202:205], v[4:7]
	s_barrier
	s_add_u32 s72, s50, 0x40000
	s_addc_u32 s73, s51, 0
	s_add_i32 s28, s28, s55
	v_lshl_add_u64 v[128:129], s[72:73], 0, v[176:177]
	s_mov_b32 m0, s28
	s_nop 0
	global_load_lds_dwordx4 v[128:129], off
	v_lshl_add_u64 v[128:129], s[72:73], 0, v[160:161]
	s_add_i32 m0, s28, 0x2000
	s_nop 0
	global_load_lds_dwordx4 v[128:129], off
	s_waitcnt vmcnt(6)
	s_barrier
	v_mfma_f32_16x16x32_bf16 v[56:59], v[206:209], v[144:147], v[56:59]
	v_mfma_f32_16x16x32_bf16 v[48:51], v[214:217], v[144:147], v[48:51]
	v_mfma_f32_16x16x32_bf16 v[40:43], v[206:209], v[152:155], v[40:43]
	v_mfma_f32_16x16x32_bf16 v[32:35], v[214:217], v[152:155], v[32:35]
	v_mfma_f32_16x16x32_bf16 v[24:27], v[206:209], v[170:173], v[24:27]
	v_mfma_f32_16x16x32_bf16 v[16:19], v[214:217], v[170:173], v[16:19]
	v_mfma_f32_16x16x32_bf16 v[8:11], v[206:209], v[192:195], v[8:11]
	v_mfma_f32_16x16x32_bf16 v[0:3], v[214:217], v[192:195], v[0:3]
	v_mfma_f32_16x16x32_bf16 v[56:59], v[210:213], v[148:151], v[56:59]
	v_mfma_f32_16x16x32_bf16 v[48:51], v[232:235], v[148:151], v[48:51]
	v_mfma_f32_16x16x32_bf16 v[40:43], v[210:213], v[166:169], v[40:43]
	v_mfma_f32_16x16x32_bf16 v[32:35], v[232:235], v[166:169], v[32:35]
	v_mfma_f32_16x16x32_bf16 v[24:27], v[210:213], v[188:191], v[24:27]
	v_mfma_f32_16x16x32_bf16 v[16:19], v[232:235], v[188:191], v[16:19]
	v_mfma_f32_16x16x32_bf16 v[8:11], v[210:213], v[202:205], v[8:11]
	v_mfma_f32_16x16x32_bf16 v[0:3], v[232:235], v[202:205], v[0:3]
	s_add_i32 s28, 0, 0x18000
	v_add_u32_e32 v140, s28, v200
	s_barrier
	ds_read_b128 v[128:131], v140
	ds_read_b128 v[132:135], v140 offset:1024
	ds_read_b128 v[136:139], v140 offset:2048
	ds_read_b128 v[140:143], v140 offset:3072
	s_add_u32 s52, s52, 0x40000
	s_addc_u32 s53, s53, 0
	s_mov_b32 m0, s58
	v_lshl_add_u64 v[206:207], s[52:53], 0, v[156:157]
	ds_read_b128 v[144:147], v201 offset:32768
	ds_read_b128 v[152:155], v201 offset:34816
	ds_read_b128 v[170:173], v201 offset:36864
	ds_read_b128 v[192:195], v201 offset:38912
	ds_read_b128 v[148:151], v201 offset:33792
	ds_read_b128 v[166:169], v201 offset:35840
	ds_read_b128 v[188:191], v201 offset:37888
	ds_read_b128 v[202:205], v201 offset:39936
	global_load_lds_dwordx4 v[206:207], off
	v_lshl_add_u64 v[206:207], s[52:53], 0, v[158:159]
	s_mov_b32 m0, s59
	s_nop 0
	global_load_lds_dwordx4 v[206:207], off
	s_waitcnt lgkmcnt(8)
	s_barrier
	s_waitcnt lgkmcnt(7)
	v_mfma_f32_16x16x32_bf16 v[124:127], v[128:131], v[144:147], v[124:127]
	v_mfma_f32_16x16x32_bf16 v[116:119], v[136:139], v[144:147], v[116:119]
	s_waitcnt lgkmcnt(6)
	v_mfma_f32_16x16x32_bf16 v[108:111], v[128:131], v[152:155], v[108:111]
	v_mfma_f32_16x16x32_bf16 v[100:103], v[136:139], v[152:155], v[100:103]
	s_waitcnt lgkmcnt(5)
	v_mfma_f32_16x16x32_bf16 v[92:95], v[128:131], v[170:173], v[92:95]
	v_mfma_f32_16x16x32_bf16 v[84:87], v[136:139], v[170:173], v[84:87]
	s_waitcnt lgkmcnt(4)
	v_mfma_f32_16x16x32_bf16 v[76:79], v[128:131], v[192:195], v[76:79]
	v_mfma_f32_16x16x32_bf16 v[68:71], v[136:139], v[192:195], v[68:71]
	s_waitcnt lgkmcnt(3)
	v_mfma_f32_16x16x32_bf16 v[124:127], v[132:135], v[148:151], v[124:127]
	v_mfma_f32_16x16x32_bf16 v[116:119], v[140:143], v[148:151], v[116:119]
	s_waitcnt lgkmcnt(2)
	v_mfma_f32_16x16x32_bf16 v[108:111], v[132:135], v[166:169], v[108:111]
	v_mfma_f32_16x16x32_bf16 v[100:103], v[140:143], v[166:169], v[100:103]
	s_waitcnt lgkmcnt(1)
	v_mfma_f32_16x16x32_bf16 v[92:95], v[132:135], v[188:191], v[92:95]
	v_mfma_f32_16x16x32_bf16 v[84:87], v[140:143], v[188:191], v[84:87]
	s_waitcnt lgkmcnt(0)
	v_mfma_f32_16x16x32_bf16 v[76:79], v[132:135], v[202:205], v[76:79]
	v_mfma_f32_16x16x32_bf16 v[68:71], v[140:143], v[202:205], v[68:71]
	s_barrier
	s_add_i32 s29, 0, 0x1c000
	s_add_i32 s28, s28, s55
	v_add_u32_e32 v232, s29, v200
	v_lshl_add_u64 v[174:175], v[174:175], 0, s[40:41]
	s_mov_b32 m0, s28
	ds_read_b128 v[206:209], v232
	ds_read_b128 v[210:213], v232 offset:1024
	ds_read_b128 v[214:217], v232 offset:2048
	ds_read_b128 v[232:235], v232 offset:3072
	global_load_lds_dwordx4 v[174:175], off
	v_lshl_add_u64 v[174:175], v[196:197], 0, s[40:41]
	s_add_i32 m0, s28, 0x2000
	s_nop 0
	global_load_lds_dwordx4 v[174:175], off
	s_barrier
	s_waitcnt lgkmcnt(3)
	v_mfma_f32_16x16x32_bf16 v[120:123], v[206:209], v[144:147], v[120:123]
	s_waitcnt lgkmcnt(1)
	v_mfma_f32_16x16x32_bf16 v[112:115], v[214:217], v[144:147], v[112:115]
	v_mfma_f32_16x16x32_bf16 v[104:107], v[206:209], v[152:155], v[104:107]
	v_mfma_f32_16x16x32_bf16 v[96:99], v[214:217], v[152:155], v[96:99]
	v_mfma_f32_16x16x32_bf16 v[88:91], v[206:209], v[170:173], v[88:91]
	v_mfma_f32_16x16x32_bf16 v[80:83], v[214:217], v[170:173], v[80:83]
	v_mfma_f32_16x16x32_bf16 v[72:75], v[206:209], v[192:195], v[72:75]
	v_mfma_f32_16x16x32_bf16 v[64:67], v[214:217], v[192:195], v[64:67]
	v_mfma_f32_16x16x32_bf16 v[120:123], v[210:213], v[148:151], v[120:123]
	s_waitcnt lgkmcnt(0)
	v_mfma_f32_16x16x32_bf16 v[112:115], v[232:235], v[148:151], v[112:115]
	v_mfma_f32_16x16x32_bf16 v[104:107], v[210:213], v[166:169], v[104:107]
	v_mfma_f32_16x16x32_bf16 v[96:99], v[232:235], v[166:169], v[96:99]
	v_mfma_f32_16x16x32_bf16 v[88:91], v[210:213], v[188:191], v[88:91]
	v_mfma_f32_16x16x32_bf16 v[80:83], v[232:235], v[188:191], v[80:83]
	v_mfma_f32_16x16x32_bf16 v[72:75], v[210:213], v[202:205], v[72:75]
	v_mfma_f32_16x16x32_bf16 v[64:67], v[232:235], v[202:205], v[64:67]
	s_mov_b32 m0, s62
	v_lshl_add_u64 v[174:175], v[236:237], 0, s[40:41]
	s_barrier
	ds_read_b128 v[144:147], v201 offset:49152
	ds_read_b128 v[152:155], v201 offset:51200
	ds_read_b128 v[170:173], v201 offset:53248
	ds_read_b128 v[192:195], v201 offset:55296
	ds_read_b128 v[148:151], v201 offset:50176
	ds_read_b128 v[166:169], v201 offset:52224
	ds_read_b128 v[188:191], v201 offset:54272
	ds_read_b128 v[202:205], v201 offset:56320
	global_load_lds_dwordx4 v[174:175], off
	v_lshl_add_u64 v[174:175], v[238:239], 0, s[40:41]
	s_mov_b32 m0, s63
	s_nop 0
	global_load_lds_dwordx4 v[174:175], off
	s_barrier
	s_waitcnt lgkmcnt(7)
	v_mfma_f32_16x16x32_bf16 v[60:63], v[128:131], v[144:147], v[60:63]
	v_mfma_f32_16x16x32_bf16 v[52:55], v[136:139], v[144:147], v[52:55]
	s_waitcnt lgkmcnt(6)
	v_mfma_f32_16x16x32_bf16 v[44:47], v[128:131], v[152:155], v[44:47]
	v_mfma_f32_16x16x32_bf16 v[36:39], v[136:139], v[152:155], v[36:39]
	s_waitcnt lgkmcnt(5)
	v_mfma_f32_16x16x32_bf16 v[28:31], v[128:131], v[170:173], v[28:31]
	v_mfma_f32_16x16x32_bf16 v[20:23], v[136:139], v[170:173], v[20:23]
	s_waitcnt lgkmcnt(4)
	v_mfma_f32_16x16x32_bf16 v[12:15], v[128:131], v[192:195], v[12:15]
	v_mfma_f32_16x16x32_bf16 v[4:7], v[136:139], v[192:195], v[4:7]
	s_waitcnt lgkmcnt(3)
	v_mfma_f32_16x16x32_bf16 v[60:63], v[132:135], v[148:151], v[60:63]
	v_mfma_f32_16x16x32_bf16 v[52:55], v[140:143], v[148:151], v[52:55]
	s_waitcnt lgkmcnt(2)
	v_mfma_f32_16x16x32_bf16 v[44:47], v[132:135], v[166:169], v[44:47]
	v_mfma_f32_16x16x32_bf16 v[36:39], v[140:143], v[166:169], v[36:39]
	s_waitcnt lgkmcnt(1)
	v_mfma_f32_16x16x32_bf16 v[28:31], v[132:135], v[188:191], v[28:31]
	v_mfma_f32_16x16x32_bf16 v[20:23], v[140:143], v[188:191], v[20:23]
	s_waitcnt lgkmcnt(0)
	v_mfma_f32_16x16x32_bf16 v[12:15], v[132:135], v[202:205], v[12:15]
	v_mfma_f32_16x16x32_bf16 v[4:7], v[140:143], v[202:205], v[4:7]
	s_barrier
	s_add_u32 s50, s50, 0x40080
	s_addc_u32 s51, s51, 0
	s_add_i32 s28, s29, s55
	v_lshl_add_u64 v[128:129], s[50:51], 0, v[176:177]
	s_mov_b32 m0, s28
	s_nop 0
	global_load_lds_dwordx4 v[128:129], off
	v_lshl_add_u64 v[128:129], s[50:51], 0, v[160:161]
	s_add_i32 m0, s28, 0x2000
	s_nop 0
	global_load_lds_dwordx4 v[128:129], off
	s_waitcnt vmcnt(6)
	s_barrier
	v_mfma_f32_16x16x32_bf16 v[56:59], v[206:209], v[144:147], v[56:59]
	v_mfma_f32_16x16x32_bf16 v[48:51], v[214:217], v[144:147], v[48:51]
	v_mfma_f32_16x16x32_bf16 v[40:43], v[206:209], v[152:155], v[40:43]
	v_mfma_f32_16x16x32_bf16 v[32:35], v[214:217], v[152:155], v[32:35]
	v_mfma_f32_16x16x32_bf16 v[24:27], v[206:209], v[170:173], v[24:27]
	v_mfma_f32_16x16x32_bf16 v[16:19], v[214:217], v[170:173], v[16:19]
	v_mfma_f32_16x16x32_bf16 v[8:11], v[206:209], v[192:195], v[8:11]
	v_mfma_f32_16x16x32_bf16 v[0:3], v[214:217], v[192:195], v[0:3]
	v_mfma_f32_16x16x32_bf16 v[56:59], v[210:213], v[148:151], v[56:59]
	v_mfma_f32_16x16x32_bf16 v[48:51], v[232:235], v[148:151], v[48:51]
	v_mfma_f32_16x16x32_bf16 v[40:43], v[210:213], v[166:169], v[40:43]
	v_mfma_f32_16x16x32_bf16 v[32:35], v[232:235], v[166:169], v[32:35]
	v_mfma_f32_16x16x32_bf16 v[24:27], v[210:213], v[188:191], v[24:27]
	v_mfma_f32_16x16x32_bf16 v[16:19], v[232:235], v[188:191], v[16:19]
	v_mfma_f32_16x16x32_bf16 v[8:11], v[210:213], v[202:205], v[8:11]
	v_mfma_f32_16x16x32_bf16 v[0:3], v[232:235], v[202:205], v[0:3]
	s_add_i32 s70, s70, 2
	s_add_u32 s6, s6, 0x100
	s_addc_u32 s7, s7, 0
	s_add_u32 s68, s68, 0x100
	s_addc_u32 s69, s69, 0
	s_cmp_lt_u32 s70, 14
	s_barrier
	s_cbranch_scc1 .LBB0_1436
	v_mov_b32_e32 v134, v199
	v_mov_b32_e32 v128, v198
	s_lshl_b32 s4, s4, 8
	s_add_i32 s4, s4, s60
	v_add_u32_e32 v192, s4, v128
	v_lshlrev_b32_e32 v128, 2, v134
	v_ashrrev_i32_e32 v129, 31, v128
	v_ashrrev_i32_e32 v193, 31, v192
	v_add_u32_e32 v190, 16, v192
	v_lshl_add_u64 v[132:133], v[128:129], 2, s[8:9]
	v_lshlrev_b64 v[128:129], 6, v[192:193]
	v_ashrrev_i32_e32 v191, 31, v190
	v_add_u32_e32 v188, 32, v192
	v_lshl_add_u64 v[128:129], v[132:133], 0, v[128:129]
	v_lshlrev_b64 v[130:131], 6, v[190:191]
	v_ashrrev_i32_e32 v189, 31, v188
	v_lshl_add_u64 v[130:131], v[132:133], 0, v[130:131]
	global_load_dwordx4 v[202:205], v[128:129], off
	global_load_dwordx4 v[144:147], v[130:131], off
	v_lshlrev_b64 v[128:129], 6, v[188:189]
	v_add_u32_e32 v174, 48, v192
	v_lshl_add_u64 v[128:129], v[132:133], 0, v[128:129]
	v_ashrrev_i32_e32 v175, 31, v174
	global_load_dwordx4 v[148:151], v[128:129], off
	v_lshlrev_b64 v[128:129], 6, v[174:175]
	v_lshl_add_u64 v[128:129], v[132:133], 0, v[128:129]
	global_load_dwordx4 v[152:155], v[128:129], off
	v_add_u32_e32 v172, 0x80, v192
	v_ashrrev_i32_e32 v173, 31, v172
	v_lshlrev_b64 v[128:129], 6, v[172:173]
	v_lshl_add_u64 v[128:129], v[132:133], 0, v[128:129]
	global_load_dwordx4 v[140:143], v[128:129], off
	v_add_u32_e32 v170, 0x90, v192
	v_ashrrev_i32_e32 v171, 31, v170
	v_lshlrev_b64 v[128:129], 6, v[170:171]
	v_lshl_add_u64 v[128:129], v[132:133], 0, v[128:129]
	global_load_dwordx4 v[128:131], v[128:129], off
	s_lshl_b32 s5, s5, 7
	v_add_u32_e32 v168, 0xa0, v192
	v_add_u32_e32 v166, 0xb0, v192
	s_or_b32 s5, s5, s61
	v_ashrrev_i32_e32 v169, 31, v168
	v_ashrrev_i32_e32 v167, 31, v166
	v_lshl_add_u32 v194, v134, 3, s5
	v_lshlrev_b64 v[134:135], 6, v[168:169]
	v_lshlrev_b64 v[136:137], 6, v[166:167]
	v_lshl_add_u64 v[134:135], v[132:133], 0, v[134:135]
	v_lshl_add_u64 v[132:133], v[132:133], 0, v[136:137]
	global_load_dwordx4 v[136:139], v[134:135], off
	s_nop 0
	global_load_dwordx4 v[132:135], v[132:133], off
	s_mov_b32 s4, 0x358637bd
	v_mov_b64_e32 v[196:197], s[4:5]
	v_ashrrev_i32_e32 v195, 31, v194
	s_mov_b64 s[50:51], s[20:21]
	s_waitcnt vmcnt(0)
	v_mov_b32_e32 v206, v203
	v_mov_b32_e32 v207, v204
	v_mov_b32_e32 v203, v205
	v_mov_b32_e32 v204, v145
	v_mov_b32_e32 v205, v146
	v_mov_b32_e32 v145, v147
	v_pk_add_f32 v[202:203], v[206:207], v[202:203]
	v_mov_b32_e32 v146, v149
	v_mov_b32_e32 v147, v150
	v_mov_b32_e32 v149, v151
	v_mov_b32_e32 v150, v153
	v_mov_b32_e32 v151, v154
	v_mov_b32_e32 v153, v155
	v_pk_add_f32 v[144:145], v[204:205], v[144:145]
	v_mov_b32_e32 v155, v202
	v_pk_add_f32 v[146:147], v[146:147], v[148:149]
	v_pk_add_f32 v[148:149], v[150:151], v[152:153]
	v_mov_b32_e32 v154, v144
	v_mov_b32_e32 v202, v145
	v_mov_b32_e32 v144, v148
	v_mov_b32_e32 v145, v146
	v_mov_b32_e32 v146, v149
	v_pk_add_f32 v[148:149], v[154:155], v[202:203]
	v_pk_add_f32 v[144:145], v[144:145], v[146:147]
	ds_bpermute_b32 v147, v219, v149
	ds_bpermute_b32 v146, v219, v148
	ds_bpermute_b32 v151, v219, v145
	ds_bpermute_b32 v150, v219, v144
	v_mov_b32_e32 v152, v141
	v_mov_b32_e32 v153, v142
	v_mov_b32_e32 v141, v143
	s_waitcnt lgkmcnt(0)
	v_pk_add_f32 v[142:143], v[148:149], v[146:147]
	ds_bpermute_b32 v147, v218, v143
	ds_bpermute_b32 v146, v218, v142
	v_pk_add_f32 v[144:145], v[144:145], v[150:151]
	ds_bpermute_b32 v149, v218, v145
	ds_bpermute_b32 v148, v218, v144
	v_mov_b32_e32 v150, v129
	s_waitcnt lgkmcnt(2)
	v_pk_add_f32 v[142:143], v[142:143], v[146:147]
	v_mov_b32_e32 v151, v130
	v_pk_fma_f32 v[142:143], v[142:143], s[30:31], v[196:197] op_sel_hi:[1,0,0]
	s_waitcnt lgkmcnt(0)
	v_pk_add_f32 v[144:145], v[144:145], v[148:149]
	v_mul_f32_e32 v129, 0x4b800000, v143
	v_cmp_gt_f32_e32 vcc, s86, v143
	v_pk_fma_f32 v[146:147], v[144:145], s[30:31], v[196:197] op_sel_hi:[1,0,0]
	v_mul_f32_e32 v130, 0x4b800000, v142
	v_cndmask_b32_e32 v129, v143, v129, vcc
	v_rsq_f32_e32 v129, v129
	v_cmp_gt_f32_e64 s[4:5], s86, v142
	v_mul_f32_e32 v144, 0x4b800000, v147
	v_cmp_gt_f32_e64 s[6:7], s86, v147
	v_cndmask_b32_e64 v130, v142, v130, s[4:5]
	v_rsq_f32_e32 v142, v130
	v_cndmask_b32_e64 v130, v147, v144, s[6:7]
	v_rsq_f32_e32 v143, v130
	v_mul_f32_e32 v130, 0x45800000, v129
	v_cndmask_b32_e32 v144, v129, v130, vcc
	v_mov_b32_e32 v129, v131
	v_pk_add_f32 v[140:141], v[152:153], v[140:141]
	v_pk_add_f32 v[128:129], v[150:151], v[128:129]
	v_mov_b32_e32 v131, v140
	v_mov_b32_e32 v130, v128
	v_mov_b32_e32 v140, v129
	v_pk_add_f32 v[128:129], v[130:131], v[140:141]
	ds_bpermute_b32 v131, v219, v129
	ds_bpermute_b32 v130, v219, v128
	v_mul_f32_e32 v145, 0x45800000, v142
	v_cndmask_b32_e64 v142, v142, v145, s[4:5]
	v_mul_f32_e32 v140, 0x4b800000, v146
	v_cmp_gt_f32_e32 vcc, s86, v146
	s_waitcnt lgkmcnt(0)
	v_pk_add_f32 v[128:129], v[128:129], v[130:131]
	ds_bpermute_b32 v131, v218, v129
	ds_bpermute_b32 v130, v218, v128
	v_cndmask_b32_e32 v140, v146, v140, vcc
	v_rsq_f32_e32 v141, v140
	v_mul_f32_e32 v140, 0x45800000, v143
	v_cndmask_b32_e64 v140, v143, v140, s[6:7]
	s_waitcnt lgkmcnt(0)
	v_pk_add_f32 v[128:129], v[128:129], v[130:131]
	v_mov_b32_e32 v131, v138
	v_pk_fma_f32 v[128:129], v[128:129], s[30:31], v[196:197] op_sel_hi:[1,0,0]
	v_mul_f32_e32 v143, 0x45800000, v141
	v_mul_f32_e32 v130, 0x4b800000, v129
	v_cmp_gt_f32_e64 s[4:5], s86, v129
	v_cmp_gt_f32_e64 s[6:7], s86, v128
	v_pk_mul_f32 v[110:111], v[110:111], v[142:143] op_sel_hi:[1,0]
	v_cndmask_b32_e64 v129, v129, v130, s[4:5]
	v_mov_b32_e32 v130, v137
	v_mov_b32_e32 v137, v139
	v_pk_add_f32 v[130:131], v[130:131], v[136:137]
	v_mov_b32_e32 v136, v133
	v_mov_b32_e32 v137, v134
	v_mov_b32_e32 v133, v135
	v_pk_add_f32 v[132:133], v[136:137], v[132:133]
	v_mov_b32_e32 v135, v130
	v_mov_b32_e32 v134, v132
	v_mov_b32_e32 v130, v133
	v_pk_add_f32 v[130:131], v[134:135], v[130:131]
	ds_bpermute_b32 v133, v219, v131
	ds_bpermute_b32 v132, v219, v130
	v_rsq_f32_e32 v145, v129
	v_mul_f32_e32 v129, 0x4b800000, v128
	v_cndmask_b32_e64 v128, v128, v129, s[6:7]
	v_rsq_f32_e32 v135, v128
	s_waitcnt lgkmcnt(0)
	v_pk_add_f32 v[128:129], v[130:131], v[132:133]
	ds_bpermute_b32 v131, v218, v129
	ds_bpermute_b32 v130, v218, v128
	v_pk_mul_f32 v[126:127], v[126:127], v[144:145] op_sel_hi:[1,0]
	v_pk_mul_f32 v[122:123], v[122:123], v[144:145] op_sel_hi:[1,0]
	v_pk_mul_f32 v[116:117], v[116:117], v[144:145] op_sel_hi:[1,0]
	v_pk_mul_f32 v[124:125], v[124:125], v[144:145] op_sel_hi:[1,0]
	v_pk_mul_f32 v[138:139], v[126:127], s[44:45] op_sel_hi:[1,0]
	v_pk_mul_f32 v[120:121], v[120:121], v[144:145] op_sel_hi:[1,0]
	v_pk_mul_f32 v[122:123], v[126:127], v[122:123]
	v_pk_mul_f32 v[118:119], v[118:119], v[144:145] op_sel_hi:[1,0]
	v_pk_mul_f32 v[126:127], v[116:117], s[44:45] op_sel_hi:[1,0]
	v_pk_mul_f32 v[146:147], v[124:125], s[44:45] op_sel_hi:[1,0]
	v_pk_mul_f32 v[120:121], v[124:125], v[120:121]
	v_pk_mul_f32 v[124:125], v[118:119], s[44:45] op_sel_hi:[1,0]
	v_exp_f32_e32 v126, v126
	v_exp_f32_e32 v127, v127
	s_waitcnt lgkmcnt(0)
	v_pk_add_f32 v[128:129], v[128:129], v[130:131]
	v_exp_f32_e32 v146, v146
	v_exp_f32_e32 v138, v138
	v_exp_f32_e32 v139, v139
	v_exp_f32_e32 v147, v147
	v_exp_f32_e32 v124, v124
	v_exp_f32_e32 v125, v125
	v_pk_fma_f32 v[128:129], v[128:129], s[30:31], v[196:197] op_sel_hi:[1,0,0]
	v_cndmask_b32_e32 v136, v141, v143, vcc
	v_mul_f32_e32 v132, 0x45800000, v145
	v_mul_f32_e32 v130, 0x4b800000, v129
	v_cmp_gt_f32_e32 vcc, s86, v129
	v_cndmask_b32_e64 v134, v145, v132, s[4:5]
	v_cmp_gt_f32_e64 s[4:5], s86, v128
	v_cndmask_b32_e32 v129, v129, v130, vcc
	v_mul_f32_e32 v130, 0x4b800000, v128
	v_pk_add_f32 v[126:127], v[126:127], 1.0 op_sel_hi:[1,0]
	v_rsq_f32_e32 v129, v129
	v_cndmask_b32_e64 v128, v128, v130, s[4:5]
	v_pk_add_f32 v[138:139], v[138:139], 1.0 op_sel_hi:[1,0]
	v_pk_add_f32 v[146:147], v[146:147], 1.0 op_sel_hi:[1,0]
	v_pk_add_f32 v[124:125], v[124:125], 1.0 op_sel_hi:[1,0]
	v_rcp_f32_e32 v126, v126
	v_rcp_f32_e32 v127, v127
	v_rsq_f32_e32 v128, v128
	v_rcp_f32_e32 v146, v146
	v_rcp_f32_e32 v138, v138
	v_rcp_f32_e32 v139, v139
	v_rcp_f32_e32 v147, v147
	v_rcp_f32_e32 v124, v124
	v_rcp_f32_e32 v125, v125
	v_pk_mul_f32 v[112:113], v[112:113], v[144:145] op_sel_hi:[1,0]
	v_pk_mul_f32 v[114:115], v[114:115], v[144:145] op_sel_hi:[1,0]
	v_pk_mul_f32 v[112:113], v[116:117], v[112:113]
	v_mul_f32_e32 v130, 0x45800000, v129
	v_pk_mul_f32 v[114:115], v[118:119], v[114:115]
	v_pk_mul_f32 v[112:113], v[112:113], v[126:127]
	v_cndmask_b32_e32 v130, v129, v130, vcc
	v_mul_f32_e32 v129, 0x45800000, v128
	v_pk_mul_f32 v[122:123], v[122:123], v[138:139]
	v_pk_mul_f32 v[120:121], v[120:121], v[146:147]
	v_pk_mul_f32 v[114:115], v[114:115], v[124:125]
	v_cvt_pk_bf16_f32 v116, v120, v121
	v_cvt_pk_bf16_f32 v117, v122, v123
	v_cvt_pk_bf16_f32 v118, v112, v113
	v_mov_b64_e32 v[112:113], s[10:11]
	v_cndmask_b32_e64 v128, v128, v129, s[4:5]
	v_cvt_pk_bf16_f32 v119, v114, v115
	v_mad_i64_i32 v[120:121], s[4:5], v192, s35, v[112:113]
	v_lshlrev_b64 v[114:115], 1, v[194:195]
	v_lshl_add_u64 v[120:121], v[120:121], 0, v[114:115]
	v_pk_mul_f32 v[108:109], v[108:109], v[142:143] op_sel_hi:[1,0]
	v_pk_mul_f32 v[106:107], v[106:107], v[142:143] op_sel_hi:[1,0]
	v_pk_mul_f32 v[104:105], v[104:105], v[142:143] op_sel_hi:[1,0]
	v_pk_mul_f32 v[102:103], v[102:103], v[142:143] op_sel_hi:[1,0]
	v_pk_mul_f32 v[100:101], v[100:101], v[142:143] op_sel_hi:[1,0]
	global_store_dwordx4 v[120:121], v[116:119], off
	v_pk_mul_f32 v[104:105], v[108:109], v[104:105]
	v_pk_mul_f32 v[106:107], v[110:111], v[106:107]
	v_pk_mul_f32 v[116:117], v[110:111], s[44:45] op_sel_hi:[1,0]
	v_pk_mul_f32 v[118:119], v[108:109], s[44:45] op_sel_hi:[1,0]
	v_pk_mul_f32 v[108:109], v[102:103], s[44:45] op_sel_hi:[1,0]
	v_pk_mul_f32 v[110:111], v[100:101], s[44:45] op_sel_hi:[1,0]
	v_exp_f32_e32 v108, v108
	v_exp_f32_e32 v110, v110
	v_exp_f32_e32 v109, v109
	v_exp_f32_e32 v111, v111
	v_exp_f32_e32 v118, v118
	v_exp_f32_e32 v116, v116
	v_exp_f32_e32 v117, v117
	v_exp_f32_e32 v119, v119
	v_pk_add_f32 v[108:109], v[108:109], 1.0 op_sel_hi:[1,0]
	v_pk_add_f32 v[110:111], v[110:111], 1.0 op_sel_hi:[1,0]
	v_pk_add_f32 v[116:117], v[116:117], 1.0 op_sel_hi:[1,0]
	v_pk_add_f32 v[118:119], v[118:119], 1.0 op_sel_hi:[1,0]
	v_rcp_f32_e32 v110, v110
	v_rcp_f32_e32 v108, v108
	v_rcp_f32_e32 v109, v109
	v_rcp_f32_e32 v111, v111
	v_rcp_f32_e32 v118, v118
	v_rcp_f32_e32 v116, v116
	v_rcp_f32_e32 v117, v117
	v_rcp_f32_e32 v119, v119
	v_pk_mul_f32 v[98:99], v[98:99], v[142:143] op_sel_hi:[1,0]
	v_pk_mul_f32 v[96:97], v[96:97], v[142:143] op_sel_hi:[1,0]
	v_pk_mul_f32 v[98:99], v[102:103], v[98:99]
	v_pk_mul_f32 v[96:97], v[100:101], v[96:97]
	v_pk_mul_f32 v[100:101], v[98:99], v[108:109]
	v_pk_mul_f32 v[98:99], v[96:97], v[110:111]
	v_pk_mul_f32 v[106:107], v[106:107], v[116:117]
	v_pk_mul_f32 v[104:105], v[104:105], v[118:119]
	v_pk_mul_f32 v[94:95], v[94:95], v[140:141] op_sel_hi:[1,0]
	v_cvt_pk_bf16_f32 v96, v104, v105
	v_cvt_pk_bf16_f32 v97, v106, v107
	v_cvt_pk_bf16_f32 v98, v98, v99
	v_cvt_pk_bf16_f32 v99, v100, v101
	v_mad_i64_i32 v[100:101], s[4:5], v190, s35, v[112:113]
	v_lshl_add_u64 v[100:101], v[100:101], 0, v[114:115]
	v_pk_mul_f32 v[92:93], v[92:93], v[140:141] op_sel_hi:[1,0]
	v_pk_mul_f32 v[90:91], v[90:91], v[140:141] op_sel_hi:[1,0]
	v_pk_mul_f32 v[88:89], v[88:89], v[140:141] op_sel_hi:[1,0]
	v_pk_mul_f32 v[86:87], v[86:87], v[140:141] op_sel_hi:[1,0]
	v_pk_mul_f32 v[84:85], v[84:85], v[140:141] op_sel_hi:[1,0]
	global_store_dwordx4 v[100:101], v[96:99], off
	v_pk_mul_f32 v[88:89], v[92:93], v[88:89]
	v_pk_mul_f32 v[90:91], v[94:95], v[90:91]
	v_pk_mul_f32 v[96:97], v[94:95], s[44:45] op_sel_hi:[1,0]
	v_pk_mul_f32 v[98:99], v[92:93], s[44:45] op_sel_hi:[1,0]
	v_pk_mul_f32 v[92:93], v[86:87], s[44:45] op_sel_hi:[1,0]
	v_pk_mul_f32 v[94:95], v[84:85], s[44:45] op_sel_hi:[1,0]
	v_exp_f32_e32 v92, v92
	v_exp_f32_e32 v94, v94
	v_exp_f32_e32 v93, v93
	v_exp_f32_e32 v95, v95
	v_exp_f32_e32 v98, v98
	v_exp_f32_e32 v96, v96
	v_exp_f32_e32 v97, v97
	v_exp_f32_e32 v99, v99
	v_pk_add_f32 v[92:93], v[92:93], 1.0 op_sel_hi:[1,0]
	v_pk_add_f32 v[94:95], v[94:95], 1.0 op_sel_hi:[1,0]
	v_pk_add_f32 v[96:97], v[96:97], 1.0 op_sel_hi:[1,0]
	v_pk_add_f32 v[98:99], v[98:99], 1.0 op_sel_hi:[1,0]
	v_rcp_f32_e32 v94, v94
	v_rcp_f32_e32 v92, v92
	v_rcp_f32_e32 v93, v93
	v_rcp_f32_e32 v95, v95
	v_rcp_f32_e32 v98, v98
	v_rcp_f32_e32 v96, v96
	v_rcp_f32_e32 v97, v97
	v_rcp_f32_e32 v99, v99
	v_pk_mul_f32 v[82:83], v[82:83], v[140:141] op_sel_hi:[1,0]
	v_pk_mul_f32 v[80:81], v[80:81], v[140:141] op_sel_hi:[1,0]
	v_pk_mul_f32 v[82:83], v[86:87], v[82:83]
	v_pk_mul_f32 v[80:81], v[84:85], v[80:81]
	v_pk_mul_f32 v[84:85], v[82:83], v[92:93]
	v_pk_mul_f32 v[82:83], v[80:81], v[94:95]
	v_pk_mul_f32 v[90:91], v[90:91], v[96:97]
	v_pk_mul_f32 v[88:89], v[88:89], v[98:99]
	v_pk_mul_f32 v[78:79], v[78:79], v[136:137] op_sel_hi:[1,0]
	v_cvt_pk_bf16_f32 v80, v88, v89
	v_cvt_pk_bf16_f32 v81, v90, v91
	v_cvt_pk_bf16_f32 v82, v82, v83
	v_cvt_pk_bf16_f32 v83, v84, v85
	v_mad_i64_i32 v[84:85], s[4:5], v188, s35, v[112:113]
	v_lshl_add_u64 v[84:85], v[84:85], 0, v[114:115]
	v_pk_mul_f32 v[76:77], v[76:77], v[136:137] op_sel_hi:[1,0]
	v_pk_mul_f32 v[74:75], v[74:75], v[136:137] op_sel_hi:[1,0]
	v_pk_mul_f32 v[72:73], v[72:73], v[136:137] op_sel_hi:[1,0]
	v_pk_mul_f32 v[70:71], v[70:71], v[136:137] op_sel_hi:[1,0]
	v_pk_mul_f32 v[68:69], v[68:69], v[136:137] op_sel_hi:[1,0]
	global_store_dwordx4 v[84:85], v[80:83], off
	v_pk_mul_f32 v[72:73], v[76:77], v[72:73]
	v_pk_mul_f32 v[74:75], v[78:79], v[74:75]
	v_pk_mul_f32 v[80:81], v[78:79], s[44:45] op_sel_hi:[1,0]
	v_pk_mul_f32 v[82:83], v[76:77], s[44:45] op_sel_hi:[1,0]
	v_pk_mul_f32 v[76:77], v[70:71], s[44:45] op_sel_hi:[1,0]
	v_pk_mul_f32 v[78:79], v[68:69], s[44:45] op_sel_hi:[1,0]
	v_exp_f32_e32 v76, v76
	v_exp_f32_e32 v78, v78
	v_exp_f32_e32 v77, v77
	v_exp_f32_e32 v79, v79
	v_exp_f32_e32 v82, v82
	v_exp_f32_e32 v80, v80
	v_exp_f32_e32 v81, v81
	v_exp_f32_e32 v83, v83
	v_pk_add_f32 v[76:77], v[76:77], 1.0 op_sel_hi:[1,0]
	v_pk_add_f32 v[78:79], v[78:79], 1.0 op_sel_hi:[1,0]
	v_pk_add_f32 v[80:81], v[80:81], 1.0 op_sel_hi:[1,0]
	v_pk_add_f32 v[82:83], v[82:83], 1.0 op_sel_hi:[1,0]
	v_rcp_f32_e32 v78, v78
	v_rcp_f32_e32 v76, v76
	v_rcp_f32_e32 v77, v77
	v_rcp_f32_e32 v79, v79
	v_rcp_f32_e32 v82, v82
	v_rcp_f32_e32 v80, v80
	v_rcp_f32_e32 v81, v81
	v_rcp_f32_e32 v83, v83
	v_pk_mul_f32 v[66:67], v[66:67], v[136:137] op_sel_hi:[1,0]
	v_pk_mul_f32 v[64:65], v[64:65], v[136:137] op_sel_hi:[1,0]
	v_pk_mul_f32 v[66:67], v[70:71], v[66:67]
	v_pk_mul_f32 v[64:65], v[68:69], v[64:65]
	v_pk_mul_f32 v[68:69], v[66:67], v[76:77]
	v_pk_mul_f32 v[66:67], v[64:65], v[78:79]
	v_pk_mul_f32 v[74:75], v[74:75], v[80:81]
	v_pk_mul_f32 v[72:73], v[72:73], v[82:83]
	v_pk_mul_f32 v[62:63], v[62:63], v[134:135] op_sel_hi:[1,0]
	v_cvt_pk_bf16_f32 v64, v72, v73
	v_cvt_pk_bf16_f32 v65, v74, v75
	v_cvt_pk_bf16_f32 v66, v66, v67
	v_cvt_pk_bf16_f32 v67, v68, v69
	v_mad_i64_i32 v[68:69], s[4:5], v174, s35, v[112:113]
	v_lshl_add_u64 v[68:69], v[68:69], 0, v[114:115]
	v_pk_mul_f32 v[60:61], v[60:61], v[134:135] op_sel_hi:[1,0]
	v_pk_mul_f32 v[58:59], v[58:59], v[134:135] op_sel_hi:[1,0]
	v_pk_mul_f32 v[56:57], v[56:57], v[134:135] op_sel_hi:[1,0]
	v_pk_mul_f32 v[54:55], v[54:55], v[134:135] op_sel_hi:[1,0]
	v_pk_mul_f32 v[52:53], v[52:53], v[134:135] op_sel_hi:[1,0]
	global_store_dwordx4 v[68:69], v[64:67], off
	v_pk_mul_f32 v[56:57], v[60:61], v[56:57]
	v_pk_mul_f32 v[58:59], v[62:63], v[58:59]
	v_pk_mul_f32 v[64:65], v[62:63], s[44:45] op_sel_hi:[1,0]
	v_pk_mul_f32 v[66:67], v[60:61], s[44:45] op_sel_hi:[1,0]
	v_pk_mul_f32 v[60:61], v[54:55], s[44:45] op_sel_hi:[1,0]
	v_pk_mul_f32 v[62:63], v[52:53], s[44:45] op_sel_hi:[1,0]
	v_exp_f32_e32 v60, v60
	v_exp_f32_e32 v62, v62
	v_exp_f32_e32 v61, v61
	v_exp_f32_e32 v63, v63
	v_exp_f32_e32 v66, v66
	v_exp_f32_e32 v64, v64
	v_exp_f32_e32 v65, v65
	v_exp_f32_e32 v67, v67
	v_pk_add_f32 v[60:61], v[60:61], 1.0 op_sel_hi:[1,0]
	v_pk_add_f32 v[62:63], v[62:63], 1.0 op_sel_hi:[1,0]
	v_pk_add_f32 v[64:65], v[64:65], 1.0 op_sel_hi:[1,0]
	v_pk_add_f32 v[66:67], v[66:67], 1.0 op_sel_hi:[1,0]
	v_rcp_f32_e32 v62, v62
	v_rcp_f32_e32 v60, v60
	v_rcp_f32_e32 v61, v61
	v_rcp_f32_e32 v63, v63
	v_rcp_f32_e32 v66, v66
	v_rcp_f32_e32 v64, v64
	v_rcp_f32_e32 v65, v65
	v_rcp_f32_e32 v67, v67
	v_pk_mul_f32 v[50:51], v[50:51], v[134:135] op_sel_hi:[1,0]
	v_pk_mul_f32 v[48:49], v[48:49], v[134:135] op_sel_hi:[1,0]
	v_pk_mul_f32 v[50:51], v[54:55], v[50:51]
	v_pk_mul_f32 v[48:49], v[52:53], v[48:49]
	v_mul_f32_e32 v132, 0x45800000, v135
	v_pk_mul_f32 v[52:53], v[50:51], v[60:61]
	v_pk_mul_f32 v[50:51], v[48:49], v[62:63]
	v_cndmask_b32_e64 v132, v135, v132, s[6:7]
	v_pk_mul_f32 v[58:59], v[58:59], v[64:65]
	v_pk_mul_f32 v[56:57], v[56:57], v[66:67]
	v_pk_mul_f32 v[46:47], v[46:47], v[132:133] op_sel_hi:[1,0]
	v_cvt_pk_bf16_f32 v48, v56, v57
	v_cvt_pk_bf16_f32 v49, v58, v59
	v_cvt_pk_bf16_f32 v50, v50, v51
	v_cvt_pk_bf16_f32 v51, v52, v53
	v_mad_i64_i32 v[52:53], s[4:5], v172, s35, v[112:113]
	v_lshl_add_u64 v[52:53], v[52:53], 0, v[114:115]
	v_pk_mul_f32 v[44:45], v[44:45], v[132:133] op_sel_hi:[1,0]
	v_pk_mul_f32 v[42:43], v[42:43], v[132:133] op_sel_hi:[1,0]
	v_pk_mul_f32 v[40:41], v[40:41], v[132:133] op_sel_hi:[1,0]
	v_pk_mul_f32 v[38:39], v[38:39], v[132:133] op_sel_hi:[1,0]
	v_pk_mul_f32 v[36:37], v[36:37], v[132:133] op_sel_hi:[1,0]
	global_store_dwordx4 v[52:53], v[48:51], off
	v_pk_mul_f32 v[40:41], v[44:45], v[40:41]
	v_pk_mul_f32 v[42:43], v[46:47], v[42:43]
	v_pk_mul_f32 v[48:49], v[46:47], s[44:45] op_sel_hi:[1,0]
	v_pk_mul_f32 v[50:51], v[44:45], s[44:45] op_sel_hi:[1,0]
	v_pk_mul_f32 v[44:45], v[38:39], s[44:45] op_sel_hi:[1,0]
	v_pk_mul_f32 v[46:47], v[36:37], s[44:45] op_sel_hi:[1,0]
	v_exp_f32_e32 v44, v44
	v_exp_f32_e32 v46, v46
	v_exp_f32_e32 v45, v45
	v_exp_f32_e32 v47, v47
	v_exp_f32_e32 v50, v50
	v_exp_f32_e32 v48, v48
	v_exp_f32_e32 v49, v49
	v_exp_f32_e32 v51, v51
	v_pk_add_f32 v[44:45], v[44:45], 1.0 op_sel_hi:[1,0]
	v_pk_add_f32 v[46:47], v[46:47], 1.0 op_sel_hi:[1,0]
	v_pk_add_f32 v[48:49], v[48:49], 1.0 op_sel_hi:[1,0]
	v_pk_add_f32 v[50:51], v[50:51], 1.0 op_sel_hi:[1,0]
	v_rcp_f32_e32 v46, v46
	v_rcp_f32_e32 v44, v44
	v_rcp_f32_e32 v45, v45
	v_rcp_f32_e32 v47, v47
	v_rcp_f32_e32 v50, v50
	v_rcp_f32_e32 v48, v48
	v_rcp_f32_e32 v49, v49
	v_rcp_f32_e32 v51, v51
	v_pk_mul_f32 v[34:35], v[34:35], v[132:133] op_sel_hi:[1,0]
	v_pk_mul_f32 v[32:33], v[32:33], v[132:133] op_sel_hi:[1,0]
	v_pk_mul_f32 v[34:35], v[38:39], v[34:35]
	v_pk_mul_f32 v[32:33], v[36:37], v[32:33]
	v_pk_mul_f32 v[36:37], v[34:35], v[44:45]
	v_pk_mul_f32 v[34:35], v[32:33], v[46:47]
	v_pk_mul_f32 v[42:43], v[42:43], v[48:49]
	v_pk_mul_f32 v[40:41], v[40:41], v[50:51]
	v_pk_mul_f32 v[30:31], v[30:31], v[130:131] op_sel_hi:[1,0]
	v_cvt_pk_bf16_f32 v32, v40, v41
	v_cvt_pk_bf16_f32 v33, v42, v43
	v_cvt_pk_bf16_f32 v34, v34, v35
	v_cvt_pk_bf16_f32 v35, v36, v37
	v_mad_i64_i32 v[36:37], s[4:5], v170, s35, v[112:113]
	v_lshl_add_u64 v[36:37], v[36:37], 0, v[114:115]
	v_pk_mul_f32 v[28:29], v[28:29], v[130:131] op_sel_hi:[1,0]
	v_pk_mul_f32 v[26:27], v[26:27], v[130:131] op_sel_hi:[1,0]
	v_pk_mul_f32 v[24:25], v[24:25], v[130:131] op_sel_hi:[1,0]
	v_pk_mul_f32 v[22:23], v[22:23], v[130:131] op_sel_hi:[1,0]
	v_pk_mul_f32 v[20:21], v[20:21], v[130:131] op_sel_hi:[1,0]
	global_store_dwordx4 v[36:37], v[32:35], off
	v_pk_mul_f32 v[24:25], v[28:29], v[24:25]
	v_pk_mul_f32 v[26:27], v[30:31], v[26:27]
	v_pk_mul_f32 v[32:33], v[30:31], s[44:45] op_sel_hi:[1,0]
	v_pk_mul_f32 v[34:35], v[28:29], s[44:45] op_sel_hi:[1,0]
	v_pk_mul_f32 v[28:29], v[22:23], s[44:45] op_sel_hi:[1,0]
	v_pk_mul_f32 v[30:31], v[20:21], s[44:45] op_sel_hi:[1,0]
	v_exp_f32_e32 v28, v28
	v_exp_f32_e32 v30, v30
	v_exp_f32_e32 v29, v29
	v_exp_f32_e32 v31, v31
	v_exp_f32_e32 v34, v34
	v_exp_f32_e32 v32, v32
	v_exp_f32_e32 v33, v33
	v_exp_f32_e32 v35, v35
	v_pk_add_f32 v[28:29], v[28:29], 1.0 op_sel_hi:[1,0]
	v_pk_add_f32 v[30:31], v[30:31], 1.0 op_sel_hi:[1,0]
	v_pk_add_f32 v[32:33], v[32:33], 1.0 op_sel_hi:[1,0]
	v_pk_add_f32 v[34:35], v[34:35], 1.0 op_sel_hi:[1,0]
	v_rcp_f32_e32 v30, v30
	v_rcp_f32_e32 v28, v28
	v_rcp_f32_e32 v29, v29
	v_rcp_f32_e32 v31, v31
	v_rcp_f32_e32 v34, v34
	v_rcp_f32_e32 v32, v32
	v_rcp_f32_e32 v33, v33
	v_rcp_f32_e32 v35, v35
	v_pk_mul_f32 v[18:19], v[18:19], v[130:131] op_sel_hi:[1,0]
	v_pk_mul_f32 v[16:17], v[16:17], v[130:131] op_sel_hi:[1,0]
	v_pk_mul_f32 v[18:19], v[22:23], v[18:19]
	v_pk_mul_f32 v[16:17], v[20:21], v[16:17]
	v_pk_mul_f32 v[20:21], v[18:19], v[28:29]
	v_pk_mul_f32 v[18:19], v[16:17], v[30:31]
	v_pk_mul_f32 v[26:27], v[26:27], v[32:33]
	v_pk_mul_f32 v[24:25], v[24:25], v[34:35]
	v_pk_mul_f32 v[14:15], v[14:15], v[128:129] op_sel_hi:[1,0]
	v_cvt_pk_bf16_f32 v16, v24, v25
	v_cvt_pk_bf16_f32 v17, v26, v27
	v_cvt_pk_bf16_f32 v18, v18, v19
	v_cvt_pk_bf16_f32 v19, v20, v21
	v_mad_i64_i32 v[20:21], s[4:5], v168, s35, v[112:113]
	v_lshl_add_u64 v[20:21], v[20:21], 0, v[114:115]
	v_pk_mul_f32 v[12:13], v[12:13], v[128:129] op_sel_hi:[1,0]
	v_pk_mul_f32 v[10:11], v[10:11], v[128:129] op_sel_hi:[1,0]
	v_pk_mul_f32 v[8:9], v[8:9], v[128:129] op_sel_hi:[1,0]
	v_pk_mul_f32 v[6:7], v[6:7], v[128:129] op_sel_hi:[1,0]
	v_pk_mul_f32 v[4:5], v[4:5], v[128:129] op_sel_hi:[1,0]
	global_store_dwordx4 v[20:21], v[16:19], off
	v_pk_mul_f32 v[8:9], v[12:13], v[8:9]
	v_pk_mul_f32 v[10:11], v[14:15], v[10:11]
	v_pk_mul_f32 v[16:17], v[14:15], s[44:45] op_sel_hi:[1,0]
	v_pk_mul_f32 v[18:19], v[12:13], s[44:45] op_sel_hi:[1,0]
	v_pk_mul_f32 v[12:13], v[6:7], s[44:45] op_sel_hi:[1,0]
	v_pk_mul_f32 v[14:15], v[4:5], s[44:45] op_sel_hi:[1,0]
	v_exp_f32_e32 v12, v12
	v_exp_f32_e32 v14, v14
	v_exp_f32_e32 v13, v13
	v_exp_f32_e32 v15, v15
	v_exp_f32_e32 v18, v18
	v_exp_f32_e32 v16, v16
	v_exp_f32_e32 v17, v17
	v_exp_f32_e32 v19, v19
	v_pk_add_f32 v[12:13], v[12:13], 1.0 op_sel_hi:[1,0]
	v_pk_add_f32 v[14:15], v[14:15], 1.0 op_sel_hi:[1,0]
	v_pk_add_f32 v[16:17], v[16:17], 1.0 op_sel_hi:[1,0]
	v_pk_add_f32 v[18:19], v[18:19], 1.0 op_sel_hi:[1,0]
	v_rcp_f32_e32 v14, v14
	v_rcp_f32_e32 v12, v12
	v_rcp_f32_e32 v13, v13
	v_rcp_f32_e32 v15, v15
	v_rcp_f32_e32 v18, v18
	v_rcp_f32_e32 v16, v16
	v_rcp_f32_e32 v17, v17
	v_rcp_f32_e32 v19, v19
	v_pk_mul_f32 v[2:3], v[2:3], v[128:129] op_sel_hi:[1,0]
	v_pk_mul_f32 v[0:1], v[0:1], v[128:129] op_sel_hi:[1,0]
	v_pk_mul_f32 v[2:3], v[6:7], v[2:3]
	v_pk_mul_f32 v[0:1], v[4:5], v[0:1]
	v_pk_mul_f32 v[4:5], v[2:3], v[12:13]
	v_pk_mul_f32 v[2:3], v[0:1], v[14:15]
	v_pk_mul_f32 v[10:11], v[10:11], v[16:17]
	v_pk_mul_f32 v[8:9], v[8:9], v[18:19]
	s_andn2_b64 vcc, exec, s[2:3]
	v_cvt_pk_bf16_f32 v0, v8, v9
	v_cvt_pk_bf16_f32 v1, v10, v11
	v_cvt_pk_bf16_f32 v2, v2, v3
	v_cvt_pk_bf16_f32 v3, v4, v5
	v_mad_i64_i32 v[4:5], s[4:5], v166, s35, v[112:113]
	v_lshl_add_u64 v[4:5], v[4:5], 0, v[114:115]
	s_mov_b32 s4, s16
	s_mov_b32 s5, s12
	s_mov_b64 s[6:7], s[18:19]
	global_store_dwordx4 v[4:5], v[0:3], off
	s_cbranch_vccnz .LBB0_1429
	s_waitcnt vmcnt(0)
	s_cmpk_gt_u32 s24, 0xff
	s_cbranch_scc1 .LBB0_1440
	s_barrier
